# GEMM k-loops: last iteration peeled without the redundant clamped prefetch loads (exact vmcnt), loop runs nk-2 steps
# speedup vs baseline: 1.0166x; 1.0114x over previous
.Lg16_proj_k:
	s_add_i32 s3, s1, 2
	s_min_u32 s4, s3, 30
	s_lshl_b32 s96, s4, 13
	v_lshl_add_u64 v[166:167], v[188:189], 0, s[96:97]
	global_load_dwordx4 v[160:163], v[166:167], off offset:-2048
	global_load_dwordx4 v[164:167], v[166:167], off offset:2048
	ds_read_b128 v[236:239], v196 offset:0
	ds_read_b128 v[240:243], v196 offset:1024
	ds_read_b128 v[244:247], v196 offset:2048
	ds_read_b128 v[248:251], v196 offset:3072
	s_lshl_b32 s96, s4, 11
	v_lshl_add_u64 v[198:199], v[184:185], 0, s[96:97]
	v_lshl_add_u64 v[200:201], v[186:187], 0, s[96:97]
	s_waitcnt vmcnt(8) lgkmcnt(3)
	v_mfma_f32_16x16x32_bf16 v[16:19], v[128:131], v[236:239], v[16:19]
	v_mfma_f32_16x16x32_bf16 v[24:27], v[132:135], v[236:239], v[24:27]
	v_mfma_f32_16x16x32_bf16 v[0:3], v[136:139], v[236:239], v[0:3]
	v_mfma_f32_16x16x32_bf16 v[8:11], v[140:143], v[236:239], v[8:11]
	ds_read_b128 v[236:239], v196 offset:4096
	s_waitcnt lgkmcnt(3)
	v_mfma_f32_16x16x32_bf16 v[20:23], v[128:131], v[240:243], v[20:23]
	v_mfma_f32_16x16x32_bf16 v[28:31], v[132:135], v[240:243], v[28:31]
	v_mfma_f32_16x16x32_bf16 v[4:7], v[136:139], v[240:243], v[4:7]
	v_mfma_f32_16x16x32_bf16 v[12:15], v[140:143], v[240:243], v[12:15]
	ds_read_b128 v[240:243], v196 offset:5120
	s_waitcnt lgkmcnt(3)
	v_mfma_f32_16x16x32_bf16 v[112:115], v[128:131], v[244:247], v[112:115]
	v_mfma_f32_16x16x32_bf16 v[120:123], v[132:135], v[244:247], v[120:123]
	v_mfma_f32_16x16x32_bf16 v[96:99], v[136:139], v[244:247], v[96:99]
	v_mfma_f32_16x16x32_bf16 v[104:107], v[140:143], v[244:247], v[104:107]
	ds_read_b128 v[244:247], v196 offset:6144
	s_waitcnt lgkmcnt(3)
	v_mfma_f32_16x16x32_bf16 v[116:119], v[128:131], v[248:251], v[116:119]
	v_mfma_f32_16x16x32_bf16 v[124:127], v[132:135], v[248:251], v[124:127]
	v_mfma_f32_16x16x32_bf16 v[100:103], v[136:139], v[248:251], v[100:103]
	v_mfma_f32_16x16x32_bf16 v[108:111], v[140:143], v[248:251], v[108:111]
	ds_read_b128 v[248:251], v196 offset:7168
	s_waitcnt vmcnt(6)
	ds_write_b128 v235, v[168:171] offset:8192
	ds_write_b128 v235, v[172:175] offset:12288
	s_waitcnt lgkmcnt(5)
	v_mfma_f32_16x16x32_bf16 v[80:83], v[128:131], v[236:239], v[80:83]
	v_mfma_f32_16x16x32_bf16 v[88:91], v[132:135], v[236:239], v[88:91]
	v_mfma_f32_16x16x32_bf16 v[48:51], v[136:139], v[236:239], v[48:51]
	v_mfma_f32_16x16x32_bf16 v[56:59], v[140:143], v[236:239], v[56:59]
	s_waitcnt lgkmcnt(4)
	v_mfma_f32_16x16x32_bf16 v[84:87], v[128:131], v[240:243], v[84:87]
	v_mfma_f32_16x16x32_bf16 v[92:95], v[132:135], v[240:243], v[92:95]
	v_mfma_f32_16x16x32_bf16 v[52:55], v[136:139], v[240:243], v[52:55]
	v_mfma_f32_16x16x32_bf16 v[60:63], v[140:143], v[240:243], v[60:63]
	s_waitcnt lgkmcnt(3)
	v_mfma_f32_16x16x32_bf16 v[64:67], v[128:131], v[244:247], v[64:67]
	v_mfma_f32_16x16x32_bf16 v[72:75], v[132:135], v[244:247], v[72:75]
	v_mfma_f32_16x16x32_bf16 v[32:35], v[136:139], v[244:247], v[32:35]
	v_mfma_f32_16x16x32_bf16 v[40:43], v[140:143], v[244:247], v[40:43]
	s_waitcnt lgkmcnt(2)
	v_mfma_f32_16x16x32_bf16 v[68:71], v[128:131], v[248:251], v[68:71]
	v_mfma_f32_16x16x32_bf16 v[76:79], v[132:135], v[248:251], v[76:79]
	v_mfma_f32_16x16x32_bf16 v[36:39], v[136:139], v[248:251], v[36:39]
	v_mfma_f32_16x16x32_bf16 v[44:47], v[140:143], v[248:251], v[44:47]
	global_load_dwordx4 v[128:131], v[198:199], off
	global_load_dwordx4 v[132:135], v[198:199], off offset:256
	global_load_dwordx4 v[136:139], v[200:201], off
	global_load_dwordx4 v[140:143], v[200:201], off offset:256
	s_waitcnt lgkmcnt(0)
	s_barrier
	s_add_i32 s3, s1, 3
	s_min_u32 s4, s3, 31
	s_lshl_b32 s96, s4, 13
	v_lshl_add_u64 v[174:175], v[188:189], 0, s[96:97]
	global_load_dwordx4 v[168:171], v[174:175], off offset:-2048
	global_load_dwordx4 v[172:175], v[174:175], off offset:2048
	ds_read_b128 v[236:239], v196 offset:8192
	ds_read_b128 v[240:243], v196 offset:9216
	ds_read_b128 v[244:247], v196 offset:10240
	ds_read_b128 v[248:251], v196 offset:11264
	s_lshl_b32 s96, s4, 11
	v_lshl_add_u64 v[198:199], v[184:185], 0, s[96:97]
	v_lshl_add_u64 v[200:201], v[186:187], 0, s[96:97]
	s_waitcnt vmcnt(8) lgkmcnt(3)
	v_mfma_f32_16x16x32_bf16 v[16:19], v[144:147], v[236:239], v[16:19]
	v_mfma_f32_16x16x32_bf16 v[24:27], v[148:151], v[236:239], v[24:27]
	v_mfma_f32_16x16x32_bf16 v[0:3], v[152:155], v[236:239], v[0:3]
	v_mfma_f32_16x16x32_bf16 v[8:11], v[156:159], v[236:239], v[8:11]
	ds_read_b128 v[236:239], v196 offset:12288
	s_waitcnt lgkmcnt(3)
	v_mfma_f32_16x16x32_bf16 v[20:23], v[144:147], v[240:243], v[20:23]
	v_mfma_f32_16x16x32_bf16 v[28:31], v[148:151], v[240:243], v[28:31]
	v_mfma_f32_16x16x32_bf16 v[4:7], v[152:155], v[240:243], v[4:7]
	v_mfma_f32_16x16x32_bf16 v[12:15], v[156:159], v[240:243], v[12:15]
	ds_read_b128 v[240:243], v196 offset:13312
	s_waitcnt lgkmcnt(3)
	v_mfma_f32_16x16x32_bf16 v[112:115], v[144:147], v[244:247], v[112:115]
	v_mfma_f32_16x16x32_bf16 v[120:123], v[148:151], v[244:247], v[120:123]
	v_mfma_f32_16x16x32_bf16 v[96:99], v[152:155], v[244:247], v[96:99]
	v_mfma_f32_16x16x32_bf16 v[104:107], v[156:159], v[244:247], v[104:107]
	ds_read_b128 v[244:247], v196 offset:14336
	s_waitcnt lgkmcnt(3)
	v_mfma_f32_16x16x32_bf16 v[116:119], v[144:147], v[248:251], v[116:119]
	v_mfma_f32_16x16x32_bf16 v[124:127], v[148:151], v[248:251], v[124:127]
	v_mfma_f32_16x16x32_bf16 v[100:103], v[152:155], v[248:251], v[100:103]
	v_mfma_f32_16x16x32_bf16 v[108:111], v[156:159], v[248:251], v[108:111]
	ds_read_b128 v[248:251], v196 offset:15360
	s_waitcnt vmcnt(6)
	ds_write_b128 v235, v[160:163] offset:0
	ds_write_b128 v235, v[164:167] offset:4096
	s_waitcnt lgkmcnt(5)
	v_mfma_f32_16x16x32_bf16 v[80:83], v[144:147], v[236:239], v[80:83]
	v_mfma_f32_16x16x32_bf16 v[88:91], v[148:151], v[236:239], v[88:91]
	v_mfma_f32_16x16x32_bf16 v[48:51], v[152:155], v[236:239], v[48:51]
	v_mfma_f32_16x16x32_bf16 v[56:59], v[156:159], v[236:239], v[56:59]
	s_waitcnt lgkmcnt(4)
	v_mfma_f32_16x16x32_bf16 v[84:87], v[144:147], v[240:243], v[84:87]
	v_mfma_f32_16x16x32_bf16 v[92:95], v[148:151], v[240:243], v[92:95]
	v_mfma_f32_16x16x32_bf16 v[52:55], v[152:155], v[240:243], v[52:55]
	v_mfma_f32_16x16x32_bf16 v[60:63], v[156:159], v[240:243], v[60:63]
	s_waitcnt lgkmcnt(3)
	v_mfma_f32_16x16x32_bf16 v[64:67], v[144:147], v[244:247], v[64:67]
	v_mfma_f32_16x16x32_bf16 v[72:75], v[148:151], v[244:247], v[72:75]
	v_mfma_f32_16x16x32_bf16 v[32:35], v[152:155], v[244:247], v[32:35]
	v_mfma_f32_16x16x32_bf16 v[40:43], v[156:159], v[244:247], v[40:43]
	s_waitcnt lgkmcnt(2)
	v_mfma_f32_16x16x32_bf16 v[68:71], v[144:147], v[248:251], v[68:71]
	v_mfma_f32_16x16x32_bf16 v[76:79], v[148:151], v[248:251], v[76:79]
	v_mfma_f32_16x16x32_bf16 v[36:39], v[152:155], v[248:251], v[36:39]
	v_mfma_f32_16x16x32_bf16 v[44:47], v[156:159], v[248:251], v[44:47]
	global_load_dwordx4 v[144:147], v[198:199], off
	global_load_dwordx4 v[148:151], v[198:199], off offset:256
	global_load_dwordx4 v[152:155], v[200:201], off
	global_load_dwordx4 v[156:159], v[200:201], off offset:256
	s_add_i32 s1, s1, 2
	s_cmp_lt_u32 s1, 30
	s_waitcnt lgkmcnt(0)
	s_barrier
	s_cbranch_scc1 .Lg16_proj_k
	ds_read_b128 v[236:239], v196 offset:0
	ds_read_b128 v[240:243], v196 offset:1024
	ds_read_b128 v[244:247], v196 offset:2048
	ds_read_b128 v[248:251], v196 offset:3072
	s_waitcnt vmcnt(6) lgkmcnt(3)
	v_mfma_f32_16x16x32_bf16 v[16:19], v[128:131], v[236:239], v[16:19]
	v_mfma_f32_16x16x32_bf16 v[24:27], v[132:135], v[236:239], v[24:27]
	v_mfma_f32_16x16x32_bf16 v[0:3], v[136:139], v[236:239], v[0:3]
	v_mfma_f32_16x16x32_bf16 v[8:11], v[140:143], v[236:239], v[8:11]
	ds_read_b128 v[236:239], v196 offset:4096
	s_waitcnt lgkmcnt(3)
	v_mfma_f32_16x16x32_bf16 v[20:23], v[128:131], v[240:243], v[20:23]
	v_mfma_f32_16x16x32_bf16 v[28:31], v[132:135], v[240:243], v[28:31]
	v_mfma_f32_16x16x32_bf16 v[4:7], v[136:139], v[240:243], v[4:7]
	v_mfma_f32_16x16x32_bf16 v[12:15], v[140:143], v[240:243], v[12:15]
	ds_read_b128 v[240:243], v196 offset:5120
	s_waitcnt lgkmcnt(3)
	v_mfma_f32_16x16x32_bf16 v[112:115], v[128:131], v[244:247], v[112:115]
	v_mfma_f32_16x16x32_bf16 v[120:123], v[132:135], v[244:247], v[120:123]
	v_mfma_f32_16x16x32_bf16 v[96:99], v[136:139], v[244:247], v[96:99]
	v_mfma_f32_16x16x32_bf16 v[104:107], v[140:143], v[244:247], v[104:107]
	ds_read_b128 v[244:247], v196 offset:6144
	s_waitcnt lgkmcnt(3)
	v_mfma_f32_16x16x32_bf16 v[116:119], v[128:131], v[248:251], v[116:119]
	v_mfma_f32_16x16x32_bf16 v[124:127], v[132:135], v[248:251], v[124:127]
	v_mfma_f32_16x16x32_bf16 v[100:103], v[136:139], v[248:251], v[100:103]
	v_mfma_f32_16x16x32_bf16 v[108:111], v[140:143], v[248:251], v[108:111]
	ds_read_b128 v[248:251], v196 offset:7168
	s_waitcnt vmcnt(4)
	ds_write_b128 v235, v[168:171] offset:8192
	ds_write_b128 v235, v[172:175] offset:12288
	s_waitcnt lgkmcnt(5)
	v_mfma_f32_16x16x32_bf16 v[80:83], v[128:131], v[236:239], v[80:83]
	v_mfma_f32_16x16x32_bf16 v[88:91], v[132:135], v[236:239], v[88:91]
	v_mfma_f32_16x16x32_bf16 v[48:51], v[136:139], v[236:239], v[48:51]
	v_mfma_f32_16x16x32_bf16 v[56:59], v[140:143], v[236:239], v[56:59]
	s_waitcnt lgkmcnt(4)
	v_mfma_f32_16x16x32_bf16 v[84:87], v[128:131], v[240:243], v[84:87]
	v_mfma_f32_16x16x32_bf16 v[92:95], v[132:135], v[240:243], v[92:95]
	v_mfma_f32_16x16x32_bf16 v[52:55], v[136:139], v[240:243], v[52:55]
	v_mfma_f32_16x16x32_bf16 v[60:63], v[140:143], v[240:243], v[60:63]
	s_waitcnt lgkmcnt(3)
	v_mfma_f32_16x16x32_bf16 v[64:67], v[128:131], v[244:247], v[64:67]
	v_mfma_f32_16x16x32_bf16 v[72:75], v[132:135], v[244:247], v[72:75]
	v_mfma_f32_16x16x32_bf16 v[32:35], v[136:139], v[244:247], v[32:35]
	v_mfma_f32_16x16x32_bf16 v[40:43], v[140:143], v[244:247], v[40:43]
	s_waitcnt lgkmcnt(2)
	v_mfma_f32_16x16x32_bf16 v[68:71], v[128:131], v[248:251], v[68:71]
	v_mfma_f32_16x16x32_bf16 v[76:79], v[132:135], v[248:251], v[76:79]
	v_mfma_f32_16x16x32_bf16 v[36:39], v[136:139], v[248:251], v[36:39]
	v_mfma_f32_16x16x32_bf16 v[44:47], v[140:143], v[248:251], v[44:47]
	s_waitcnt lgkmcnt(0)
	s_barrier
	ds_read_b128 v[236:239], v196 offset:8192
	ds_read_b128 v[240:243], v196 offset:9216
	ds_read_b128 v[244:247], v196 offset:10240
	ds_read_b128 v[248:251], v196 offset:11264
	s_waitcnt vmcnt(0) lgkmcnt(3)
	v_mfma_f32_16x16x32_bf16 v[16:19], v[144:147], v[236:239], v[16:19]
	v_mfma_f32_16x16x32_bf16 v[24:27], v[148:151], v[236:239], v[24:27]
	v_mfma_f32_16x16x32_bf16 v[0:3], v[152:155], v[236:239], v[0:3]
	v_mfma_f32_16x16x32_bf16 v[8:11], v[156:159], v[236:239], v[8:11]
	ds_read_b128 v[236:239], v196 offset:12288
	s_waitcnt lgkmcnt(3)
	v_mfma_f32_16x16x32_bf16 v[20:23], v[144:147], v[240:243], v[20:23]
	v_mfma_f32_16x16x32_bf16 v[28:31], v[148:151], v[240:243], v[28:31]
	v_mfma_f32_16x16x32_bf16 v[4:7], v[152:155], v[240:243], v[4:7]
	v_mfma_f32_16x16x32_bf16 v[12:15], v[156:159], v[240:243], v[12:15]
	ds_read_b128 v[240:243], v196 offset:13312
	s_waitcnt lgkmcnt(3)
	v_mfma_f32_16x16x32_bf16 v[112:115], v[144:147], v[244:247], v[112:115]
	v_mfma_f32_16x16x32_bf16 v[120:123], v[148:151], v[244:247], v[120:123]
	v_mfma_f32_16x16x32_bf16 v[96:99], v[152:155], v[244:247], v[96:99]
	v_mfma_f32_16x16x32_bf16 v[104:107], v[156:159], v[244:247], v[104:107]
	ds_read_b128 v[244:247], v196 offset:14336
	s_waitcnt lgkmcnt(3)
	v_mfma_f32_16x16x32_bf16 v[116:119], v[144:147], v[248:251], v[116:119]
	v_mfma_f32_16x16x32_bf16 v[124:127], v[148:151], v[248:251], v[124:127]
	v_mfma_f32_16x16x32_bf16 v[100:103], v[152:155], v[248:251], v[100:103]
	v_mfma_f32_16x16x32_bf16 v[108:111], v[156:159], v[248:251], v[108:111]
	ds_read_b128 v[248:251], v196 offset:15360
	s_waitcnt lgkmcnt(3)
	v_mfma_f32_16x16x32_bf16 v[80:83], v[144:147], v[236:239], v[80:83]
	v_mfma_f32_16x16x32_bf16 v[88:91], v[148:151], v[236:239], v[88:91]
	v_mfma_f32_16x16x32_bf16 v[48:51], v[152:155], v[236:239], v[48:51]
	v_mfma_f32_16x16x32_bf16 v[56:59], v[156:159], v[236:239], v[56:59]
	s_waitcnt lgkmcnt(2)
	v_mfma_f32_16x16x32_bf16 v[84:87], v[144:147], v[240:243], v[84:87]
	v_mfma_f32_16x16x32_bf16 v[92:95], v[148:151], v[240:243], v[92:95]
	v_mfma_f32_16x16x32_bf16 v[52:55], v[152:155], v[240:243], v[52:55]
	v_mfma_f32_16x16x32_bf16 v[60:63], v[156:159], v[240:243], v[60:63]
	s_waitcnt lgkmcnt(1)
	v_mfma_f32_16x16x32_bf16 v[64:67], v[144:147], v[244:247], v[64:67]
	v_mfma_f32_16x16x32_bf16 v[72:75], v[148:151], v[244:247], v[72:75]
	v_mfma_f32_16x16x32_bf16 v[32:35], v[152:155], v[244:247], v[32:35]
	v_mfma_f32_16x16x32_bf16 v[40:43], v[156:159], v[244:247], v[40:43]
	s_waitcnt lgkmcnt(0)
	v_mfma_f32_16x16x32_bf16 v[68:71], v[144:147], v[248:251], v[68:71]
	v_mfma_f32_16x16x32_bf16 v[76:79], v[148:151], v[248:251], v[76:79]
	v_mfma_f32_16x16x32_bf16 v[36:39], v[152:155], v[248:251], v[36:39]
	v_mfma_f32_16x16x32_bf16 v[44:47], v[156:159], v[248:251], v[44:47]
	s_waitcnt lgkmcnt(0)
	s_barrier
	s_nop 7
	v_permlane16_swap_b32_e32 v16, v20
	v_permlane16_swap_b32_e32 v17, v21
	v_permlane16_swap_b32_e32 v18, v22
	v_permlane16_swap_b32_e32 v19, v23
	v_permlane16_swap_b32_e32 v24, v28
	v_permlane16_swap_b32_e32 v25, v29
	v_permlane16_swap_b32_e32 v26, v30
	v_permlane16_swap_b32_e32 v27, v31
	v_permlane16_swap_b32_e32 v112, v116
	v_permlane16_swap_b32_e32 v113, v117
	v_permlane16_swap_b32_e32 v114, v118
	v_permlane16_swap_b32_e32 v115, v119
	v_permlane16_swap_b32_e32 v120, v124
	v_permlane16_swap_b32_e32 v121, v125
	v_permlane16_swap_b32_e32 v122, v126
	v_permlane16_swap_b32_e32 v123, v127
	v_permlane16_swap_b32_e32 v80, v84
	v_permlane16_swap_b32_e32 v81, v85
	v_permlane16_swap_b32_e32 v82, v86
	v_permlane16_swap_b32_e32 v83, v87
	v_permlane16_swap_b32_e32 v88, v92
	v_permlane16_swap_b32_e32 v89, v93
	v_permlane16_swap_b32_e32 v90, v94
	v_permlane16_swap_b32_e32 v91, v95
	v_permlane16_swap_b32_e32 v64, v68
	v_permlane16_swap_b32_e32 v65, v69
	v_permlane16_swap_b32_e32 v66, v70
	v_permlane16_swap_b32_e32 v67, v71
	v_permlane16_swap_b32_e32 v72, v76
	v_permlane16_swap_b32_e32 v73, v77
	v_permlane16_swap_b32_e32 v74, v78
	v_permlane16_swap_b32_e32 v75, v79
	v_permlane16_swap_b32_e32 v0, v4
	v_permlane16_swap_b32_e32 v1, v5
	v_permlane16_swap_b32_e32 v2, v6
	v_permlane16_swap_b32_e32 v3, v7
	v_permlane16_swap_b32_e32 v8, v12
	v_permlane16_swap_b32_e32 v9, v13
	v_permlane16_swap_b32_e32 v10, v14
	v_permlane16_swap_b32_e32 v11, v15
	v_permlane16_swap_b32_e32 v96, v100
	v_permlane16_swap_b32_e32 v97, v101
	v_permlane16_swap_b32_e32 v98, v102
	v_permlane16_swap_b32_e32 v99, v103
	v_permlane16_swap_b32_e32 v104, v108
	v_permlane16_swap_b32_e32 v105, v109
	v_permlane16_swap_b32_e32 v106, v110
	v_permlane16_swap_b32_e32 v107, v111
	v_permlane16_swap_b32_e32 v48, v52
	v_permlane16_swap_b32_e32 v49, v53
	v_permlane16_swap_b32_e32 v50, v54
	v_permlane16_swap_b32_e32 v51, v55
	v_permlane16_swap_b32_e32 v56, v60
	v_permlane16_swap_b32_e32 v57, v61
	v_permlane16_swap_b32_e32 v58, v62
	v_permlane16_swap_b32_e32 v59, v63
	v_permlane16_swap_b32_e32 v32, v36
	v_permlane16_swap_b32_e32 v33, v37
	v_permlane16_swap_b32_e32 v34, v38
	v_permlane16_swap_b32_e32 v35, v39
	v_permlane16_swap_b32_e32 v40, v44
	v_permlane16_swap_b32_e32 v41, v45
	v_permlane16_swap_b32_e32 v42, v46
	v_permlane16_swap_b32_e32 v43, v47
	v_permlane32_swap_b32_e32 v16, v20
	v_permlane32_swap_b32_e32 v17, v21
	v_permlane32_swap_b32_e32 v18, v22
	v_permlane32_swap_b32_e32 v19, v23
	v_permlane32_swap_b32_e32 v24, v28
	v_permlane32_swap_b32_e32 v25, v29
	v_permlane32_swap_b32_e32 v26, v30
	v_permlane32_swap_b32_e32 v27, v31
	v_permlane32_swap_b32_e32 v112, v116
	v_permlane32_swap_b32_e32 v113, v117
	v_permlane32_swap_b32_e32 v114, v118
	v_permlane32_swap_b32_e32 v115, v119
	v_permlane32_swap_b32_e32 v120, v124
	v_permlane32_swap_b32_e32 v121, v125
	v_permlane32_swap_b32_e32 v122, v126
	v_permlane32_swap_b32_e32 v123, v127
	v_permlane32_swap_b32_e32 v80, v84
	v_permlane32_swap_b32_e32 v81, v85
	v_permlane32_swap_b32_e32 v82, v86
	v_permlane32_swap_b32_e32 v83, v87
	v_permlane32_swap_b32_e32 v88, v92
	v_permlane32_swap_b32_e32 v89, v93
	v_permlane32_swap_b32_e32 v90, v94
	v_permlane32_swap_b32_e32 v91, v95
	v_permlane32_swap_b32_e32 v64, v68
	v_permlane32_swap_b32_e32 v65, v69
	v_permlane32_swap_b32_e32 v66, v70
	v_permlane32_swap_b32_e32 v67, v71
	v_permlane32_swap_b32_e32 v72, v76
	v_permlane32_swap_b32_e32 v73, v77
	v_permlane32_swap_b32_e32 v74, v78
	v_permlane32_swap_b32_e32 v75, v79
	v_permlane32_swap_b32_e32 v0, v4
	v_permlane32_swap_b32_e32 v1, v5
	v_permlane32_swap_b32_e32 v2, v6
	v_permlane32_swap_b32_e32 v3, v7
	v_permlane32_swap_b32_e32 v8, v12
	v_permlane32_swap_b32_e32 v9, v13
	v_permlane32_swap_b32_e32 v10, v14
	v_permlane32_swap_b32_e32 v11, v15
	v_permlane32_swap_b32_e32 v96, v100
	v_permlane32_swap_b32_e32 v97, v101
	v_permlane32_swap_b32_e32 v98, v102
	v_permlane32_swap_b32_e32 v99, v103
	v_permlane32_swap_b32_e32 v104, v108
	v_permlane32_swap_b32_e32 v105, v109
	v_permlane32_swap_b32_e32 v106, v110
	v_permlane32_swap_b32_e32 v107, v111
	v_permlane32_swap_b32_e32 v48, v52
	v_permlane32_swap_b32_e32 v49, v53
	v_permlane32_swap_b32_e32 v50, v54
	v_permlane32_swap_b32_e32 v51, v55
	v_permlane32_swap_b32_e32 v56, v60
	v_permlane32_swap_b32_e32 v57, v61
	v_permlane32_swap_b32_e32 v58, v62
	v_permlane32_swap_b32_e32 v59, v63
	v_permlane32_swap_b32_e32 v32, v36
	v_permlane32_swap_b32_e32 v33, v37
	v_permlane32_swap_b32_e32 v34, v38
	v_permlane32_swap_b32_e32 v35, v39
	v_permlane32_swap_b32_e32 v40, v44
	v_permlane32_swap_b32_e32 v41, v45
	v_permlane32_swap_b32_e32 v42, v46
	v_permlane32_swap_b32_e32 v43, v47
	s_waitcnt vmcnt(0)
	s_lshl_b32 s12, s2, 8
	s_cmp_eq_u32 s0, 23
	s_mov_b64 s[2:3], -1
	s_cbranch_scc1 .LBB0_347
	s_movk_i32 s1, 0x2400
	s_waitcnt vmcnt(6)
	v_and_b32_e32 v130, 0xffffffc0, v181
	s_cmp_gt_i32 s0, 10
	v_mul_lo_u32 v129, v233, s1
	v_and_b32_e32 v128, 56, v234
	v_add_u32_e32 v131, s12, v130
	s_cselect_b64 s[2:3], -1, 0
	s_cmp_gt_u32 s0, 19
	v_mul_u32_u24_e32 v130, 0x120, v183
	s_waitcnt vmcnt(0)
	v_lshl_or_b32 v132, v128, 1, v129
	v_lshl_or_b32 v128, s0, 7, v128
	s_cselect_b64 s[0:1], -1, 0
	v_lshl_add_u32 v129, v130, 1, v129
	v_lshl_or_b32 v130, v231, 1, v129
	v_cvt_pk_bf16_f32 v112, v112, s0
	ds_write_b16 v130, v112 offset:64
	v_cvt_pk_bf16_f32 v112, v17, s0
	v_cvt_pk_bf16_f32 v96, v96, s0
	ds_write_b16 v130, v112 offset:144
	v_cvt_pk_bf16_f32 v112, v113, s0
	ds_write_b16 v130, v96 offset:4672
	v_cvt_pk_bf16_f32 v96, v1, s0
	ds_write_b16 v130, v112 offset:208
	v_cvt_pk_bf16_f32 v112, v18, s0
	ds_write_b16 v130, v96 offset:4752
	v_cvt_pk_bf16_f32 v96, v97, s0
	ds_write_b16 v130, v112 offset:288
	v_cvt_pk_bf16_f32 v112, v114, s0
	ds_write_b16 v130, v96 offset:4816
	v_cvt_pk_bf16_f32 v96, v2, s0
	ds_write_b16 v130, v112 offset:352
	v_cvt_pk_bf16_f32 v112, v19, s0
	ds_write_b16 v130, v96 offset:4896
	v_cvt_pk_bf16_f32 v96, v98, s0
	ds_write_b16 v130, v112 offset:432
	v_cvt_pk_bf16_f32 v112, v115, s0
	ds_write_b16 v130, v96 offset:4960
	v_cvt_pk_bf16_f32 v96, v3, s0
	ds_write_b16 v130, v112 offset:496
	v_cvt_pk_bf16_f32 v112, v20, s0
	ds_write_b16 v130, v96 offset:5040
	v_cvt_pk_bf16_f32 v96, v99, s0
	ds_write_b16 v130, v112 offset:1152
	v_cvt_pk_bf16_f32 v112, v116, s0
	ds_write_b16 v130, v96 offset:5104
	v_cvt_pk_bf16_f32 v96, v4, s0
	ds_write_b16 v130, v112 offset:1216
	v_cvt_pk_bf16_f32 v112, v21, s0
	ds_write_b16 v130, v96 offset:5760
	v_cvt_pk_bf16_f32 v96, v100, s0
	ds_write_b16 v130, v112 offset:1296
	v_cvt_pk_bf16_f32 v112, v117, s0
	ds_write_b16 v130, v96 offset:5824
	v_cvt_pk_bf16_f32 v96, v5, s0
	ds_write_b16 v130, v112 offset:1360
	v_cvt_pk_bf16_f32 v112, v22, s0
	ds_write_b16 v130, v96 offset:5904
	v_cvt_pk_bf16_f32 v96, v101, s0
	ds_write_b16 v130, v112 offset:1440
	v_cvt_pk_bf16_f32 v112, v118, s0
	ds_write_b16 v130, v96 offset:5968
	v_cvt_pk_bf16_f32 v96, v6, s0
	ds_write_b16 v130, v112 offset:1504
	v_cvt_pk_bf16_f32 v112, v23, s0
	ds_write_b16 v130, v96 offset:6048
	v_cvt_pk_bf16_f32 v96, v102, s0
	ds_write_b16 v130, v112 offset:1584
	v_cvt_pk_bf16_f32 v112, v119, s0
	ds_write_b16 v130, v96 offset:6112
	v_cvt_pk_bf16_f32 v96, v7, s0
	ds_write_b16 v130, v112 offset:1648
	v_cvt_pk_bf16_f32 v112, v24, s0
	ds_write_b16 v130, v96 offset:6192
	v_cvt_pk_bf16_f32 v96, v103, s0
	ds_write_b16 v130, v112 offset:2304
	v_cvt_pk_bf16_f32 v112, v120, s0
	ds_write_b16 v130, v96 offset:6256
	v_cvt_pk_bf16_f32 v96, v8, s0
	ds_write_b16 v130, v112 offset:2368
	v_cvt_pk_bf16_f32 v112, v25, s0
	ds_write_b16 v130, v96 offset:6912
	v_cvt_pk_bf16_f32 v96, v104, s0
	ds_write_b16 v130, v112 offset:2448
	v_cvt_pk_bf16_f32 v112, v121, s0
	ds_write_b16 v130, v96 offset:6976
	v_cvt_pk_bf16_f32 v96, v9, s0
	ds_write_b16 v130, v112 offset:2512
	v_cvt_pk_bf16_f32 v112, v26, s0
	ds_write_b16 v130, v96 offset:7056
	v_cvt_pk_bf16_f32 v96, v105, s0
	ds_write_b16 v130, v112 offset:2592
	v_cvt_pk_bf16_f32 v112, v122, s0
	ds_write_b16 v130, v96 offset:7120
	v_cvt_pk_bf16_f32 v96, v10, s0
	ds_write_b16 v130, v112 offset:2656
	v_cvt_pk_bf16_f32 v112, v27, s0
	ds_write_b16 v130, v96 offset:7200
	v_cvt_pk_bf16_f32 v96, v106, s0
	ds_write_b16 v130, v112 offset:2736
	v_cvt_pk_bf16_f32 v112, v123, s0
	ds_write_b16 v130, v96 offset:7264
	v_cvt_pk_bf16_f32 v96, v11, s0
	ds_write_b16 v130, v112 offset:2800
	v_cvt_pk_bf16_f32 v112, v28, s0
	ds_write_b16 v130, v96 offset:7344
	v_cvt_pk_bf16_f32 v96, v107, s0
	ds_write_b16 v130, v112 offset:3456
	v_cvt_pk_bf16_f32 v112, v124, s0
	ds_write_b16 v130, v96 offset:7408
	v_cvt_pk_bf16_f32 v96, v12, s0
	ds_write_b16 v130, v112 offset:3520
	v_cvt_pk_bf16_f32 v112, v29, s0
	ds_write_b16 v130, v96 offset:8064
	v_cvt_pk_bf16_f32 v96, v108, s0
	ds_write_b16 v130, v112 offset:3600
	v_cvt_pk_bf16_f32 v112, v125, s0
	ds_write_b16 v130, v96 offset:8128
	v_cvt_pk_bf16_f32 v96, v13, s0
	ds_write_b16 v130, v112 offset:3664
	v_cvt_pk_bf16_f32 v112, v30, s0
	ds_write_b16 v130, v96 offset:8208
	v_cvt_pk_bf16_f32 v96, v109, s0
	ds_write_b16 v130, v112 offset:3744
	v_cvt_pk_bf16_f32 v112, v126, s0
	ds_write_b16 v130, v96 offset:8272
	v_cvt_pk_bf16_f32 v96, v14, s0
	ds_write_b16 v130, v112 offset:3808
	v_cvt_pk_bf16_f32 v112, v31, s0
	ds_write_b16 v130, v96 offset:8352
	v_cvt_pk_bf16_f32 v96, v110, s0
	ds_write_b16 v130, v112 offset:3888
	v_cvt_pk_bf16_f32 v112, v127, s0
	ds_write_b16 v130, v96 offset:8416
	v_cvt_pk_bf16_f32 v96, v15, s0
	v_cvt_pk_bf16_f32 v133, v16, s0
	ds_write_b16 v130, v112 offset:3952
	v_cvt_pk_bf16_f32 v112, v0, s0
	ds_write_b16 v130, v96 offset:8496
	v_cvt_pk_bf16_f32 v96, v111, s0
	ds_write_b16 v130, v133
	ds_write_b16 v130, v112 offset:4608
	ds_write_b16 v130, v96 offset:8560
	v_lshrrev_b32_e32 v109, 3, v232
	s_waitcnt lgkmcnt(0)
	v_mad_u32_u24 v96, v109, s42, v132
	ds_read_b128 v[96:99], v96
	v_mov_b32_e32 v176, v128
	v_or_b32_e32 v110, v131, v109
	s_mov_b64 s[4:5], -1
	s_and_b64 vcc, exec, s[2:3]
	s_cbranch_vccz .LBB0_224
	s_and_b64 vcc, exec, s[0:1]
	s_cbranch_vccz .LBB0_221
	v_readlane_b32 s16, v254, 15
	v_readlane_b32 s18, v254, 17
	v_readlane_b32 s19, v254, 18
	v_readlane_b32 s17, v254, 16
	v_readlane_b32 s20, v254, 19
	v_mov_b64_e32 v[100:101], s[18:19]
	v_mad_i64_i32 v[100:101], s[4:5], v110, s89, v[100:101]
	s_movk_i32 s4, 0xec00
	v_lshl_add_u64 v[100:101], v[176:177], 1, v[100:101]
	s_mov_b32 s5, -1
	v_readlane_b32 s21, v254, 20
	v_readlane_b32 s22, v254, 21
	v_readlane_b32 s23, v254, 22
	v_readlane_b32 s24, v254, 23
	v_readlane_b32 s25, v254, 24
	v_readlane_b32 s26, v254, 25
	v_readlane_b32 s27, v254, 26
	v_readlane_b32 s28, v254, 27
	v_readlane_b32 s29, v254, 28
	v_readlane_b32 s30, v254, 29
	v_readlane_b32 s31, v254, 30
	v_lshl_add_u64 v[100:101], v[100:101], 0, s[4:5]
	s_mov_b64 s[4:5], 0

.Lg16_out_k:
	s_add_i32 s9, s3, 2
	s_min_u32 s10, s9, 30
	s_lshl_b32 s96, s10, 13
	v_lshl_add_u64 v[166:167], v[188:189], 0, s[96:97]
	global_load_dwordx4 v[160:163], v[166:167], off offset:-2048
	global_load_dwordx4 v[164:167], v[166:167], off offset:2048
	ds_read_b128 v[196:199], v246 offset:0
	ds_read_b128 v[200:203], v246 offset:1024
	ds_read_b128 v[204:207], v246 offset:2048
	ds_read_b128 v[242:245], v246 offset:3072
	s_lshl_b32 s96, s10, 11
	v_lshl_add_u64 v[248:249], v[184:185], 0, s[96:97]
	v_lshl_add_u64 v[250:251], v[186:187], 0, s[96:97]
	s_waitcnt vmcnt(8) lgkmcnt(3)
	v_mfma_f32_16x16x32_bf16 v[112:115], v[128:131], v[196:199], v[112:115]
	v_mfma_f32_16x16x32_bf16 v[120:123], v[132:135], v[196:199], v[120:123]
	v_mfma_f32_16x16x32_bf16 v[48:51], v[136:139], v[196:199], v[48:51]
	v_mfma_f32_16x16x32_bf16 v[56:59], v[140:143], v[196:199], v[56:59]
	ds_read_b128 v[196:199], v246 offset:4096
	s_waitcnt lgkmcnt(3)
	v_mfma_f32_16x16x32_bf16 v[116:119], v[128:131], v[200:203], v[116:119]
	v_mfma_f32_16x16x32_bf16 v[124:127], v[132:135], v[200:203], v[124:127]
	v_mfma_f32_16x16x32_bf16 v[52:55], v[136:139], v[200:203], v[52:55]
	v_mfma_f32_16x16x32_bf16 v[60:63], v[140:143], v[200:203], v[60:63]
	ds_read_b128 v[200:203], v246 offset:5120
	s_waitcnt lgkmcnt(3)
	v_mfma_f32_16x16x32_bf16 v[96:99], v[128:131], v[204:207], v[96:99]
	v_mfma_f32_16x16x32_bf16 v[104:107], v[132:135], v[204:207], v[104:107]
	v_mfma_f32_16x16x32_bf16 v[32:35], v[136:139], v[204:207], v[32:35]
	v_mfma_f32_16x16x32_bf16 v[40:43], v[140:143], v[204:207], v[40:43]
	ds_read_b128 v[204:207], v246 offset:6144
	s_waitcnt lgkmcnt(3)
	v_mfma_f32_16x16x32_bf16 v[100:103], v[128:131], v[242:245], v[100:103]
	v_mfma_f32_16x16x32_bf16 v[108:111], v[132:135], v[242:245], v[108:111]
	v_mfma_f32_16x16x32_bf16 v[36:39], v[136:139], v[242:245], v[36:39]
	v_mfma_f32_16x16x32_bf16 v[44:47], v[140:143], v[242:245], v[44:47]
	ds_read_b128 v[242:245], v246 offset:7168
	s_waitcnt vmcnt(6)
	ds_write_b128 v241, v[168:171] offset:8192
	ds_write_b128 v241, v[172:175] offset:12288
	s_waitcnt lgkmcnt(5)
	v_mfma_f32_16x16x32_bf16 v[80:83], v[128:131], v[196:199], v[80:83]
	v_mfma_f32_16x16x32_bf16 v[88:91], v[132:135], v[196:199], v[88:91]
	v_mfma_f32_16x16x32_bf16 v[16:19], v[136:139], v[196:199], v[16:19]
	v_mfma_f32_16x16x32_bf16 v[24:27], v[140:143], v[196:199], v[24:27]
	s_waitcnt lgkmcnt(4)
	v_mfma_f32_16x16x32_bf16 v[84:87], v[128:131], v[200:203], v[84:87]
	v_mfma_f32_16x16x32_bf16 v[92:95], v[132:135], v[200:203], v[92:95]
	v_mfma_f32_16x16x32_bf16 v[20:23], v[136:139], v[200:203], v[20:23]
	v_mfma_f32_16x16x32_bf16 v[28:31], v[140:143], v[200:203], v[28:31]
	s_waitcnt lgkmcnt(3)
	v_mfma_f32_16x16x32_bf16 v[64:67], v[128:131], v[204:207], v[64:67]
	v_mfma_f32_16x16x32_bf16 v[72:75], v[132:135], v[204:207], v[72:75]
	v_mfma_f32_16x16x32_bf16 v[0:3], v[136:139], v[204:207], v[0:3]
	v_mfma_f32_16x16x32_bf16 v[8:11], v[140:143], v[204:207], v[8:11]
	s_waitcnt lgkmcnt(2)
	v_mfma_f32_16x16x32_bf16 v[68:71], v[128:131], v[242:245], v[68:71]
	v_mfma_f32_16x16x32_bf16 v[76:79], v[132:135], v[242:245], v[76:79]
	v_mfma_f32_16x16x32_bf16 v[4:7], v[136:139], v[242:245], v[4:7]
	v_mfma_f32_16x16x32_bf16 v[12:15], v[140:143], v[242:245], v[12:15]
	global_load_dwordx4 v[128:131], v[248:249], off
	global_load_dwordx4 v[132:135], v[248:249], off offset:256
	global_load_dwordx4 v[136:139], v[250:251], off
	global_load_dwordx4 v[140:143], v[250:251], off offset:256
	s_waitcnt lgkmcnt(0)
	s_barrier
	s_add_i32 s9, s3, 3
	s_min_u32 s10, s9, 31
	s_lshl_b32 s96, s10, 13
	v_lshl_add_u64 v[174:175], v[188:189], 0, s[96:97]
	global_load_dwordx4 v[168:171], v[174:175], off offset:-2048
	global_load_dwordx4 v[172:175], v[174:175], off offset:2048
	ds_read_b128 v[196:199], v246 offset:8192
	ds_read_b128 v[200:203], v246 offset:9216
	ds_read_b128 v[204:207], v246 offset:10240
	ds_read_b128 v[242:245], v246 offset:11264
	s_lshl_b32 s96, s10, 11
	v_lshl_add_u64 v[248:249], v[184:185], 0, s[96:97]
	v_lshl_add_u64 v[250:251], v[186:187], 0, s[96:97]
	s_waitcnt vmcnt(8) lgkmcnt(3)
	v_mfma_f32_16x16x32_bf16 v[112:115], v[144:147], v[196:199], v[112:115]
	v_mfma_f32_16x16x32_bf16 v[120:123], v[148:151], v[196:199], v[120:123]
	v_mfma_f32_16x16x32_bf16 v[48:51], v[152:155], v[196:199], v[48:51]
	v_mfma_f32_16x16x32_bf16 v[56:59], v[156:159], v[196:199], v[56:59]
	ds_read_b128 v[196:199], v246 offset:12288
	s_waitcnt lgkmcnt(3)
	v_mfma_f32_16x16x32_bf16 v[116:119], v[144:147], v[200:203], v[116:119]
	v_mfma_f32_16x16x32_bf16 v[124:127], v[148:151], v[200:203], v[124:127]
	v_mfma_f32_16x16x32_bf16 v[52:55], v[152:155], v[200:203], v[52:55]
	v_mfma_f32_16x16x32_bf16 v[60:63], v[156:159], v[200:203], v[60:63]
	ds_read_b128 v[200:203], v246 offset:13312
	s_waitcnt lgkmcnt(3)
	v_mfma_f32_16x16x32_bf16 v[96:99], v[144:147], v[204:207], v[96:99]
	v_mfma_f32_16x16x32_bf16 v[104:107], v[148:151], v[204:207], v[104:107]
	v_mfma_f32_16x16x32_bf16 v[32:35], v[152:155], v[204:207], v[32:35]
	v_mfma_f32_16x16x32_bf16 v[40:43], v[156:159], v[204:207], v[40:43]
	ds_read_b128 v[204:207], v246 offset:14336
	s_waitcnt lgkmcnt(3)
	v_mfma_f32_16x16x32_bf16 v[100:103], v[144:147], v[242:245], v[100:103]
	v_mfma_f32_16x16x32_bf16 v[108:111], v[148:151], v[242:245], v[108:111]
	v_mfma_f32_16x16x32_bf16 v[36:39], v[152:155], v[242:245], v[36:39]
	v_mfma_f32_16x16x32_bf16 v[44:47], v[156:159], v[242:245], v[44:47]
	ds_read_b128 v[242:245], v246 offset:15360
	s_waitcnt vmcnt(6)
	ds_write_b128 v241, v[160:163] offset:0
	ds_write_b128 v241, v[164:167] offset:4096
	s_waitcnt lgkmcnt(5)
	v_mfma_f32_16x16x32_bf16 v[80:83], v[144:147], v[196:199], v[80:83]
	v_mfma_f32_16x16x32_bf16 v[88:91], v[148:151], v[196:199], v[88:91]
	v_mfma_f32_16x16x32_bf16 v[16:19], v[152:155], v[196:199], v[16:19]
	v_mfma_f32_16x16x32_bf16 v[24:27], v[156:159], v[196:199], v[24:27]
	s_waitcnt lgkmcnt(4)
	v_mfma_f32_16x16x32_bf16 v[84:87], v[144:147], v[200:203], v[84:87]
	v_mfma_f32_16x16x32_bf16 v[92:95], v[148:151], v[200:203], v[92:95]
	v_mfma_f32_16x16x32_bf16 v[20:23], v[152:155], v[200:203], v[20:23]
	v_mfma_f32_16x16x32_bf16 v[28:31], v[156:159], v[200:203], v[28:31]
	s_waitcnt lgkmcnt(3)
	v_mfma_f32_16x16x32_bf16 v[64:67], v[144:147], v[204:207], v[64:67]
	v_mfma_f32_16x16x32_bf16 v[72:75], v[148:151], v[204:207], v[72:75]
	v_mfma_f32_16x16x32_bf16 v[0:3], v[152:155], v[204:207], v[0:3]
	v_mfma_f32_16x16x32_bf16 v[8:11], v[156:159], v[204:207], v[8:11]
	s_waitcnt lgkmcnt(2)
	v_mfma_f32_16x16x32_bf16 v[68:71], v[144:147], v[242:245], v[68:71]
	v_mfma_f32_16x16x32_bf16 v[76:79], v[148:151], v[242:245], v[76:79]
	v_mfma_f32_16x16x32_bf16 v[4:7], v[152:155], v[242:245], v[4:7]
	v_mfma_f32_16x16x32_bf16 v[12:15], v[156:159], v[242:245], v[12:15]
	global_load_dwordx4 v[144:147], v[248:249], off
	global_load_dwordx4 v[148:151], v[248:249], off offset:256
	global_load_dwordx4 v[152:155], v[250:251], off
	global_load_dwordx4 v[156:159], v[250:251], off offset:256
	s_add_i32 s3, s3, 2
	s_cmp_lt_u32 s3, 30
	s_waitcnt lgkmcnt(0)
	s_barrier
	s_cbranch_scc1 .Lg16_out_k
	ds_read_b128 v[196:199], v246 offset:0
	ds_read_b128 v[200:203], v246 offset:1024
	ds_read_b128 v[204:207], v246 offset:2048
	ds_read_b128 v[242:245], v246 offset:3072
	s_waitcnt vmcnt(6) lgkmcnt(3)
	v_mfma_f32_16x16x32_bf16 v[112:115], v[128:131], v[196:199], v[112:115]
	v_mfma_f32_16x16x32_bf16 v[120:123], v[132:135], v[196:199], v[120:123]
	v_mfma_f32_16x16x32_bf16 v[48:51], v[136:139], v[196:199], v[48:51]
	v_mfma_f32_16x16x32_bf16 v[56:59], v[140:143], v[196:199], v[56:59]
	ds_read_b128 v[196:199], v246 offset:4096
	s_waitcnt lgkmcnt(3)
	v_mfma_f32_16x16x32_bf16 v[116:119], v[128:131], v[200:203], v[116:119]
	v_mfma_f32_16x16x32_bf16 v[124:127], v[132:135], v[200:203], v[124:127]
	v_mfma_f32_16x16x32_bf16 v[52:55], v[136:139], v[200:203], v[52:55]
	v_mfma_f32_16x16x32_bf16 v[60:63], v[140:143], v[200:203], v[60:63]
	ds_read_b128 v[200:203], v246 offset:5120
	s_waitcnt lgkmcnt(3)
	v_mfma_f32_16x16x32_bf16 v[96:99], v[128:131], v[204:207], v[96:99]
	v_mfma_f32_16x16x32_bf16 v[104:107], v[132:135], v[204:207], v[104:107]
	v_mfma_f32_16x16x32_bf16 v[32:35], v[136:139], v[204:207], v[32:35]
	v_mfma_f32_16x16x32_bf16 v[40:43], v[140:143], v[204:207], v[40:43]
	ds_read_b128 v[204:207], v246 offset:6144
	s_waitcnt lgkmcnt(3)
	v_mfma_f32_16x16x32_bf16 v[100:103], v[128:131], v[242:245], v[100:103]
	v_mfma_f32_16x16x32_bf16 v[108:111], v[132:135], v[242:245], v[108:111]
	v_mfma_f32_16x16x32_bf16 v[36:39], v[136:139], v[242:245], v[36:39]
	v_mfma_f32_16x16x32_bf16 v[44:47], v[140:143], v[242:245], v[44:47]
	ds_read_b128 v[242:245], v246 offset:7168
	s_waitcnt vmcnt(4)
	ds_write_b128 v241, v[168:171] offset:8192
	ds_write_b128 v241, v[172:175] offset:12288
	s_waitcnt lgkmcnt(5)
	v_mfma_f32_16x16x32_bf16 v[80:83], v[128:131], v[196:199], v[80:83]
	v_mfma_f32_16x16x32_bf16 v[88:91], v[132:135], v[196:199], v[88:91]
	v_mfma_f32_16x16x32_bf16 v[16:19], v[136:139], v[196:199], v[16:19]
	v_mfma_f32_16x16x32_bf16 v[24:27], v[140:143], v[196:199], v[24:27]
	s_waitcnt lgkmcnt(4)
	v_mfma_f32_16x16x32_bf16 v[84:87], v[128:131], v[200:203], v[84:87]
	v_mfma_f32_16x16x32_bf16 v[92:95], v[132:135], v[200:203], v[92:95]
	v_mfma_f32_16x16x32_bf16 v[20:23], v[136:139], v[200:203], v[20:23]
	v_mfma_f32_16x16x32_bf16 v[28:31], v[140:143], v[200:203], v[28:31]
	s_waitcnt lgkmcnt(3)
	v_mfma_f32_16x16x32_bf16 v[64:67], v[128:131], v[204:207], v[64:67]
	v_mfma_f32_16x16x32_bf16 v[72:75], v[132:135], v[204:207], v[72:75]
	v_mfma_f32_16x16x32_bf16 v[0:3], v[136:139], v[204:207], v[0:3]
	v_mfma_f32_16x16x32_bf16 v[8:11], v[140:143], v[204:207], v[8:11]
	s_waitcnt lgkmcnt(2)
	v_mfma_f32_16x16x32_bf16 v[68:71], v[128:131], v[242:245], v[68:71]
	v_mfma_f32_16x16x32_bf16 v[76:79], v[132:135], v[242:245], v[76:79]
	v_mfma_f32_16x16x32_bf16 v[4:7], v[136:139], v[242:245], v[4:7]
	v_mfma_f32_16x16x32_bf16 v[12:15], v[140:143], v[242:245], v[12:15]
	s_waitcnt lgkmcnt(0)
	s_barrier
	ds_read_b128 v[196:199], v246 offset:8192
	ds_read_b128 v[200:203], v246 offset:9216
	ds_read_b128 v[204:207], v246 offset:10240
	ds_read_b128 v[242:245], v246 offset:11264
	s_waitcnt vmcnt(0) lgkmcnt(3)
	v_mfma_f32_16x16x32_bf16 v[112:115], v[144:147], v[196:199], v[112:115]
	v_mfma_f32_16x16x32_bf16 v[120:123], v[148:151], v[196:199], v[120:123]
	v_mfma_f32_16x16x32_bf16 v[48:51], v[152:155], v[196:199], v[48:51]
	v_mfma_f32_16x16x32_bf16 v[56:59], v[156:159], v[196:199], v[56:59]
	ds_read_b128 v[196:199], v246 offset:12288
	s_waitcnt lgkmcnt(3)
	v_mfma_f32_16x16x32_bf16 v[116:119], v[144:147], v[200:203], v[116:119]
	v_mfma_f32_16x16x32_bf16 v[124:127], v[148:151], v[200:203], v[124:127]
	v_mfma_f32_16x16x32_bf16 v[52:55], v[152:155], v[200:203], v[52:55]
	v_mfma_f32_16x16x32_bf16 v[60:63], v[156:159], v[200:203], v[60:63]
	ds_read_b128 v[200:203], v246 offset:13312
	s_waitcnt lgkmcnt(3)
	v_mfma_f32_16x16x32_bf16 v[96:99], v[144:147], v[204:207], v[96:99]
	v_mfma_f32_16x16x32_bf16 v[104:107], v[148:151], v[204:207], v[104:107]
	v_mfma_f32_16x16x32_bf16 v[32:35], v[152:155], v[204:207], v[32:35]
	v_mfma_f32_16x16x32_bf16 v[40:43], v[156:159], v[204:207], v[40:43]
	ds_read_b128 v[204:207], v246 offset:14336
	s_waitcnt lgkmcnt(3)
	v_mfma_f32_16x16x32_bf16 v[100:103], v[144:147], v[242:245], v[100:103]
	v_mfma_f32_16x16x32_bf16 v[108:111], v[148:151], v[242:245], v[108:111]
	v_mfma_f32_16x16x32_bf16 v[36:39], v[152:155], v[242:245], v[36:39]
	v_mfma_f32_16x16x32_bf16 v[44:47], v[156:159], v[242:245], v[44:47]
	ds_read_b128 v[242:245], v246 offset:15360
	s_waitcnt lgkmcnt(3)
	v_mfma_f32_16x16x32_bf16 v[80:83], v[144:147], v[196:199], v[80:83]
	v_mfma_f32_16x16x32_bf16 v[88:91], v[148:151], v[196:199], v[88:91]
	v_mfma_f32_16x16x32_bf16 v[16:19], v[152:155], v[196:199], v[16:19]
	v_mfma_f32_16x16x32_bf16 v[24:27], v[156:159], v[196:199], v[24:27]
	s_waitcnt lgkmcnt(2)
	v_mfma_f32_16x16x32_bf16 v[84:87], v[144:147], v[200:203], v[84:87]
	v_mfma_f32_16x16x32_bf16 v[92:95], v[148:151], v[200:203], v[92:95]
	v_mfma_f32_16x16x32_bf16 v[20:23], v[152:155], v[200:203], v[20:23]
	v_mfma_f32_16x16x32_bf16 v[28:31], v[156:159], v[200:203], v[28:31]
	s_waitcnt lgkmcnt(1)
	v_mfma_f32_16x16x32_bf16 v[64:67], v[144:147], v[204:207], v[64:67]
	v_mfma_f32_16x16x32_bf16 v[72:75], v[148:151], v[204:207], v[72:75]
	v_mfma_f32_16x16x32_bf16 v[0:3], v[152:155], v[204:207], v[0:3]
	v_mfma_f32_16x16x32_bf16 v[8:11], v[156:159], v[204:207], v[8:11]
	s_waitcnt lgkmcnt(0)
	v_mfma_f32_16x16x32_bf16 v[68:71], v[144:147], v[242:245], v[68:71]
	v_mfma_f32_16x16x32_bf16 v[76:79], v[148:151], v[242:245], v[76:79]
	v_mfma_f32_16x16x32_bf16 v[4:7], v[152:155], v[242:245], v[4:7]
	v_mfma_f32_16x16x32_bf16 v[12:15], v[156:159], v[242:245], v[12:15]
	s_waitcnt lgkmcnt(0)
	s_barrier
	s_nop 7
	v_permlane16_swap_b32_e32 v112, v116
	v_permlane16_swap_b32_e32 v113, v117
	v_permlane16_swap_b32_e32 v114, v118
	v_permlane16_swap_b32_e32 v115, v119
	v_permlane16_swap_b32_e32 v120, v124
	v_permlane16_swap_b32_e32 v121, v125
	v_permlane16_swap_b32_e32 v122, v126
	v_permlane16_swap_b32_e32 v123, v127
	v_permlane16_swap_b32_e32 v96, v100
	v_permlane16_swap_b32_e32 v97, v101
	v_permlane16_swap_b32_e32 v98, v102
	v_permlane16_swap_b32_e32 v99, v103
	v_permlane16_swap_b32_e32 v104, v108
	v_permlane16_swap_b32_e32 v105, v109
	v_permlane16_swap_b32_e32 v106, v110
	v_permlane16_swap_b32_e32 v107, v111
	v_permlane16_swap_b32_e32 v80, v84
	v_permlane16_swap_b32_e32 v81, v85
	v_permlane16_swap_b32_e32 v82, v86
	v_permlane16_swap_b32_e32 v83, v87
	v_permlane16_swap_b32_e32 v88, v92
	v_permlane16_swap_b32_e32 v89, v93
	v_permlane16_swap_b32_e32 v90, v94
	v_permlane16_swap_b32_e32 v91, v95
	v_permlane16_swap_b32_e32 v64, v68
	v_permlane16_swap_b32_e32 v65, v69
	v_permlane16_swap_b32_e32 v66, v70
	v_permlane16_swap_b32_e32 v67, v71
	v_permlane16_swap_b32_e32 v72, v76
	v_permlane16_swap_b32_e32 v73, v77
	v_permlane16_swap_b32_e32 v74, v78
	v_permlane16_swap_b32_e32 v75, v79
	v_permlane16_swap_b32_e32 v48, v52
	v_permlane16_swap_b32_e32 v49, v53
	v_permlane16_swap_b32_e32 v50, v54
	v_permlane16_swap_b32_e32 v51, v55
	v_permlane16_swap_b32_e32 v56, v60
	v_permlane16_swap_b32_e32 v57, v61
	v_permlane16_swap_b32_e32 v58, v62
	v_permlane16_swap_b32_e32 v59, v63
	v_permlane16_swap_b32_e32 v32, v36
	v_permlane16_swap_b32_e32 v33, v37
	v_permlane16_swap_b32_e32 v34, v38
	v_permlane16_swap_b32_e32 v35, v39
	v_permlane16_swap_b32_e32 v40, v44
	v_permlane16_swap_b32_e32 v41, v45
	v_permlane16_swap_b32_e32 v42, v46
	v_permlane16_swap_b32_e32 v43, v47
	v_permlane16_swap_b32_e32 v16, v20
	v_permlane16_swap_b32_e32 v17, v21
	v_permlane16_swap_b32_e32 v18, v22
	v_permlane16_swap_b32_e32 v19, v23
	v_permlane16_swap_b32_e32 v24, v28
	v_permlane16_swap_b32_e32 v25, v29
	v_permlane16_swap_b32_e32 v26, v30
	v_permlane16_swap_b32_e32 v27, v31
	v_permlane16_swap_b32_e32 v0, v4
	v_permlane16_swap_b32_e32 v1, v5
	v_permlane16_swap_b32_e32 v2, v6
	v_permlane16_swap_b32_e32 v3, v7
	v_permlane16_swap_b32_e32 v8, v12
	v_permlane16_swap_b32_e32 v9, v13
	v_permlane16_swap_b32_e32 v10, v14
	v_permlane16_swap_b32_e32 v11, v15
	v_permlane32_swap_b32_e32 v112, v116
	v_permlane32_swap_b32_e32 v113, v117
	v_permlane32_swap_b32_e32 v114, v118
	v_permlane32_swap_b32_e32 v115, v119
	v_permlane32_swap_b32_e32 v120, v124
	v_permlane32_swap_b32_e32 v121, v125
	v_permlane32_swap_b32_e32 v122, v126
	v_permlane32_swap_b32_e32 v123, v127
	v_permlane32_swap_b32_e32 v96, v100
	v_permlane32_swap_b32_e32 v97, v101
	v_permlane32_swap_b32_e32 v98, v102
	v_permlane32_swap_b32_e32 v99, v103
	v_permlane32_swap_b32_e32 v104, v108
	v_permlane32_swap_b32_e32 v105, v109
	v_permlane32_swap_b32_e32 v106, v110
	v_permlane32_swap_b32_e32 v107, v111
	v_permlane32_swap_b32_e32 v80, v84
	v_permlane32_swap_b32_e32 v81, v85
	v_permlane32_swap_b32_e32 v82, v86
	v_permlane32_swap_b32_e32 v83, v87
	v_permlane32_swap_b32_e32 v88, v92
	v_permlane32_swap_b32_e32 v89, v93
	v_permlane32_swap_b32_e32 v90, v94
	v_permlane32_swap_b32_e32 v91, v95
	v_permlane32_swap_b32_e32 v64, v68
	v_permlane32_swap_b32_e32 v65, v69
	v_permlane32_swap_b32_e32 v66, v70
	v_permlane32_swap_b32_e32 v67, v71
	v_permlane32_swap_b32_e32 v72, v76
	v_permlane32_swap_b32_e32 v73, v77
	v_permlane32_swap_b32_e32 v74, v78
	v_permlane32_swap_b32_e32 v75, v79
	v_permlane32_swap_b32_e32 v48, v52
	v_permlane32_swap_b32_e32 v49, v53
	v_permlane32_swap_b32_e32 v50, v54
	v_permlane32_swap_b32_e32 v51, v55
	v_permlane32_swap_b32_e32 v56, v60
	v_permlane32_swap_b32_e32 v57, v61
	v_permlane32_swap_b32_e32 v58, v62
	v_permlane32_swap_b32_e32 v59, v63
	v_permlane32_swap_b32_e32 v32, v36
	v_permlane32_swap_b32_e32 v33, v37
	v_permlane32_swap_b32_e32 v34, v38
	v_permlane32_swap_b32_e32 v35, v39
	v_permlane32_swap_b32_e32 v40, v44
	v_permlane32_swap_b32_e32 v41, v45
	v_permlane32_swap_b32_e32 v42, v46
	v_permlane32_swap_b32_e32 v43, v47
	v_permlane32_swap_b32_e32 v16, v20
	v_permlane32_swap_b32_e32 v17, v21
	v_permlane32_swap_b32_e32 v18, v22
	v_permlane32_swap_b32_e32 v19, v23
	v_permlane32_swap_b32_e32 v24, v28
	v_permlane32_swap_b32_e32 v25, v29
	v_permlane32_swap_b32_e32 v26, v30
	v_permlane32_swap_b32_e32 v27, v31
	v_permlane32_swap_b32_e32 v0, v4
	v_permlane32_swap_b32_e32 v1, v5
	v_permlane32_swap_b32_e32 v2, v6
	v_permlane32_swap_b32_e32 v3, v7
	v_permlane32_swap_b32_e32 v8, v12
	v_permlane32_swap_b32_e32 v9, v13
	v_permlane32_swap_b32_e32 v10, v14
	v_permlane32_swap_b32_e32 v11, v15
	s_waitcnt vmcnt(0)
	s_movk_i32 s3, 0x2400
	s_waitcnt vmcnt(6)
	v_lshlrev_b32_e32 v128, 2, v181
	s_waitcnt vmcnt(0)
	v_and_b32_e32 v133, 0xffffffc0, v181
	v_mul_lo_u32 v129, v237, s3
	v_lshlrev_b32_e32 v130, 2, v238
	v_and_b32_e32 v128, 60, v128
	v_lshl_add_u32 v176, s8, 8, v133
	v_mul_u32_u24_e32 v133, 0x110, v183
	v_or_b32_e32 v131, v129, v130
	v_lshl_or_b32 v132, v128, 2, v129
	v_lshl_or_b32 v128, s2, 7, v128
	v_lshlrev_b32_e32 v133, 2, v133
	v_lshrrev_b32_e32 v175, 4, v239
	s_movk_i32 s2, 0x110
	v_add_u32_e32 v147, v131, v133
	v_add3_u32 v148, v129, v133, v130
	v_mad_u32_u24 v146, v175, s2, v132
	v_readlane_b32 s2, v254, 39
	v_readlane_b32 s8, v253, 36
	v_add_u32_e32 v149, 0x800, v147
	v_add_u32_e32 v150, 0x800, v148
	v_add_u32_e32 v151, 0xa00, v148
	v_mov_b32_e32 v160, s2
	v_readlane_b32 s2, v254, 37
	v_readlane_b32 s9, v253, 37
	v_readlane_b32 s10, v253, 38
	v_readlane_b32 s11, v253, 39
	v_readlane_b32 s12, v253, 40
	v_readlane_b32 s13, v253, 41
	v_readlane_b32 s14, v253, 42
	v_readlane_b32 s15, v253, 43
	v_readlane_b32 s16, v253, 44
	v_readlane_b32 s17, v253, 45
	ds_write2_b32 v147, v112, v113 offset1:68
	ds_write2_b32 v148, v96, v97 offset0:32 offset1:100
	ds_write2_b32 v147, v114, v115 offset0:136 offset1:204
	ds_write2_b32 v148, v98, v99 offset0:168 offset1:236
	ds_write2_b32 v149, v116, v117 offset0:32 offset1:100
	ds_write2_b32 v150, v100, v101 offset0:64 offset1:132
	ds_write2_b32 v149, v118, v119 offset0:168 offset1:236
	ds_write2_b32 v151, v102, v103 offset0:72 offset1:140
	v_or_b32_e32 v102, v176, v175
	v_mov_b32_e32 v161, s2
	v_readlane_b32 s2, v254, 40
	v_readlane_b32 s18, v253, 46
	v_readlane_b32 s19, v253, 47
	v_readlane_b32 s20, v253, 48
	v_readlane_b32 s21, v253, 49
	v_readlane_b32 s22, v253, 50
	v_readlane_b32 s23, v253, 51
	s_mov_b64 s[8:9], s[16:17]
	v_cmp_gt_i32_e32 vcc, s39, v102
	v_add_u32_e32 v96, 0xffff8000, v102
	v_ashrrev_i32_e32 v97, 31, v102
	v_mov_b32_e32 v162, s2
	v_readlane_b32 s2, v254, 38
	s_mov_b64 s[10:11], s[18:19]
	v_cndmask_b32_e32 v97, 0, v97, vcc
	v_cndmask_b32_e32 v96, v96, v102, vcc
	v_mov_b32_e32 v163, s2
	v_mov_b32_e32 v164, s63
	v_mov_b32_e32 v165, s11
	v_mov_b32_e32 v166, s62
	v_mov_b32_e32 v167, s10
	v_min_i32_e32 v102, 0x8000, v102
	v_add_u32_e32 v152, 0x1000, v147
	v_add_u32_e32 v153, 0x1000, v148
	v_add_u32_e32 v154, 0x1200, v147
	v_add_u32_e32 v155, 0x1200, v148
	v_add_u32_e32 v156, 0x1800, v147
	v_add_u32_e32 v157, 0x1800, v148
	v_add_u32_e32 v158, 0x1a00, v147
	v_add_u32_e32 v159, 0x1c00, v148
	v_ashrrev_i32_e32 v129, 31, v128
	v_cndmask_b32_e32 v99, v160, v161, vcc
	v_cndmask_b32_e32 v98, v162, v163, vcc
	v_lshlrev_b64 v[96:97], 12, v[96:97]
	v_cndmask_b32_e32 v101, v164, v165, vcc
	v_cndmask_b32_e32 v100, v166, v167, vcc
	v_ashrrev_i32_e32 v102, 12, v102
	ds_write2_b32 v152, v120, v121 offset0:64 offset1:132
	ds_write2_b32 v153, v104, v105 offset0:96 offset1:164
	ds_write2_b32 v154, v122, v123 offset0:72 offset1:140
	ds_write2_b32 v155, v106, v107 offset0:104 offset1:172
	ds_write2_b32 v156, v124, v125 offset0:96 offset1:164
	ds_write2_b32 v157, v108, v109 offset0:128 offset1:196
	ds_write2_b32 v158, v126, v127 offset0:104 offset1:172
	ds_write2_b32 v159, v110, v111 offset0:8 offset1:76
	v_lshl_add_u64 v[98:99], v[98:99], 0, v[96:97]
	v_lshl_add_u64 v[100:101], v[100:101], 0, v[96:97]
	v_lshlrev_b64 v[96:97], 2, v[128:129]
	v_mul_hi_i32_i24_e32 v103, 0x6000, v102
	v_mul_i32_i24_e32 v102, 0x6000, v102
	s_waitcnt lgkmcnt(0)
	v_lshl_add_u64 v[98:99], v[98:99], 0, v[96:97]
	v_lshl_add_u64 v[102:103], s[0:1], 0, v[102:103]
	v_lshl_add_u64 v[102:103], v[102:103], 0, v[96:97]
	ds_read_b128 v[104:107], v146
	global_load_dwordx4 v[108:111], v[98:99], off
	global_load_dwordx4 v[112:115], v[102:103], off
	v_or_b32_e32 v168, 4, v175
	v_lshl_add_u64 v[100:101], v[100:101], 0, v[96:97]
	v_or_b32_e32 v169, 8, v175
	v_or_b32_e32 v170, 12, v175
	v_or_b32_e32 v171, 16, v175
	v_or_b32_e32 v172, 20, v175
	v_or_b32_e32 v173, 24, v175
	v_or_b32_e32 v174, 28, v175
	v_or_b32_e32 v181, v176, v174
	v_readlane_b32 s2, v254, 11
	s_add_i32 s4, s4, s2
	s_cmp_lt_i32 s4, s26
	s_mov_b64 s[12:13], s[20:21]
	s_mov_b64 s[14:15], s[22:23]
	s_waitcnt vmcnt(0) lgkmcnt(0)
	v_pk_fma_f32 v[104:105], v[104:105], v[112:113], v[108:109]
	v_pk_fma_f32 v[106:107], v[106:107], v[114:115], v[110:111]
	v_or_b32_e32 v110, v176, v168
	global_store_dwordx4 v[100:101], v[104:107], off
	v_cmp_gt_i32_e32 vcc, s39, v110
	s_nop 0
	v_ashrrev_i32_e32 v104, 31, v110
	v_add_u32_e32 v106, 0xffff8000, v110
	v_cndmask_b32_e32 v105, 0, v104, vcc
	v_cndmask_b32_e32 v104, v106, v110, vcc
	v_cndmask_b32_e32 v107, v160, v161, vcc
	v_cndmask_b32_e32 v106, v162, v163, vcc
	v_lshlrev_b64 v[104:105], 12, v[104:105]
	v_cndmask_b32_e32 v109, v164, v165, vcc
	v_cndmask_b32_e32 v108, v166, v167, vcc
	v_lshl_add_u64 v[106:107], v[106:107], 0, v[104:105]
	v_lshl_add_u64 v[104:105], v[108:109], 0, v[104:105]
	v_min_i32_e32 v108, 0x8000, v110
	v_ashrrev_i32_e32 v108, 12, v108
	v_mul_hi_i32_i24_e32 v109, 0x6000, v108
	v_mul_i32_i24_e32 v108, 0x6000, v108
	v_lshl_add_u64 v[106:107], v[106:107], 0, v[96:97]
	v_lshl_add_u64 v[108:109], s[0:1], 0, v[108:109]
	v_lshl_add_u64 v[108:109], v[108:109], 0, v[96:97]
	ds_read_b128 v[110:113], v146 offset:1088
	global_load_dwordx4 v[114:117], v[106:107], off
	global_load_dwordx4 v[118:121], v[108:109], off
	v_lshl_add_u64 v[104:105], v[104:105], 0, v[96:97]
	s_waitcnt vmcnt(0) lgkmcnt(0)
	v_pk_fma_f32 v[110:111], v[110:111], v[118:119], v[114:115]
	v_pk_fma_f32 v[112:113], v[112:113], v[120:121], v[116:117]
	v_or_b32_e32 v118, v176, v169
	global_store_dwordx4 v[104:105], v[110:113], off
	v_cmp_gt_i32_e32 vcc, s39, v118
	s_nop 0
	v_ashrrev_i32_e32 v110, 31, v118
	v_add_u32_e32 v112, 0xffff8000, v118
	v_cndmask_b32_e32 v111, 0, v110, vcc
	v_cndmask_b32_e32 v110, v112, v118, vcc
	v_cndmask_b32_e32 v113, v160, v161, vcc
	v_cndmask_b32_e32 v112, v162, v163, vcc
	v_lshlrev_b64 v[110:111], 12, v[110:111]
	v_lshl_add_u64 v[112:113], v[112:113], 0, v[110:111]
	v_cndmask_b32_e32 v115, v164, v165, vcc
	v_cndmask_b32_e32 v114, v166, v167, vcc
	v_lshl_add_u64 v[116:117], v[114:115], 0, v[110:111]
	v_lshl_add_u64 v[110:111], v[112:113], 0, v[96:97]
	v_min_i32_e32 v112, 0x8000, v118
	v_ashrrev_i32_e32 v112, 12, v112
	v_mul_hi_i32_i24_e32 v113, 0x6000, v112
	v_mul_i32_i24_e32 v112, 0x6000, v112
	v_lshl_add_u64 v[112:113], s[0:1], 0, v[112:113]
	v_lshl_add_u64 v[114:115], v[112:113], 0, v[96:97]
	v_lshl_add_u64 v[112:113], v[116:117], 0, v[96:97]
	ds_read_b128 v[116:119], v146 offset:2176
	global_load_dwordx4 v[120:123], v[110:111], off
	global_load_dwordx4 v[124:127], v[114:115], off
	s_waitcnt vmcnt(0) lgkmcnt(0)
	v_pk_fma_f32 v[116:117], v[116:117], v[124:125], v[120:121]
	v_pk_fma_f32 v[118:119], v[118:119], v[126:127], v[122:123]
	v_or_b32_e32 v124, v176, v170
	global_store_dwordx4 v[112:113], v[116:119], off
	v_cmp_gt_i32_e32 vcc, s39, v124
	s_nop 0
	v_ashrrev_i32_e32 v116, 31, v124
	v_add_u32_e32 v118, 0xffff8000, v124
	v_cndmask_b32_e32 v117, 0, v116, vcc
	v_cndmask_b32_e32 v116, v118, v124, vcc
	v_cndmask_b32_e32 v119, v160, v161, vcc
	v_cndmask_b32_e32 v118, v162, v163, vcc
	v_lshlrev_b64 v[116:117], 12, v[116:117]
	v_lshl_add_u64 v[118:119], v[118:119], 0, v[116:117]
	v_cndmask_b32_e32 v121, v164, v165, vcc
	v_cndmask_b32_e32 v120, v166, v167, vcc
	v_lshl_add_u64 v[122:123], v[120:121], 0, v[116:117]
	v_lshl_add_u64 v[116:117], v[118:119], 0, v[96:97]
	v_min_i32_e32 v118, 0x8000, v124
	v_ashrrev_i32_e32 v118, 12, v118
	v_mul_hi_i32_i24_e32 v119, 0x6000, v118
	v_mul_i32_i24_e32 v118, 0x6000, v118
	v_lshl_add_u64 v[118:119], s[0:1], 0, v[118:119]
	v_lshl_add_u64 v[120:121], v[118:119], 0, v[96:97]
	v_lshl_add_u64 v[118:119], v[122:123], 0, v[96:97]
	ds_read_b128 v[122:125], v146 offset:3264
	global_load_dwordx4 v[126:129], v[116:117], off
	global_load_dwordx4 v[130:133], v[120:121], off
	s_waitcnt vmcnt(0) lgkmcnt(0)
	v_pk_fma_f32 v[122:123], v[122:123], v[130:131], v[126:127]
	v_pk_fma_f32 v[124:125], v[124:125], v[132:133], v[128:129]
	v_or_b32_e32 v130, v176, v171
	global_store_dwordx4 v[118:119], v[122:125], off
	v_cmp_gt_i32_e32 vcc, s39, v130
	s_nop 0
	v_ashrrev_i32_e32 v122, 31, v130
	v_add_u32_e32 v124, 0xffff8000, v130
	v_cndmask_b32_e32 v123, 0, v122, vcc
	v_cndmask_b32_e32 v122, v124, v130, vcc
	v_cndmask_b32_e32 v125, v160, v161, vcc
	v_cndmask_b32_e32 v124, v162, v163, vcc
	v_lshlrev_b64 v[122:123], 12, v[122:123]
	v_lshl_add_u64 v[124:125], v[124:125], 0, v[122:123]
	v_cndmask_b32_e32 v127, v164, v165, vcc
	v_cndmask_b32_e32 v126, v166, v167, vcc
	v_lshl_add_u64 v[128:129], v[126:127], 0, v[122:123]
	v_lshl_add_u64 v[122:123], v[124:125], 0, v[96:97]
	v_min_i32_e32 v124, 0x8000, v130
	v_ashrrev_i32_e32 v124, 12, v124
	v_mul_hi_i32_i24_e32 v125, 0x6000, v124
	v_mul_i32_i24_e32 v124, 0x6000, v124
	v_lshl_add_u64 v[124:125], s[0:1], 0, v[124:125]
	v_lshl_add_u64 v[126:127], v[124:125], 0, v[96:97]
	v_lshl_add_u64 v[124:125], v[128:129], 0, v[96:97]
	ds_read_b128 v[128:131], v146 offset:4352
	global_load_dwordx4 v[132:135], v[122:123], off
	global_load_dwordx4 v[136:139], v[126:127], off
	s_waitcnt vmcnt(0) lgkmcnt(0)
	v_pk_fma_f32 v[128:129], v[128:129], v[136:137], v[132:133]
	v_pk_fma_f32 v[130:131], v[130:131], v[138:139], v[134:135]
	v_or_b32_e32 v136, v176, v172
	global_store_dwordx4 v[124:125], v[128:131], off
	v_cmp_gt_i32_e32 vcc, s39, v136
	s_nop 0
	v_ashrrev_i32_e32 v128, 31, v136
	v_add_u32_e32 v130, 0xffff8000, v136
	v_cndmask_b32_e32 v129, 0, v128, vcc
	v_cndmask_b32_e32 v128, v130, v136, vcc
	v_cndmask_b32_e32 v131, v160, v161, vcc
	v_cndmask_b32_e32 v130, v162, v163, vcc
	v_lshlrev_b64 v[128:129], 12, v[128:129]
	v_lshl_add_u64 v[130:131], v[130:131], 0, v[128:129]
	v_cndmask_b32_e32 v133, v164, v165, vcc
	v_cndmask_b32_e32 v132, v166, v167, vcc
	v_lshl_add_u64 v[134:135], v[132:133], 0, v[128:129]
	v_lshl_add_u64 v[128:129], v[130:131], 0, v[96:97]
	v_min_i32_e32 v130, 0x8000, v136
	v_ashrrev_i32_e32 v130, 12, v130
	v_mul_hi_i32_i24_e32 v131, 0x6000, v130
	v_mul_i32_i24_e32 v130, 0x6000, v130
	v_lshl_add_u64 v[130:131], s[0:1], 0, v[130:131]
	v_lshl_add_u64 v[132:133], v[130:131], 0, v[96:97]
	v_lshl_add_u64 v[130:131], v[134:135], 0, v[96:97]
	ds_read_b128 v[134:137], v146 offset:5440
	global_load_dwordx4 v[138:141], v[128:129], off
	global_load_dwordx4 v[142:145], v[132:133], off
	s_waitcnt vmcnt(0) lgkmcnt(0)
	v_pk_fma_f32 v[134:135], v[134:135], v[142:143], v[138:139]
	v_pk_fma_f32 v[136:137], v[136:137], v[144:145], v[140:141]
	v_or_b32_e32 v142, v176, v173
	global_store_dwordx4 v[130:131], v[134:137], off
	v_cmp_gt_i32_e32 vcc, s39, v142
	s_nop 0
	v_ashrrev_i32_e32 v134, 31, v142
	v_add_u32_e32 v136, 0xffff8000, v142
	v_cndmask_b32_e32 v135, 0, v134, vcc
	v_cndmask_b32_e32 v134, v136, v142, vcc
	v_cndmask_b32_e32 v137, v160, v161, vcc
	v_cndmask_b32_e32 v136, v162, v163, vcc
	v_lshlrev_b64 v[134:135], 12, v[134:135]
	v_lshl_add_u64 v[136:137], v[136:137], 0, v[134:135]
	v_cndmask_b32_e32 v139, v164, v165, vcc
	v_cndmask_b32_e32 v138, v166, v167, vcc
	v_lshl_add_u64 v[140:141], v[138:139], 0, v[134:135]
	v_lshl_add_u64 v[134:135], v[136:137], 0, v[96:97]
	v_min_i32_e32 v136, 0x8000, v142
	v_ashrrev_i32_e32 v136, 12, v136
	v_mul_hi_i32_i24_e32 v137, 0x6000, v136
	v_mul_i32_i24_e32 v136, 0x6000, v136
	v_lshl_add_u64 v[136:137], s[0:1], 0, v[136:137]
	v_lshl_add_u64 v[138:139], v[136:137], 0, v[96:97]
	v_lshl_add_u64 v[136:137], v[140:141], 0, v[96:97]
	ds_read_b128 v[140:143], v146 offset:6528
	global_load_dwordx4 v[184:187], v[134:135], off
	global_load_dwordx4 v[196:199], v[138:139], off
	v_cmp_gt_i32_e32 vcc, s39, v181
	s_waitcnt vmcnt(0) lgkmcnt(0)
	v_pk_fma_f32 v[140:141], v[140:141], v[196:197], v[184:185]
	v_pk_fma_f32 v[142:143], v[142:143], v[198:199], v[186:187]
	global_store_dwordx4 v[136:137], v[140:143], off
	v_cndmask_b32_e32 v145, v164, v165, vcc
	v_cndmask_b32_e32 v144, v166, v167, vcc
	v_ashrrev_i32_e32 v140, 31, v181
	v_add_u32_e32 v142, 0xffff8000, v181
	v_cndmask_b32_e32 v141, 0, v140, vcc
	v_cndmask_b32_e32 v140, v142, v181, vcc
	v_cndmask_b32_e32 v143, v160, v161, vcc
	v_cndmask_b32_e32 v142, v162, v163, vcc
	v_lshlrev_b64 v[140:141], 12, v[140:141]
	v_lshl_add_u64 v[142:143], v[142:143], 0, v[140:141]
	v_lshl_add_u64 v[184:185], v[144:145], 0, v[140:141]
	v_lshl_add_u64 v[140:141], v[142:143], 0, v[96:97]
	v_min_i32_e32 v142, 0x8000, v181
	v_ashrrev_i32_e32 v142, 12, v142
	v_mul_hi_i32_i24_e32 v143, 0x6000, v142
	v_mul_i32_i24_e32 v142, 0x6000, v142
	v_lshl_add_u64 v[142:143], s[0:1], 0, v[142:143]
	v_lshl_add_u64 v[144:145], v[142:143], 0, v[96:97]
	v_lshl_add_u64 v[142:143], v[184:185], 0, v[96:97]
	ds_read_b128 v[184:187], v146 offset:7616
	global_load_dwordx4 v[196:199], v[140:141], off
	global_load_dwordx4 v[200:203], v[144:145], off
	s_waitcnt vmcnt(0) lgkmcnt(0)
	v_pk_fma_f32 v[184:185], v[184:185], v[200:201], v[196:197]
	v_pk_fma_f32 v[186:187], v[186:187], v[202:203], v[198:199]
	global_store_dwordx4 v[142:143], v[184:187], off
	s_waitcnt lgkmcnt(0)
	ds_write2_b32 v147, v80, v81 offset1:68
	ds_write2_b32 v148, v64, v65 offset0:32 offset1:100
	ds_write2_b32 v147, v82, v83 offset0:136 offset1:204
	ds_write2_b32 v148, v66, v67 offset0:168 offset1:236
	ds_write2_b32 v149, v84, v85 offset0:32 offset1:100
	ds_write2_b32 v150, v68, v69 offset0:64 offset1:132
	ds_write2_b32 v149, v86, v87 offset0:168 offset1:236
	ds_write2_b32 v151, v70, v71 offset0:72 offset1:140
	ds_write2_b32 v152, v88, v89 offset0:64 offset1:132
	ds_write2_b32 v153, v72, v73 offset0:96 offset1:164
	ds_write2_b32 v154, v90, v91 offset0:72 offset1:140
	ds_write2_b32 v155, v74, v75 offset0:104 offset1:172
	ds_write2_b32 v156, v92, v93 offset0:96 offset1:164
	ds_write2_b32 v157, v76, v77 offset0:128 offset1:196
	ds_write2_b32 v158, v94, v95 offset0:104 offset1:172
	ds_write2_b32 v159, v78, v79 offset0:8 offset1:76
	s_waitcnt lgkmcnt(0)
	ds_read_b128 v[64:67], v146
	global_load_dwordx4 v[68:71], v[98:99], off offset:256
	global_load_dwordx4 v[72:75], v[102:103], off offset:256
	s_waitcnt vmcnt(0) lgkmcnt(0)
	v_pk_fma_f32 v[64:65], v[64:65], v[72:73], v[68:69]
	v_pk_fma_f32 v[66:67], v[66:67], v[74:75], v[70:71]
	global_store_dwordx4 v[100:101], v[64:67], off offset:256
	ds_read_b128 v[64:67], v146 offset:1088
	global_load_dwordx4 v[68:71], v[106:107], off offset:256
	global_load_dwordx4 v[72:75], v[108:109], off offset:256
	s_waitcnt vmcnt(0) lgkmcnt(0)
	v_pk_fma_f32 v[64:65], v[64:65], v[72:73], v[68:69]
	v_pk_fma_f32 v[66:67], v[66:67], v[74:75], v[70:71]
	global_store_dwordx4 v[104:105], v[64:67], off offset:256
	ds_read_b128 v[64:67], v146 offset:2176
	global_load_dwordx4 v[68:71], v[110:111], off offset:256
	global_load_dwordx4 v[72:75], v[114:115], off offset:256
	s_waitcnt vmcnt(0) lgkmcnt(0)
	v_pk_fma_f32 v[64:65], v[64:65], v[72:73], v[68:69]
	v_pk_fma_f32 v[66:67], v[66:67], v[74:75], v[70:71]
	global_store_dwordx4 v[112:113], v[64:67], off offset:256
	ds_read_b128 v[64:67], v146 offset:3264
	global_load_dwordx4 v[68:71], v[116:117], off offset:256
	global_load_dwordx4 v[72:75], v[120:121], off offset:256
	s_waitcnt vmcnt(0) lgkmcnt(0)
	v_pk_fma_f32 v[64:65], v[64:65], v[72:73], v[68:69]
	v_pk_fma_f32 v[66:67], v[66:67], v[74:75], v[70:71]
	global_store_dwordx4 v[118:119], v[64:67], off offset:256
	ds_read_b128 v[64:67], v146 offset:4352
	global_load_dwordx4 v[68:71], v[122:123], off offset:256
	global_load_dwordx4 v[72:75], v[126:127], off offset:256
	s_waitcnt vmcnt(0) lgkmcnt(0)
	v_pk_fma_f32 v[64:65], v[64:65], v[72:73], v[68:69]
	v_pk_fma_f32 v[66:67], v[66:67], v[74:75], v[70:71]
	global_store_dwordx4 v[124:125], v[64:67], off offset:256
	ds_read_b128 v[64:67], v146 offset:5440
	global_load_dwordx4 v[68:71], v[128:129], off offset:256
	global_load_dwordx4 v[72:75], v[132:133], off offset:256
	s_waitcnt vmcnt(0) lgkmcnt(0)
	v_pk_fma_f32 v[64:65], v[64:65], v[72:73], v[68:69]
	v_pk_fma_f32 v[66:67], v[66:67], v[74:75], v[70:71]
	global_store_dwordx4 v[130:131], v[64:67], off offset:256
	ds_read_b128 v[64:67], v146 offset:6528
	global_load_dwordx4 v[68:71], v[134:135], off offset:256
	global_load_dwordx4 v[72:75], v[138:139], off offset:256
	s_waitcnt vmcnt(0) lgkmcnt(0)
	v_pk_fma_f32 v[64:65], v[64:65], v[72:73], v[68:69]
	v_pk_fma_f32 v[66:67], v[66:67], v[74:75], v[70:71]
	global_store_dwordx4 v[136:137], v[64:67], off offset:256
	ds_read_b128 v[64:67], v146 offset:7616
	global_load_dwordx4 v[68:71], v[140:141], off offset:256
	global_load_dwordx4 v[72:75], v[144:145], off offset:256
	s_waitcnt vmcnt(0) lgkmcnt(0)
	v_pk_fma_f32 v[64:65], v[64:65], v[72:73], v[68:69]
	v_pk_fma_f32 v[66:67], v[66:67], v[74:75], v[70:71]
	global_store_dwordx4 v[142:143], v[64:67], off offset:256
	v_or_b32_e32 v74, 32, v176
	s_waitcnt lgkmcnt(0)
	ds_write2_b32 v147, v48, v49 offset1:68
	ds_write2_b32 v148, v32, v33 offset0:32 offset1:100
	ds_write2_b32 v147, v50, v51 offset0:136 offset1:204
	ds_write2_b32 v148, v34, v35 offset0:168 offset1:236
	ds_write2_b32 v149, v52, v53 offset0:32 offset1:100
	ds_write2_b32 v150, v36, v37 offset0:64 offset1:132
	ds_write2_b32 v149, v54, v55 offset0:168 offset1:236
	ds_write2_b32 v151, v38, v39 offset0:72 offset1:140
	ds_write2_b32 v152, v56, v57 offset0:64 offset1:132
	ds_write2_b32 v153, v40, v41 offset0:96 offset1:164
	ds_write2_b32 v154, v58, v59 offset0:72 offset1:140
	ds_write2_b32 v155, v42, v43 offset0:104 offset1:172
	ds_write2_b32 v156, v60, v61 offset0:96 offset1:164
	ds_write2_b32 v157, v44, v45 offset0:128 offset1:196
	ds_write2_b32 v158, v62, v63 offset0:104 offset1:172
	ds_write2_b32 v159, v46, v47 offset0:8 offset1:76
	v_or_b32_e32 v40, v74, v175
	v_cmp_gt_i32_e32 vcc, s39, v40
	v_ashrrev_i32_e32 v32, 31, v40
	v_add_u32_e32 v34, 0xffff8000, v40
	v_cndmask_b32_e32 v33, 0, v32, vcc
	v_cndmask_b32_e32 v32, v34, v40, vcc
	v_cndmask_b32_e32 v35, v160, v161, vcc
	v_cndmask_b32_e32 v34, v162, v163, vcc
	v_lshlrev_b64 v[32:33], 12, v[32:33]
	v_lshl_add_u64 v[34:35], v[34:35], 0, v[32:33]
	v_cndmask_b32_e32 v37, v164, v165, vcc
	v_cndmask_b32_e32 v36, v166, v167, vcc
	v_lshl_add_u64 v[38:39], v[36:37], 0, v[32:33]
	v_lshl_add_u64 v[32:33], v[34:35], 0, v[96:97]
	v_min_i32_e32 v34, 0x8000, v40
	v_ashrrev_i32_e32 v34, 12, v34
	v_mul_hi_i32_i24_e32 v35, 0x6000, v34
	v_mul_i32_i24_e32 v34, 0x6000, v34
	s_waitcnt lgkmcnt(0)
	v_lshl_add_u64 v[34:35], s[0:1], 0, v[34:35]
	v_lshl_add_u64 v[36:37], v[34:35], 0, v[96:97]
	v_lshl_add_u64 v[34:35], v[38:39], 0, v[96:97]
	ds_read_b128 v[38:41], v146
	global_load_dwordx4 v[42:45], v[32:33], off
	global_load_dwordx4 v[46:49], v[36:37], off
	v_or_b32_e32 v75, v74, v173
	s_waitcnt vmcnt(0) lgkmcnt(0)
	v_pk_fma_f32 v[38:39], v[38:39], v[46:47], v[42:43]
	v_pk_fma_f32 v[40:41], v[40:41], v[48:49], v[44:45]
	v_or_b32_e32 v46, v74, v168
	global_store_dwordx4 v[34:35], v[38:41], off
	v_cmp_gt_i32_e32 vcc, s39, v46
	s_nop 0
	v_ashrrev_i32_e32 v38, 31, v46
	v_add_u32_e32 v40, 0xffff8000, v46
	v_cndmask_b32_e32 v39, 0, v38, vcc
	v_cndmask_b32_e32 v38, v40, v46, vcc
	v_cndmask_b32_e32 v41, v160, v161, vcc
	v_cndmask_b32_e32 v40, v162, v163, vcc
	v_lshlrev_b64 v[38:39], 12, v[38:39]
	v_lshl_add_u64 v[40:41], v[40:41], 0, v[38:39]
	v_cndmask_b32_e32 v43, v164, v165, vcc
	v_cndmask_b32_e32 v42, v166, v167, vcc
	v_lshl_add_u64 v[44:45], v[42:43], 0, v[38:39]
	v_lshl_add_u64 v[38:39], v[40:41], 0, v[96:97]
	v_min_i32_e32 v40, 0x8000, v46
	v_ashrrev_i32_e32 v40, 12, v40
	v_mul_hi_i32_i24_e32 v41, 0x6000, v40
	v_mul_i32_i24_e32 v40, 0x6000, v40
	v_lshl_add_u64 v[40:41], s[0:1], 0, v[40:41]
	v_lshl_add_u64 v[42:43], v[40:41], 0, v[96:97]
	v_lshl_add_u64 v[40:41], v[44:45], 0, v[96:97]
	ds_read_b128 v[44:47], v146 offset:1088
	global_load_dwordx4 v[48:51], v[38:39], off
	global_load_dwordx4 v[52:55], v[42:43], off
	s_waitcnt vmcnt(0) lgkmcnt(0)
	v_pk_fma_f32 v[44:45], v[44:45], v[52:53], v[48:49]
	v_pk_fma_f32 v[46:47], v[46:47], v[54:55], v[50:51]
	v_or_b32_e32 v52, v74, v169
	global_store_dwordx4 v[40:41], v[44:47], off
	v_cmp_gt_i32_e32 vcc, s39, v52
	s_nop 0
	v_ashrrev_i32_e32 v44, 31, v52
	v_add_u32_e32 v46, 0xffff8000, v52
	v_cndmask_b32_e32 v45, 0, v44, vcc
	v_cndmask_b32_e32 v44, v46, v52, vcc
	v_cndmask_b32_e32 v47, v160, v161, vcc
	v_cndmask_b32_e32 v46, v162, v163, vcc
	v_lshlrev_b64 v[44:45], 12, v[44:45]
	v_lshl_add_u64 v[46:47], v[46:47], 0, v[44:45]
	v_cndmask_b32_e32 v49, v164, v165, vcc
	v_cndmask_b32_e32 v48, v166, v167, vcc
	v_lshl_add_u64 v[50:51], v[48:49], 0, v[44:45]
	v_lshl_add_u64 v[44:45], v[46:47], 0, v[96:97]
	v_min_i32_e32 v46, 0x8000, v52
	v_ashrrev_i32_e32 v46, 12, v46
	v_mul_hi_i32_i24_e32 v47, 0x6000, v46
	v_mul_i32_i24_e32 v46, 0x6000, v46
	v_lshl_add_u64 v[46:47], s[0:1], 0, v[46:47]
	v_lshl_add_u64 v[48:49], v[46:47], 0, v[96:97]
	v_lshl_add_u64 v[46:47], v[50:51], 0, v[96:97]
	ds_read_b128 v[50:53], v146 offset:2176
	global_load_dwordx4 v[54:57], v[44:45], off
	global_load_dwordx4 v[58:61], v[48:49], off
	s_waitcnt vmcnt(0) lgkmcnt(0)
	v_pk_fma_f32 v[50:51], v[50:51], v[58:59], v[54:55]
	v_pk_fma_f32 v[52:53], v[52:53], v[60:61], v[56:57]
	v_or_b32_e32 v58, v74, v170
	global_store_dwordx4 v[46:47], v[50:53], off
	v_cmp_gt_i32_e32 vcc, s39, v58
	s_nop 0
	v_ashrrev_i32_e32 v50, 31, v58
	v_add_u32_e32 v52, 0xffff8000, v58
	v_cndmask_b32_e32 v51, 0, v50, vcc
	v_cndmask_b32_e32 v50, v52, v58, vcc
	v_cndmask_b32_e32 v53, v160, v161, vcc
	v_cndmask_b32_e32 v52, v162, v163, vcc
	v_lshlrev_b64 v[50:51], 12, v[50:51]
	v_lshl_add_u64 v[52:53], v[52:53], 0, v[50:51]
	v_cndmask_b32_e32 v55, v164, v165, vcc
	v_cndmask_b32_e32 v54, v166, v167, vcc
	v_lshl_add_u64 v[56:57], v[54:55], 0, v[50:51]
	v_lshl_add_u64 v[50:51], v[52:53], 0, v[96:97]
	v_min_i32_e32 v52, 0x8000, v58
	v_ashrrev_i32_e32 v52, 12, v52
	v_mul_hi_i32_i24_e32 v53, 0x6000, v52
	v_mul_i32_i24_e32 v52, 0x6000, v52
	v_lshl_add_u64 v[52:53], s[0:1], 0, v[52:53]
	v_lshl_add_u64 v[54:55], v[52:53], 0, v[96:97]
	v_lshl_add_u64 v[52:53], v[56:57], 0, v[96:97]
	ds_read_b128 v[56:59], v146 offset:3264
	global_load_dwordx4 v[60:63], v[50:51], off
	global_load_dwordx4 v[64:67], v[54:55], off
	s_waitcnt vmcnt(0) lgkmcnt(0)
	v_pk_fma_f32 v[56:57], v[56:57], v[64:65], v[60:61]
	v_pk_fma_f32 v[58:59], v[58:59], v[66:67], v[62:63]
	v_or_b32_e32 v64, v74, v171
	global_store_dwordx4 v[52:53], v[56:59], off
	v_cmp_gt_i32_e32 vcc, s39, v64
	s_nop 0
	v_ashrrev_i32_e32 v56, 31, v64
	v_add_u32_e32 v58, 0xffff8000, v64
	v_cndmask_b32_e32 v57, 0, v56, vcc
	v_cndmask_b32_e32 v56, v58, v64, vcc
	v_cndmask_b32_e32 v59, v160, v161, vcc
	v_cndmask_b32_e32 v58, v162, v163, vcc
	v_lshlrev_b64 v[56:57], 12, v[56:57]
	v_lshl_add_u64 v[58:59], v[58:59], 0, v[56:57]
	v_cndmask_b32_e32 v61, v164, v165, vcc
	v_cndmask_b32_e32 v60, v166, v167, vcc
	v_lshl_add_u64 v[62:63], v[60:61], 0, v[56:57]
	v_lshl_add_u64 v[56:57], v[58:59], 0, v[96:97]
	v_min_i32_e32 v58, 0x8000, v64
	v_ashrrev_i32_e32 v58, 12, v58
	v_mul_hi_i32_i24_e32 v59, 0x6000, v58
	v_mul_i32_i24_e32 v58, 0x6000, v58
	v_lshl_add_u64 v[58:59], s[0:1], 0, v[58:59]
	v_lshl_add_u64 v[60:61], v[58:59], 0, v[96:97]
	v_lshl_add_u64 v[58:59], v[62:63], 0, v[96:97]
	ds_read_b128 v[62:65], v146 offset:4352
	global_load_dwordx4 v[66:69], v[56:57], off
	global_load_dwordx4 v[70:73], v[60:61], off
	s_waitcnt vmcnt(0) lgkmcnt(0)
	v_pk_fma_f32 v[62:63], v[62:63], v[70:71], v[66:67]
	v_pk_fma_f32 v[64:65], v[64:65], v[72:73], v[68:69]
	v_or_b32_e32 v70, v74, v172
	global_store_dwordx4 v[58:59], v[62:65], off
	v_cmp_gt_i32_e32 vcc, s39, v70
	s_nop 0
	v_ashrrev_i32_e32 v62, 31, v70
	v_add_u32_e32 v64, 0xffff8000, v70
	v_cndmask_b32_e32 v63, 0, v62, vcc
	v_cndmask_b32_e32 v62, v64, v70, vcc
	v_cndmask_b32_e32 v65, v160, v161, vcc
	v_cndmask_b32_e32 v64, v162, v163, vcc
	v_lshlrev_b64 v[62:63], 12, v[62:63]
	v_lshl_add_u64 v[64:65], v[64:65], 0, v[62:63]
	v_cndmask_b32_e32 v67, v164, v165, vcc
	v_cndmask_b32_e32 v66, v166, v167, vcc
	v_lshl_add_u64 v[68:69], v[66:67], 0, v[62:63]
	v_lshl_add_u64 v[62:63], v[64:65], 0, v[96:97]
	v_min_i32_e32 v64, 0x8000, v70
	v_ashrrev_i32_e32 v64, 12, v64
	v_mul_hi_i32_i24_e32 v65, 0x6000, v64
	v_mul_i32_i24_e32 v64, 0x6000, v64
	v_lshl_add_u64 v[64:65], s[0:1], 0, v[64:65]
	v_lshl_add_u64 v[66:67], v[64:65], 0, v[96:97]
	v_lshl_add_u64 v[64:65], v[68:69], 0, v[96:97]
	ds_read_b128 v[68:71], v146 offset:5440
	global_load_dwordx4 v[76:79], v[62:63], off
	global_load_dwordx4 v[80:83], v[66:67], off
	v_cmp_gt_i32_e32 vcc, s39, v75
	s_waitcnt vmcnt(0) lgkmcnt(0)
	v_pk_fma_f32 v[68:69], v[68:69], v[80:81], v[76:77]
	v_pk_fma_f32 v[70:71], v[70:71], v[82:83], v[78:79]
	global_store_dwordx4 v[64:65], v[68:71], off
	v_cndmask_b32_e32 v73, v164, v165, vcc
	v_cndmask_b32_e32 v72, v166, v167, vcc
	v_ashrrev_i32_e32 v68, 31, v75
	v_add_u32_e32 v70, 0xffff8000, v75
	v_cndmask_b32_e32 v69, 0, v68, vcc
	v_cndmask_b32_e32 v68, v70, v75, vcc
	v_cndmask_b32_e32 v71, v160, v161, vcc
	v_cndmask_b32_e32 v70, v162, v163, vcc
	v_lshlrev_b64 v[68:69], 12, v[68:69]
	v_lshl_add_u64 v[70:71], v[70:71], 0, v[68:69]
	v_lshl_add_u64 v[76:77], v[72:73], 0, v[68:69]
	v_lshl_add_u64 v[68:69], v[70:71], 0, v[96:97]
	v_min_i32_e32 v70, 0x8000, v75
	v_ashrrev_i32_e32 v70, 12, v70
	v_mul_hi_i32_i24_e32 v71, 0x6000, v70
	v_mul_i32_i24_e32 v70, 0x6000, v70
	v_lshl_add_u64 v[70:71], s[0:1], 0, v[70:71]
	v_lshl_add_u64 v[72:73], v[70:71], 0, v[96:97]
	v_lshl_add_u64 v[70:71], v[76:77], 0, v[96:97]
	ds_read_b128 v[76:79], v146 offset:6528
	global_load_dwordx4 v[80:83], v[68:69], off
	global_load_dwordx4 v[84:87], v[72:73], off
	s_waitcnt vmcnt(0) lgkmcnt(0)
	v_pk_fma_f32 v[76:77], v[76:77], v[84:85], v[80:81]
	v_pk_fma_f32 v[78:79], v[78:79], v[86:87], v[82:83]
	v_or_b32_e32 v82, v74, v174
	global_store_dwordx4 v[70:71], v[76:79], off
	v_cmp_gt_i32_e32 vcc, s39, v82
	v_ashrrev_i32_e32 v74, 31, v82
	v_add_u32_e32 v76, 0xffff8000, v82
	v_cndmask_b32_e32 v75, 0, v74, vcc
	v_cndmask_b32_e32 v74, v76, v82, vcc
	v_cndmask_b32_e32 v77, v160, v161, vcc
	v_cndmask_b32_e32 v76, v162, v163, vcc
	v_lshlrev_b64 v[74:75], 12, v[74:75]
	v_lshl_add_u64 v[76:77], v[76:77], 0, v[74:75]
	v_cndmask_b32_e32 v79, v164, v165, vcc
	v_cndmask_b32_e32 v78, v166, v167, vcc
	v_lshl_add_u64 v[80:81], v[78:79], 0, v[74:75]
	v_lshl_add_u64 v[74:75], v[76:77], 0, v[96:97]
	v_min_i32_e32 v76, 0x8000, v82
	v_ashrrev_i32_e32 v76, 12, v76
	v_mul_hi_i32_i24_e32 v77, 0x6000, v76
	v_mul_i32_i24_e32 v76, 0x6000, v76
	v_lshl_add_u64 v[76:77], s[0:1], 0, v[76:77]
	v_lshl_add_u64 v[78:79], v[76:77], 0, v[96:97]
	v_lshl_add_u64 v[76:77], v[80:81], 0, v[96:97]
	ds_read_b128 v[80:83], v146 offset:7616
	global_load_dwordx4 v[84:87], v[74:75], off
	global_load_dwordx4 v[88:91], v[78:79], off
	s_waitcnt vmcnt(0) lgkmcnt(0)
	v_pk_fma_f32 v[80:81], v[80:81], v[88:89], v[84:85]
	v_pk_fma_f32 v[82:83], v[82:83], v[90:91], v[86:87]
	global_store_dwordx4 v[76:77], v[80:83], off
	s_waitcnt lgkmcnt(0)
	ds_write2_b32 v147, v16, v17 offset1:68
	ds_write2_b32 v148, v0, v1 offset0:32 offset1:100
	ds_write2_b32 v147, v18, v19 offset0:136 offset1:204
	ds_write2_b32 v148, v2, v3 offset0:168 offset1:236
	ds_write2_b32 v149, v20, v21 offset0:32 offset1:100
	ds_write2_b32 v150, v4, v5 offset0:64 offset1:132
	ds_write2_b32 v149, v22, v23 offset0:168 offset1:236
	ds_write2_b32 v151, v6, v7 offset0:72 offset1:140
	ds_write2_b32 v152, v24, v25 offset0:64 offset1:132
	ds_write2_b32 v153, v8, v9 offset0:96 offset1:164
	ds_write2_b32 v154, v26, v27 offset0:72 offset1:140
	ds_write2_b32 v155, v10, v11 offset0:104 offset1:172
	ds_write2_b32 v156, v28, v29 offset0:96 offset1:164
	ds_write2_b32 v157, v12, v13 offset0:128 offset1:196
	ds_write2_b32 v158, v30, v31 offset0:104 offset1:172
	ds_write2_b32 v159, v14, v15 offset0:8 offset1:76
	s_waitcnt lgkmcnt(0)
	ds_read_b128 v[0:3], v146
	global_load_dwordx4 v[4:7], v[32:33], off offset:256
	global_load_dwordx4 v[8:11], v[36:37], off offset:256
	s_waitcnt vmcnt(0) lgkmcnt(0)
	v_pk_fma_f32 v[0:1], v[0:1], v[8:9], v[4:5]
	v_pk_fma_f32 v[2:3], v[2:3], v[10:11], v[6:7]
	global_store_dwordx4 v[34:35], v[0:3], off offset:256
	ds_read_b128 v[0:3], v146 offset:1088
	global_load_dwordx4 v[4:7], v[38:39], off offset:256
	global_load_dwordx4 v[8:11], v[42:43], off offset:256
	s_waitcnt vmcnt(0) lgkmcnt(0)
	v_pk_fma_f32 v[0:1], v[0:1], v[8:9], v[4:5]
	v_pk_fma_f32 v[2:3], v[2:3], v[10:11], v[6:7]
	global_store_dwordx4 v[40:41], v[0:3], off offset:256
	ds_read_b128 v[0:3], v146 offset:2176
	global_load_dwordx4 v[4:7], v[44:45], off offset:256
	global_load_dwordx4 v[8:11], v[48:49], off offset:256
	s_waitcnt vmcnt(0) lgkmcnt(0)
	v_pk_fma_f32 v[0:1], v[0:1], v[8:9], v[4:5]
	v_pk_fma_f32 v[2:3], v[2:3], v[10:11], v[6:7]
	global_store_dwordx4 v[46:47], v[0:3], off offset:256
	ds_read_b128 v[0:3], v146 offset:3264
	global_load_dwordx4 v[4:7], v[50:51], off offset:256
	global_load_dwordx4 v[8:11], v[54:55], off offset:256
	s_waitcnt vmcnt(0) lgkmcnt(0)
	v_pk_fma_f32 v[0:1], v[0:1], v[8:9], v[4:5]
	v_pk_fma_f32 v[2:3], v[2:3], v[10:11], v[6:7]
	global_store_dwordx4 v[52:53], v[0:3], off offset:256
	ds_read_b128 v[0:3], v146 offset:4352
	global_load_dwordx4 v[4:7], v[56:57], off offset:256
	global_load_dwordx4 v[8:11], v[60:61], off offset:256
	s_waitcnt vmcnt(0) lgkmcnt(0)
	v_pk_fma_f32 v[0:1], v[0:1], v[8:9], v[4:5]
	v_pk_fma_f32 v[2:3], v[2:3], v[10:11], v[6:7]
	global_store_dwordx4 v[58:59], v[0:3], off offset:256
	ds_read_b128 v[0:3], v146 offset:5440
	global_load_dwordx4 v[4:7], v[62:63], off offset:256
	global_load_dwordx4 v[8:11], v[66:67], off offset:256
	s_waitcnt vmcnt(0) lgkmcnt(0)
	v_pk_fma_f32 v[0:1], v[0:1], v[8:9], v[4:5]
	v_pk_fma_f32 v[2:3], v[2:3], v[10:11], v[6:7]
	global_store_dwordx4 v[64:65], v[0:3], off offset:256
	ds_read_b128 v[0:3], v146 offset:6528
	global_load_dwordx4 v[4:7], v[68:69], off offset:256
	global_load_dwordx4 v[8:11], v[72:73], off offset:256
	s_waitcnt vmcnt(0) lgkmcnt(0)
	v_pk_fma_f32 v[0:1], v[0:1], v[8:9], v[4:5]
	v_pk_fma_f32 v[2:3], v[2:3], v[10:11], v[6:7]
	global_store_dwordx4 v[70:71], v[0:3], off offset:256
	ds_read_b128 v[0:3], v146 offset:7616
	global_load_dwordx4 v[4:7], v[74:75], off offset:256
	global_load_dwordx4 v[8:11], v[78:79], off offset:256
	s_waitcnt vmcnt(0) lgkmcnt(0)
	v_pk_fma_f32 v[0:1], v[0:1], v[8:9], v[4:5]
	v_pk_fma_f32 v[2:3], v[2:3], v[10:11], v[6:7]
	global_store_dwordx4 v[76:77], v[0:3], off offset:256
	s_waitcnt lgkmcnt(0)
	s_barrier
	s_cbranch_scc1 .LBB0_923

.Lg16_gu_k:
	s_add_i32 s8, s1, 2
	s_min_u32 s9, s8, 30
	s_lshl_b32 s96, s9, 13
	v_lshl_add_u64 v[166:167], v[188:189], 0, s[96:97]
	global_load_dwordx4 v[160:163], v[166:167], off offset:-2048
	global_load_dwordx4 v[164:167], v[166:167], off offset:2048
	ds_read_b128 v[196:199], v246 offset:0
	ds_read_b128 v[200:203], v246 offset:1024
	ds_read_b128 v[204:207], v246 offset:2048
	ds_read_b128 v[242:245], v246 offset:3072
	s_lshl_b32 s96, s9, 11
	v_lshl_add_u64 v[248:249], v[184:185], 0, s[96:97]
	v_lshl_add_u64 v[250:251], v[186:187], 0, s[96:97]
	s_waitcnt vmcnt(8) lgkmcnt(3)
	v_mfma_f32_16x16x32_bf16 v[112:115], v[128:131], v[196:199], v[112:115]
	v_mfma_f32_16x16x32_bf16 v[120:123], v[132:135], v[196:199], v[120:123]
	v_mfma_f32_16x16x32_bf16 v[80:83], v[136:139], v[196:199], v[80:83]
	v_mfma_f32_16x16x32_bf16 v[88:91], v[140:143], v[196:199], v[88:91]
	ds_read_b128 v[196:199], v246 offset:4096
	s_waitcnt lgkmcnt(3)
	v_mfma_f32_16x16x32_bf16 v[116:119], v[128:131], v[200:203], v[116:119]
	v_mfma_f32_16x16x32_bf16 v[124:127], v[132:135], v[200:203], v[124:127]
	v_mfma_f32_16x16x32_bf16 v[84:87], v[136:139], v[200:203], v[84:87]
	v_mfma_f32_16x16x32_bf16 v[92:95], v[140:143], v[200:203], v[92:95]
	ds_read_b128 v[200:203], v246 offset:5120
	s_waitcnt lgkmcnt(3)
	v_mfma_f32_16x16x32_bf16 v[96:99], v[128:131], v[204:207], v[96:99]
	v_mfma_f32_16x16x32_bf16 v[104:107], v[132:135], v[204:207], v[104:107]
	v_mfma_f32_16x16x32_bf16 v[64:67], v[136:139], v[204:207], v[64:67]
	v_mfma_f32_16x16x32_bf16 v[72:75], v[140:143], v[204:207], v[72:75]
	ds_read_b128 v[204:207], v246 offset:6144
	s_waitcnt lgkmcnt(3)
	v_mfma_f32_16x16x32_bf16 v[100:103], v[128:131], v[242:245], v[100:103]
	v_mfma_f32_16x16x32_bf16 v[108:111], v[132:135], v[242:245], v[108:111]
	v_mfma_f32_16x16x32_bf16 v[68:71], v[136:139], v[242:245], v[68:71]
	v_mfma_f32_16x16x32_bf16 v[76:79], v[140:143], v[242:245], v[76:79]
	ds_read_b128 v[242:245], v246 offset:7168
	s_waitcnt vmcnt(6)
	ds_write_b128 v241, v[168:171] offset:8192
	ds_write_b128 v241, v[172:175] offset:12288
	s_waitcnt lgkmcnt(5)
	v_mfma_f32_16x16x32_bf16 v[48:51], v[128:131], v[196:199], v[48:51]
	v_mfma_f32_16x16x32_bf16 v[56:59], v[132:135], v[196:199], v[56:59]
	v_mfma_f32_16x16x32_bf16 v[16:19], v[136:139], v[196:199], v[16:19]
	v_mfma_f32_16x16x32_bf16 v[24:27], v[140:143], v[196:199], v[24:27]
	s_waitcnt lgkmcnt(4)
	v_mfma_f32_16x16x32_bf16 v[52:55], v[128:131], v[200:203], v[52:55]
	v_mfma_f32_16x16x32_bf16 v[60:63], v[132:135], v[200:203], v[60:63]
	v_mfma_f32_16x16x32_bf16 v[20:23], v[136:139], v[200:203], v[20:23]
	v_mfma_f32_16x16x32_bf16 v[28:31], v[140:143], v[200:203], v[28:31]
	s_waitcnt lgkmcnt(3)
	v_mfma_f32_16x16x32_bf16 v[32:35], v[128:131], v[204:207], v[32:35]
	v_mfma_f32_16x16x32_bf16 v[40:43], v[132:135], v[204:207], v[40:43]
	v_mfma_f32_16x16x32_bf16 v[0:3], v[136:139], v[204:207], v[0:3]
	v_mfma_f32_16x16x32_bf16 v[8:11], v[140:143], v[204:207], v[8:11]
	s_waitcnt lgkmcnt(2)
	v_mfma_f32_16x16x32_bf16 v[36:39], v[128:131], v[242:245], v[36:39]
	v_mfma_f32_16x16x32_bf16 v[44:47], v[132:135], v[242:245], v[44:47]
	v_mfma_f32_16x16x32_bf16 v[4:7], v[136:139], v[242:245], v[4:7]
	v_mfma_f32_16x16x32_bf16 v[12:15], v[140:143], v[242:245], v[12:15]
	global_load_dwordx4 v[128:131], v[248:249], off
	global_load_dwordx4 v[132:135], v[248:249], off offset:256
	global_load_dwordx4 v[136:139], v[250:251], off
	global_load_dwordx4 v[140:143], v[250:251], off offset:256
	s_waitcnt lgkmcnt(0)
	s_barrier
	s_add_i32 s8, s1, 3
	s_min_u32 s9, s8, 31
	s_lshl_b32 s96, s9, 13
	v_lshl_add_u64 v[174:175], v[188:189], 0, s[96:97]
	global_load_dwordx4 v[168:171], v[174:175], off offset:-2048
	global_load_dwordx4 v[172:175], v[174:175], off offset:2048
	ds_read_b128 v[196:199], v246 offset:8192
	ds_read_b128 v[200:203], v246 offset:9216
	ds_read_b128 v[204:207], v246 offset:10240
	ds_read_b128 v[242:245], v246 offset:11264
	s_lshl_b32 s96, s9, 11
	v_lshl_add_u64 v[248:249], v[184:185], 0, s[96:97]
	v_lshl_add_u64 v[250:251], v[186:187], 0, s[96:97]
	s_waitcnt vmcnt(8) lgkmcnt(3)
	v_mfma_f32_16x16x32_bf16 v[112:115], v[144:147], v[196:199], v[112:115]
	v_mfma_f32_16x16x32_bf16 v[120:123], v[148:151], v[196:199], v[120:123]
	v_mfma_f32_16x16x32_bf16 v[80:83], v[152:155], v[196:199], v[80:83]
	v_mfma_f32_16x16x32_bf16 v[88:91], v[156:159], v[196:199], v[88:91]
	ds_read_b128 v[196:199], v246 offset:12288
	s_waitcnt lgkmcnt(3)
	v_mfma_f32_16x16x32_bf16 v[116:119], v[144:147], v[200:203], v[116:119]
	v_mfma_f32_16x16x32_bf16 v[124:127], v[148:151], v[200:203], v[124:127]
	v_mfma_f32_16x16x32_bf16 v[84:87], v[152:155], v[200:203], v[84:87]
	v_mfma_f32_16x16x32_bf16 v[92:95], v[156:159], v[200:203], v[92:95]
	ds_read_b128 v[200:203], v246 offset:13312
	s_waitcnt lgkmcnt(3)
	v_mfma_f32_16x16x32_bf16 v[96:99], v[144:147], v[204:207], v[96:99]
	v_mfma_f32_16x16x32_bf16 v[104:107], v[148:151], v[204:207], v[104:107]
	v_mfma_f32_16x16x32_bf16 v[64:67], v[152:155], v[204:207], v[64:67]
	v_mfma_f32_16x16x32_bf16 v[72:75], v[156:159], v[204:207], v[72:75]
	ds_read_b128 v[204:207], v246 offset:14336
	s_waitcnt lgkmcnt(3)
	v_mfma_f32_16x16x32_bf16 v[100:103], v[144:147], v[242:245], v[100:103]
	v_mfma_f32_16x16x32_bf16 v[108:111], v[148:151], v[242:245], v[108:111]
	v_mfma_f32_16x16x32_bf16 v[68:71], v[152:155], v[242:245], v[68:71]
	v_mfma_f32_16x16x32_bf16 v[76:79], v[156:159], v[242:245], v[76:79]
	ds_read_b128 v[242:245], v246 offset:15360
	s_waitcnt vmcnt(6)
	ds_write_b128 v241, v[160:163] offset:0
	ds_write_b128 v241, v[164:167] offset:4096
	s_waitcnt lgkmcnt(5)
	v_mfma_f32_16x16x32_bf16 v[48:51], v[144:147], v[196:199], v[48:51]
	v_mfma_f32_16x16x32_bf16 v[56:59], v[148:151], v[196:199], v[56:59]
	v_mfma_f32_16x16x32_bf16 v[16:19], v[152:155], v[196:199], v[16:19]
	v_mfma_f32_16x16x32_bf16 v[24:27], v[156:159], v[196:199], v[24:27]
	s_waitcnt lgkmcnt(4)
	v_mfma_f32_16x16x32_bf16 v[52:55], v[144:147], v[200:203], v[52:55]
	v_mfma_f32_16x16x32_bf16 v[60:63], v[148:151], v[200:203], v[60:63]
	v_mfma_f32_16x16x32_bf16 v[20:23], v[152:155], v[200:203], v[20:23]
	v_mfma_f32_16x16x32_bf16 v[28:31], v[156:159], v[200:203], v[28:31]
	s_waitcnt lgkmcnt(3)
	v_mfma_f32_16x16x32_bf16 v[32:35], v[144:147], v[204:207], v[32:35]
	v_mfma_f32_16x16x32_bf16 v[40:43], v[148:151], v[204:207], v[40:43]
	v_mfma_f32_16x16x32_bf16 v[0:3], v[152:155], v[204:207], v[0:3]
	v_mfma_f32_16x16x32_bf16 v[8:11], v[156:159], v[204:207], v[8:11]
	s_waitcnt lgkmcnt(2)
	v_mfma_f32_16x16x32_bf16 v[36:39], v[144:147], v[242:245], v[36:39]
	v_mfma_f32_16x16x32_bf16 v[44:47], v[148:151], v[242:245], v[44:47]
	v_mfma_f32_16x16x32_bf16 v[4:7], v[152:155], v[242:245], v[4:7]
	v_mfma_f32_16x16x32_bf16 v[12:15], v[156:159], v[242:245], v[12:15]
	global_load_dwordx4 v[144:147], v[248:249], off
	global_load_dwordx4 v[148:151], v[248:249], off offset:256
	global_load_dwordx4 v[152:155], v[250:251], off
	global_load_dwordx4 v[156:159], v[250:251], off offset:256
	s_add_i32 s1, s1, 2
	s_cmp_lt_u32 s1, 30
	s_waitcnt lgkmcnt(0)
	s_barrier
	s_cbranch_scc1 .Lg16_gu_k
	ds_read_b128 v[196:199], v246 offset:0
	ds_read_b128 v[200:203], v246 offset:1024
	ds_read_b128 v[204:207], v246 offset:2048
	ds_read_b128 v[242:245], v246 offset:3072
	s_waitcnt vmcnt(6) lgkmcnt(3)
	v_mfma_f32_16x16x32_bf16 v[112:115], v[128:131], v[196:199], v[112:115]
	v_mfma_f32_16x16x32_bf16 v[120:123], v[132:135], v[196:199], v[120:123]
	v_mfma_f32_16x16x32_bf16 v[80:83], v[136:139], v[196:199], v[80:83]
	v_mfma_f32_16x16x32_bf16 v[88:91], v[140:143], v[196:199], v[88:91]
	ds_read_b128 v[196:199], v246 offset:4096
	s_waitcnt lgkmcnt(3)
	v_mfma_f32_16x16x32_bf16 v[116:119], v[128:131], v[200:203], v[116:119]
	v_mfma_f32_16x16x32_bf16 v[124:127], v[132:135], v[200:203], v[124:127]
	v_mfma_f32_16x16x32_bf16 v[84:87], v[136:139], v[200:203], v[84:87]
	v_mfma_f32_16x16x32_bf16 v[92:95], v[140:143], v[200:203], v[92:95]
	ds_read_b128 v[200:203], v246 offset:5120
	s_waitcnt lgkmcnt(3)
	v_mfma_f32_16x16x32_bf16 v[96:99], v[128:131], v[204:207], v[96:99]
	v_mfma_f32_16x16x32_bf16 v[104:107], v[132:135], v[204:207], v[104:107]
	v_mfma_f32_16x16x32_bf16 v[64:67], v[136:139], v[204:207], v[64:67]
	v_mfma_f32_16x16x32_bf16 v[72:75], v[140:143], v[204:207], v[72:75]
	ds_read_b128 v[204:207], v246 offset:6144
	s_waitcnt lgkmcnt(3)
	v_mfma_f32_16x16x32_bf16 v[100:103], v[128:131], v[242:245], v[100:103]
	v_mfma_f32_16x16x32_bf16 v[108:111], v[132:135], v[242:245], v[108:111]
	v_mfma_f32_16x16x32_bf16 v[68:71], v[136:139], v[242:245], v[68:71]
	v_mfma_f32_16x16x32_bf16 v[76:79], v[140:143], v[242:245], v[76:79]
	ds_read_b128 v[242:245], v246 offset:7168
	s_waitcnt vmcnt(4)
	ds_write_b128 v241, v[168:171] offset:8192
	ds_write_b128 v241, v[172:175] offset:12288
	s_waitcnt lgkmcnt(5)
	v_mfma_f32_16x16x32_bf16 v[48:51], v[128:131], v[196:199], v[48:51]
	v_mfma_f32_16x16x32_bf16 v[56:59], v[132:135], v[196:199], v[56:59]
	v_mfma_f32_16x16x32_bf16 v[16:19], v[136:139], v[196:199], v[16:19]
	v_mfma_f32_16x16x32_bf16 v[24:27], v[140:143], v[196:199], v[24:27]
	s_waitcnt lgkmcnt(4)
	v_mfma_f32_16x16x32_bf16 v[52:55], v[128:131], v[200:203], v[52:55]
	v_mfma_f32_16x16x32_bf16 v[60:63], v[132:135], v[200:203], v[60:63]
	v_mfma_f32_16x16x32_bf16 v[20:23], v[136:139], v[200:203], v[20:23]
	v_mfma_f32_16x16x32_bf16 v[28:31], v[140:143], v[200:203], v[28:31]
	s_waitcnt lgkmcnt(3)
	v_mfma_f32_16x16x32_bf16 v[32:35], v[128:131], v[204:207], v[32:35]
	v_mfma_f32_16x16x32_bf16 v[40:43], v[132:135], v[204:207], v[40:43]
	v_mfma_f32_16x16x32_bf16 v[0:3], v[136:139], v[204:207], v[0:3]
	v_mfma_f32_16x16x32_bf16 v[8:11], v[140:143], v[204:207], v[8:11]
	s_waitcnt lgkmcnt(2)
	v_mfma_f32_16x16x32_bf16 v[36:39], v[128:131], v[242:245], v[36:39]
	v_mfma_f32_16x16x32_bf16 v[44:47], v[132:135], v[242:245], v[44:47]
	v_mfma_f32_16x16x32_bf16 v[4:7], v[136:139], v[242:245], v[4:7]
	v_mfma_f32_16x16x32_bf16 v[12:15], v[140:143], v[242:245], v[12:15]
	s_waitcnt lgkmcnt(0)
	s_barrier
	ds_read_b128 v[196:199], v246 offset:8192
	ds_read_b128 v[200:203], v246 offset:9216
	ds_read_b128 v[204:207], v246 offset:10240
	ds_read_b128 v[242:245], v246 offset:11264
	s_waitcnt vmcnt(0) lgkmcnt(3)
	v_mfma_f32_16x16x32_bf16 v[112:115], v[144:147], v[196:199], v[112:115]
	v_mfma_f32_16x16x32_bf16 v[120:123], v[148:151], v[196:199], v[120:123]
	v_mfma_f32_16x16x32_bf16 v[80:83], v[152:155], v[196:199], v[80:83]
	v_mfma_f32_16x16x32_bf16 v[88:91], v[156:159], v[196:199], v[88:91]
	ds_read_b128 v[196:199], v246 offset:12288
	s_waitcnt lgkmcnt(3)
	v_mfma_f32_16x16x32_bf16 v[116:119], v[144:147], v[200:203], v[116:119]
	v_mfma_f32_16x16x32_bf16 v[124:127], v[148:151], v[200:203], v[124:127]
	v_mfma_f32_16x16x32_bf16 v[84:87], v[152:155], v[200:203], v[84:87]
	v_mfma_f32_16x16x32_bf16 v[92:95], v[156:159], v[200:203], v[92:95]
	ds_read_b128 v[200:203], v246 offset:13312
	s_waitcnt lgkmcnt(3)
	v_mfma_f32_16x16x32_bf16 v[96:99], v[144:147], v[204:207], v[96:99]
	v_mfma_f32_16x16x32_bf16 v[104:107], v[148:151], v[204:207], v[104:107]
	v_mfma_f32_16x16x32_bf16 v[64:67], v[152:155], v[204:207], v[64:67]
	v_mfma_f32_16x16x32_bf16 v[72:75], v[156:159], v[204:207], v[72:75]
	ds_read_b128 v[204:207], v246 offset:14336
	s_waitcnt lgkmcnt(3)
	v_mfma_f32_16x16x32_bf16 v[100:103], v[144:147], v[242:245], v[100:103]
	v_mfma_f32_16x16x32_bf16 v[108:111], v[148:151], v[242:245], v[108:111]
	v_mfma_f32_16x16x32_bf16 v[68:71], v[152:155], v[242:245], v[68:71]
	v_mfma_f32_16x16x32_bf16 v[76:79], v[156:159], v[242:245], v[76:79]
	ds_read_b128 v[242:245], v246 offset:15360
	s_waitcnt lgkmcnt(3)
	v_mfma_f32_16x16x32_bf16 v[48:51], v[144:147], v[196:199], v[48:51]
	v_mfma_f32_16x16x32_bf16 v[56:59], v[148:151], v[196:199], v[56:59]
	v_mfma_f32_16x16x32_bf16 v[16:19], v[152:155], v[196:199], v[16:19]
	v_mfma_f32_16x16x32_bf16 v[24:27], v[156:159], v[196:199], v[24:27]
	s_waitcnt lgkmcnt(2)
	v_mfma_f32_16x16x32_bf16 v[52:55], v[144:147], v[200:203], v[52:55]
	v_mfma_f32_16x16x32_bf16 v[60:63], v[148:151], v[200:203], v[60:63]
	v_mfma_f32_16x16x32_bf16 v[20:23], v[152:155], v[200:203], v[20:23]
	v_mfma_f32_16x16x32_bf16 v[28:31], v[156:159], v[200:203], v[28:31]
	s_waitcnt lgkmcnt(1)
	v_mfma_f32_16x16x32_bf16 v[32:35], v[144:147], v[204:207], v[32:35]
	v_mfma_f32_16x16x32_bf16 v[40:43], v[148:151], v[204:207], v[40:43]
	v_mfma_f32_16x16x32_bf16 v[0:3], v[152:155], v[204:207], v[0:3]
	v_mfma_f32_16x16x32_bf16 v[8:11], v[156:159], v[204:207], v[8:11]
	s_waitcnt lgkmcnt(0)
	v_mfma_f32_16x16x32_bf16 v[36:39], v[144:147], v[242:245], v[36:39]
	v_mfma_f32_16x16x32_bf16 v[44:47], v[148:151], v[242:245], v[44:47]
	v_mfma_f32_16x16x32_bf16 v[4:7], v[152:155], v[242:245], v[4:7]
	v_mfma_f32_16x16x32_bf16 v[12:15], v[156:159], v[242:245], v[12:15]
	s_waitcnt lgkmcnt(0)
	s_barrier
	s_nop 7
	v_permlane16_swap_b32_e32 v112, v116
	v_permlane16_swap_b32_e32 v113, v117
	v_permlane16_swap_b32_e32 v114, v118
	v_permlane16_swap_b32_e32 v115, v119
	v_permlane16_swap_b32_e32 v120, v124
	v_permlane16_swap_b32_e32 v121, v125
	v_permlane16_swap_b32_e32 v122, v126
	v_permlane16_swap_b32_e32 v123, v127
	v_permlane16_swap_b32_e32 v96, v100
	v_permlane16_swap_b32_e32 v97, v101
	v_permlane16_swap_b32_e32 v98, v102
	v_permlane16_swap_b32_e32 v99, v103
	v_permlane16_swap_b32_e32 v104, v108
	v_permlane16_swap_b32_e32 v105, v109
	v_permlane16_swap_b32_e32 v106, v110
	v_permlane16_swap_b32_e32 v107, v111
	v_permlane16_swap_b32_e32 v48, v52
	v_permlane16_swap_b32_e32 v49, v53
	v_permlane16_swap_b32_e32 v50, v54
	v_permlane16_swap_b32_e32 v51, v55
	v_permlane16_swap_b32_e32 v56, v60
	v_permlane16_swap_b32_e32 v57, v61
	v_permlane16_swap_b32_e32 v58, v62
	v_permlane16_swap_b32_e32 v59, v63
	v_permlane16_swap_b32_e32 v32, v36
	v_permlane16_swap_b32_e32 v33, v37
	v_permlane16_swap_b32_e32 v34, v38
	v_permlane16_swap_b32_e32 v35, v39
	v_permlane16_swap_b32_e32 v40, v44
	v_permlane16_swap_b32_e32 v41, v45
	v_permlane16_swap_b32_e32 v42, v46
	v_permlane16_swap_b32_e32 v43, v47
	v_permlane16_swap_b32_e32 v80, v84
	v_permlane16_swap_b32_e32 v81, v85
	v_permlane16_swap_b32_e32 v82, v86
	v_permlane16_swap_b32_e32 v83, v87
	v_permlane16_swap_b32_e32 v88, v92
	v_permlane16_swap_b32_e32 v89, v93
	v_permlane16_swap_b32_e32 v90, v94
	v_permlane16_swap_b32_e32 v91, v95
	v_permlane16_swap_b32_e32 v64, v68
	v_permlane16_swap_b32_e32 v65, v69
	v_permlane16_swap_b32_e32 v66, v70
	v_permlane16_swap_b32_e32 v67, v71
	v_permlane16_swap_b32_e32 v72, v76
	v_permlane16_swap_b32_e32 v73, v77
	v_permlane16_swap_b32_e32 v74, v78
	v_permlane16_swap_b32_e32 v75, v79
	v_permlane16_swap_b32_e32 v16, v20
	v_permlane16_swap_b32_e32 v17, v21
	v_permlane16_swap_b32_e32 v18, v22
	v_permlane16_swap_b32_e32 v19, v23
	v_permlane16_swap_b32_e32 v24, v28
	v_permlane16_swap_b32_e32 v25, v29
	v_permlane16_swap_b32_e32 v26, v30
	v_permlane16_swap_b32_e32 v27, v31
	v_permlane16_swap_b32_e32 v0, v4
	v_permlane16_swap_b32_e32 v1, v5
	v_permlane16_swap_b32_e32 v2, v6
	v_permlane16_swap_b32_e32 v3, v7
	v_permlane16_swap_b32_e32 v8, v12
	v_permlane16_swap_b32_e32 v9, v13
	v_permlane16_swap_b32_e32 v10, v14
	v_permlane16_swap_b32_e32 v11, v15
	v_permlane32_swap_b32_e32 v112, v116
	v_permlane32_swap_b32_e32 v113, v117
	v_permlane32_swap_b32_e32 v114, v118
	v_permlane32_swap_b32_e32 v115, v119
	v_permlane32_swap_b32_e32 v120, v124
	v_permlane32_swap_b32_e32 v121, v125
	v_permlane32_swap_b32_e32 v122, v126
	v_permlane32_swap_b32_e32 v123, v127
	v_permlane32_swap_b32_e32 v96, v100
	v_permlane32_swap_b32_e32 v97, v101
	v_permlane32_swap_b32_e32 v98, v102
	v_permlane32_swap_b32_e32 v99, v103
	v_permlane32_swap_b32_e32 v104, v108
	v_permlane32_swap_b32_e32 v105, v109
	v_permlane32_swap_b32_e32 v106, v110
	v_permlane32_swap_b32_e32 v107, v111
	v_permlane32_swap_b32_e32 v48, v52
	v_permlane32_swap_b32_e32 v49, v53
	v_permlane32_swap_b32_e32 v50, v54
	v_permlane32_swap_b32_e32 v51, v55
	v_permlane32_swap_b32_e32 v56, v60
	v_permlane32_swap_b32_e32 v57, v61
	v_permlane32_swap_b32_e32 v58, v62
	v_permlane32_swap_b32_e32 v59, v63
	v_permlane32_swap_b32_e32 v32, v36
	v_permlane32_swap_b32_e32 v33, v37
	v_permlane32_swap_b32_e32 v34, v38
	v_permlane32_swap_b32_e32 v35, v39
	v_permlane32_swap_b32_e32 v40, v44
	v_permlane32_swap_b32_e32 v41, v45
	v_permlane32_swap_b32_e32 v42, v46
	v_permlane32_swap_b32_e32 v43, v47
	v_permlane32_swap_b32_e32 v80, v84
	v_permlane32_swap_b32_e32 v81, v85
	v_permlane32_swap_b32_e32 v82, v86
	v_permlane32_swap_b32_e32 v83, v87
	v_permlane32_swap_b32_e32 v88, v92
	v_permlane32_swap_b32_e32 v89, v93
	v_permlane32_swap_b32_e32 v90, v94
	v_permlane32_swap_b32_e32 v91, v95
	v_permlane32_swap_b32_e32 v64, v68
	v_permlane32_swap_b32_e32 v65, v69
	v_permlane32_swap_b32_e32 v66, v70
	v_permlane32_swap_b32_e32 v67, v71
	v_permlane32_swap_b32_e32 v72, v76
	v_permlane32_swap_b32_e32 v73, v77
	v_permlane32_swap_b32_e32 v74, v78
	v_permlane32_swap_b32_e32 v75, v79
	v_permlane32_swap_b32_e32 v16, v20
	v_permlane32_swap_b32_e32 v17, v21
	v_permlane32_swap_b32_e32 v18, v22
	v_permlane32_swap_b32_e32 v19, v23
	v_permlane32_swap_b32_e32 v24, v28
	v_permlane32_swap_b32_e32 v25, v29
	v_permlane32_swap_b32_e32 v26, v30
	v_permlane32_swap_b32_e32 v27, v31
	v_permlane32_swap_b32_e32 v0, v4
	v_permlane32_swap_b32_e32 v1, v5
	v_permlane32_swap_b32_e32 v2, v6
	v_permlane32_swap_b32_e32 v3, v7
	v_permlane32_swap_b32_e32 v8, v12
	v_permlane32_swap_b32_e32 v9, v13
	v_permlane32_swap_b32_e32 v10, v14
	v_permlane32_swap_b32_e32 v11, v15
	s_waitcnt vmcnt(0)
	s_waitcnt vmcnt(0)
	v_mul_f32_e32 v133, 0xbfb8aa3b, v112
	v_exp_f32_e32 v133, v133
	s_movk_i32 s1, 0x2400
	v_mul_lo_u32 v128, v238, s1
	v_lshl_or_b32 v131, s0, 6, v181
	v_add_f32_e32 v133, 1.0, v133
	v_lshl_or_b32 v132, v239, 1, v128
	v_and_b32_e32 v129, 0xffffffc0, v237
	v_lshl_or_b32 v128, v181, 1, v128
	v_rcp_f32_e32 v135, v133
	s_nop 0
	v_mul_f32_e32 v112, v112, v135
	v_mul_f32_e32 v96, v96, v112
	v_cvt_pk_bf16_f32 v112, v96, s0
	s_movk_i32 s0, 0x240
	v_mad_u32_u24 v96, v183, s0, v132
	ds_write_b16 v96, v112
	v_mul_f32_e32 v112, 0xbfb8aa3b, v113
	v_exp_f32_e32 v112, v112
	v_lshl_add_u32 v130, s7, 8, v129
	v_lshrrev_b32_e32 v129, 2, v240
	v_mad_u32_u24 v128, v129, s42, v128
	v_add_f32_e32 v112, 1.0, v112
	v_rcp_f32_e32 v133, v112
	s_nop 0
	v_mul_f32_e32 v112, v113, v133
	v_mul_f32_e32 v97, v97, v112
	v_cvt_pk_bf16_f32 v97, v97, s0
	ds_write_b16 v96, v97 offset:144
	v_mul_f32_e32 v97, 0xbfb8aa3b, v114
	v_exp_f32_e32 v97, v97
	s_nop 0
	v_add_f32_e32 v97, 1.0, v97
	v_rcp_f32_e32 v113, v97
	s_nop 0
	v_mul_f32_e32 v97, v114, v113
	v_mul_f32_e32 v97, v98, v97
	v_cvt_pk_bf16_f32 v97, v97, s0
	ds_write_b16 v96, v97 offset:288
	v_mul_f32_e32 v97, 0xbfb8aa3b, v115
	v_exp_f32_e32 v97, v97
	s_nop 0
	v_add_f32_e32 v97, 1.0, v97
	v_rcp_f32_e32 v112, v97
	s_nop 0
	v_mul_f32_e32 v97, v115, v112
	v_mul_f32_e32 v97, v99, v97
	v_cvt_pk_bf16_f32 v97, v97, s0
	ds_write_b16 v96, v97 offset:432
	v_mul_f32_e32 v97, 0xbfb8aa3b, v116
	v_exp_f32_e32 v97, v97
	s_nop 0
	v_add_f32_e32 v97, 1.0, v97
	v_rcp_f32_e32 v99, v97
	s_nop 0
	v_mul_f32_e32 v97, v116, v99
	v_mul_f32_e32 v97, v100, v97
	v_cvt_pk_bf16_f32 v97, v97, s0
	ds_write_b16 v96, v97 offset:1152
	v_mul_f32_e32 v97, 0xbfb8aa3b, v117
	v_exp_f32_e32 v97, v97
	s_nop 0
	v_add_f32_e32 v97, 1.0, v97
	v_rcp_f32_e32 v99, v97
	s_nop 0
	v_mul_f32_e32 v97, v117, v99
	v_mul_f32_e32 v97, v101, v97
	v_cvt_pk_bf16_f32 v97, v97, s0
	ds_write_b16 v96, v97 offset:1296
	v_mul_f32_e32 v97, 0xbfb8aa3b, v118
	v_exp_f32_e32 v97, v97
	s_nop 0
	v_add_f32_e32 v97, 1.0, v97
	v_rcp_f32_e32 v99, v97
	s_nop 0
	v_mul_f32_e32 v97, v118, v99
	v_mul_f32_e32 v97, v102, v97
	v_cvt_pk_bf16_f32 v97, v97, s0
	ds_write_b16 v96, v97 offset:1440
	v_mul_f32_e32 v97, 0xbfb8aa3b, v119
	v_exp_f32_e32 v97, v97
	s_nop 0
	v_add_f32_e32 v97, 1.0, v97
	v_rcp_f32_e32 v99, v97
	s_nop 0
	v_mul_f32_e32 v97, v119, v99
	v_mul_f32_e32 v97, v103, v97
	v_cvt_pk_bf16_f32 v97, v97, s0
	ds_write_b16 v96, v97 offset:1584
	v_mul_f32_e32 v97, 0xbfb8aa3b, v120
	v_exp_f32_e32 v97, v97
	s_nop 0
	v_add_f32_e32 v97, 1.0, v97
	v_rcp_f32_e32 v99, v97
	s_nop 0
	v_mul_f32_e32 v97, v120, v99
	v_mul_f32_e32 v97, v104, v97
	v_cvt_pk_bf16_f32 v97, v97, s0
	ds_write_b16 v96, v97 offset:2304
	v_mul_f32_e32 v97, 0xbfb8aa3b, v121
	v_exp_f32_e32 v97, v97
	s_nop 0
	v_add_f32_e32 v97, 1.0, v97
	v_rcp_f32_e32 v99, v97
	s_nop 0
	v_mul_f32_e32 v97, v121, v99
	v_mul_f32_e32 v97, v105, v97
	v_cvt_pk_bf16_f32 v97, v97, s0
	ds_write_b16 v96, v97 offset:2448
	v_mul_f32_e32 v97, 0xbfb8aa3b, v122
	v_exp_f32_e32 v97, v97
	s_nop 0
	v_add_f32_e32 v97, 1.0, v97
	v_rcp_f32_e32 v99, v97
	s_nop 0
	v_mul_f32_e32 v97, v122, v99
	v_mul_f32_e32 v97, v106, v97
	v_cvt_pk_bf16_f32 v97, v97, s0
	ds_write_b16 v96, v97 offset:2592
	v_mul_f32_e32 v97, 0xbfb8aa3b, v123
	v_exp_f32_e32 v97, v97
	s_nop 0
	v_add_f32_e32 v97, 1.0, v97
	v_rcp_f32_e32 v99, v97
	s_nop 0
	v_mul_f32_e32 v97, v123, v99
	v_mul_f32_e32 v97, v107, v97
	v_cvt_pk_bf16_f32 v97, v97, s0
	ds_write_b16 v96, v97 offset:2736
	v_mul_f32_e32 v97, 0xbfb8aa3b, v124
	v_exp_f32_e32 v97, v97
	s_nop 0
	v_add_f32_e32 v97, 1.0, v97
	v_rcp_f32_e32 v99, v97
	s_nop 0
	v_mul_f32_e32 v97, v124, v99
	v_mul_f32_e32 v97, v108, v97
	v_cvt_pk_bf16_f32 v97, v97, s0
	ds_write_b16 v96, v97 offset:3456
	v_mul_f32_e32 v97, 0xbfb8aa3b, v125
	v_exp_f32_e32 v97, v97
	s_nop 0
	v_add_f32_e32 v97, 1.0, v97
	v_rcp_f32_e32 v99, v97
	s_nop 0
	v_mul_f32_e32 v97, v125, v99
	v_mul_f32_e32 v97, v109, v97
	v_cvt_pk_bf16_f32 v97, v97, s0
	ds_write_b16 v96, v97 offset:3600
	v_mul_f32_e32 v97, 0xbfb8aa3b, v126
	v_exp_f32_e32 v97, v97
	s_nop 0
	v_add_f32_e32 v97, 1.0, v97
	v_rcp_f32_e32 v99, v97
	s_nop 0
	v_mul_f32_e32 v97, v126, v99
	v_mul_f32_e32 v97, v110, v97
	v_cvt_pk_bf16_f32 v97, v97, s0
	ds_write_b16 v96, v97 offset:3744
	v_mul_f32_e32 v97, 0xbfb8aa3b, v127
	v_exp_f32_e32 v97, v97
	s_nop 0
	v_add_f32_e32 v97, 1.0, v97
	v_rcp_f32_e32 v99, v97
	s_nop 0
	v_mul_f32_e32 v97, v127, v99
	v_mul_f32_e32 v97, v111, v97
	v_cvt_pk_bf16_f32 v97, v97, s0
	ds_write_b16 v96, v97 offset:3888
	v_mul_f32_e32 v97, 0xbfb8aa3b, v80
	v_exp_f32_e32 v97, v97
	s_nop 0
	v_add_f32_e32 v97, 1.0, v97
	v_rcp_f32_e32 v99, v97
	s_nop 0
	v_mul_f32_e32 v80, v80, v99
	v_mul_f32_e32 v64, v64, v80
	v_cvt_pk_bf16_f32 v64, v64, s0
	ds_write_b16 v96, v64 offset:4608
	v_mul_f32_e32 v64, 0xbfb8aa3b, v81
	v_exp_f32_e32 v64, v64
	s_nop 0
	v_add_f32_e32 v64, 1.0, v64
	v_rcp_f32_e32 v97, v64
	s_nop 0
	v_mul_f32_e32 v64, v81, v97
	v_mul_f32_e32 v64, v65, v64
	v_cvt_pk_bf16_f32 v64, v64, s0
	ds_write_b16 v96, v64 offset:4752
	v_mul_f32_e32 v64, 0xbfb8aa3b, v82
	v_exp_f32_e32 v64, v64
	s_nop 0
	v_add_f32_e32 v64, 1.0, v64
	v_rcp_f32_e32 v80, v64
	s_nop 0
	v_mul_f32_e32 v64, v82, v80
	v_mul_f32_e32 v64, v66, v64
	v_cvt_pk_bf16_f32 v64, v64, s0
	ds_write_b16 v96, v64 offset:4896
	v_mul_f32_e32 v64, 0xbfb8aa3b, v83
	v_exp_f32_e32 v64, v64
	s_nop 0
	v_add_f32_e32 v64, 1.0, v64
	v_rcp_f32_e32 v66, v64
	s_nop 0
	v_mul_f32_e32 v64, v83, v66
	v_mul_f32_e32 v64, v67, v64
	v_cvt_pk_bf16_f32 v64, v64, s0
	ds_write_b16 v96, v64 offset:5040
	v_mul_f32_e32 v64, 0xbfb8aa3b, v84
	v_exp_f32_e32 v64, v64
	s_nop 0
	v_add_f32_e32 v64, 1.0, v64
	v_rcp_f32_e32 v66, v64
	s_nop 0
	v_mul_f32_e32 v64, v84, v66
	v_mul_f32_e32 v64, v68, v64
	v_cvt_pk_bf16_f32 v64, v64, s0
	ds_write_b16 v96, v64 offset:5760
	v_mul_f32_e32 v64, 0xbfb8aa3b, v85
	v_exp_f32_e32 v64, v64
	s_nop 0
	v_add_f32_e32 v64, 1.0, v64
	v_rcp_f32_e32 v66, v64
	s_nop 0
	v_mul_f32_e32 v64, v85, v66
	v_mul_f32_e32 v64, v69, v64
	v_cvt_pk_bf16_f32 v64, v64, s0
	ds_write_b16 v96, v64 offset:5904
	v_mul_f32_e32 v64, 0xbfb8aa3b, v86
	v_exp_f32_e32 v64, v64
	s_nop 0
	v_add_f32_e32 v64, 1.0, v64
	v_rcp_f32_e32 v66, v64
	s_nop 0
	v_mul_f32_e32 v64, v86, v66
	v_mul_f32_e32 v64, v70, v64
	v_cvt_pk_bf16_f32 v64, v64, s0
	ds_write_b16 v96, v64 offset:6048
	v_mul_f32_e32 v64, 0xbfb8aa3b, v87
	v_exp_f32_e32 v64, v64
	s_nop 0
	v_add_f32_e32 v64, 1.0, v64
	v_rcp_f32_e32 v66, v64
	s_nop 0
	v_mul_f32_e32 v64, v87, v66
	v_mul_f32_e32 v64, v71, v64
	v_cvt_pk_bf16_f32 v64, v64, s0
	ds_write_b16 v96, v64 offset:6192
	v_mul_f32_e32 v64, 0xbfb8aa3b, v88
	v_exp_f32_e32 v64, v64
	v_ashrrev_i32_e32 v71, 5, v130
	v_or_b32_e32 v70, 1, v71
	v_add_f32_e32 v64, 1.0, v64
	v_rcp_f32_e32 v66, v64
	s_nop 0
	v_mul_f32_e32 v64, v88, v66
	v_mul_f32_e32 v64, v72, v64
	v_cvt_pk_bf16_f32 v64, v64, s0
	ds_write_b16 v96, v64 offset:6912
	v_mul_f32_e32 v64, 0xbfb8aa3b, v89
	v_exp_f32_e32 v64, v64
	s_nop 0
	v_add_f32_e32 v64, 1.0, v64
	v_rcp_f32_e32 v66, v64
	s_nop 0
	v_mul_f32_e32 v64, v89, v66
	v_mul_f32_e32 v64, v73, v64
	v_cvt_pk_bf16_f32 v64, v64, s0
	ds_write_b16 v96, v64 offset:7056
	v_mul_f32_e32 v64, 0xbfb8aa3b, v90
	v_exp_f32_e32 v64, v64
	s_nop 0
	v_add_f32_e32 v64, 1.0, v64
	v_rcp_f32_e32 v66, v64
	s_nop 0
	v_mul_f32_e32 v64, v90, v66
	v_mul_f32_e32 v64, v74, v64
	v_cvt_pk_bf16_f32 v64, v64, s0
	ds_write_b16 v96, v64 offset:7200
	v_mul_f32_e32 v64, 0xbfb8aa3b, v91
	v_exp_f32_e32 v64, v64
	s_nop 0
	v_add_f32_e32 v64, 1.0, v64
	v_rcp_f32_e32 v66, v64
	s_nop 0
	v_mul_f32_e32 v64, v91, v66
	v_mul_f32_e32 v64, v75, v64
	v_cvt_pk_bf16_f32 v64, v64, s0
	ds_write_b16 v96, v64 offset:7344
	v_mul_f32_e32 v64, 0xbfb8aa3b, v92
	v_exp_f32_e32 v64, v64
	s_nop 0
	v_add_f32_e32 v64, 1.0, v64
	v_rcp_f32_e32 v66, v64
	s_nop 0
	v_mul_f32_e32 v64, v92, v66
	v_mul_f32_e32 v64, v76, v64
	v_cvt_pk_bf16_f32 v64, v64, s0
	ds_write_b16 v96, v64 offset:8064
	v_mul_f32_e32 v64, 0xbfb8aa3b, v93
	v_exp_f32_e32 v64, v64
	s_nop 0
	v_add_f32_e32 v64, 1.0, v64
	v_rcp_f32_e32 v66, v64
	s_nop 0
	v_mul_f32_e32 v64, v93, v66
	v_mul_f32_e32 v64, v77, v64
	v_cvt_pk_bf16_f32 v64, v64, s0
	ds_write_b16 v96, v64 offset:8208
	v_mul_f32_e32 v64, 0xbfb8aa3b, v94
	v_exp_f32_e32 v64, v64
	s_nop 0
	v_add_f32_e32 v64, 1.0, v64
	v_rcp_f32_e32 v66, v64
	s_nop 0
	v_mul_f32_e32 v64, v94, v66
	v_mul_f32_e32 v64, v78, v64
	v_cvt_pk_bf16_f32 v64, v64, s0
	ds_write_b16 v96, v64 offset:8352
	v_mul_f32_e32 v64, 0xbfb8aa3b, v95
	v_exp_f32_e32 v64, v64
	s_nop 0
	v_add_f32_e32 v64, 1.0, v64
	v_rcp_f32_e32 v66, v64
	s_nop 0
	v_mul_f32_e32 v64, v95, v66
	v_mul_f32_e32 v64, v79, v64
	v_cvt_pk_bf16_f32 v64, v64, s0
	ds_write_b16 v96, v64 offset:8496
	v_ashrrev_i32_e32 v68, 4, v131
	s_waitcnt lgkmcnt(0)
	v_ashrrev_i32_e32 v69, 31, v68
	ds_read_b128 v[72:75], v128
	v_mad_i64_i32 v[64:65], s[0:1], v71, s23, v[68:69]
	v_lshlrev_b64 v[64:65], 10, v[64:65]
	v_lshlrev_b32_e32 v66, 6, v181
	v_lshl_add_u64 v[64:65], s[66:67], 0, v[64:65]
	v_and_b32_e32 v176, 0x200, v66
	v_lshl_add_u64 v[76:77], v[64:65], 0, v[176:177]
	v_lshlrev_b32_e32 v66, 4, v129
	v_mov_b32_e32 v67, v177
	v_lshl_add_u64 v[64:65], v[76:77], 0, v[66:67]
	s_waitcnt lgkmcnt(0)
	global_store_dwordx4 v[64:65], v[72:75], off
	ds_read_b128 v[72:75], v128 offset:2304
	v_or_b32_e32 v64, 0x100, v66
	v_mov_b32_e32 v65, v177
	v_lshl_add_u64 v[76:77], v[76:77], 0, v[64:65]
	s_waitcnt lgkmcnt(0)
	global_store_dwordx4 v[76:77], v[72:75], off
	ds_read_b128 v[72:75], v128 offset:4608
	v_mad_i64_i32 v[76:77], s[0:1], v70, s23, v[68:69]
	v_lshlrev_b64 v[76:77], 10, v[76:77]
	v_lshl_add_u64 v[76:77], s[66:67], 0, v[76:77]
	v_lshl_add_u64 v[76:77], v[76:77], 0, v[176:177]
	v_lshl_add_u64 v[78:79], v[76:77], 0, v[66:67]
	v_mul_f32_e32 v69, 0xbfb8aa3b, v48
	s_waitcnt lgkmcnt(0)
	global_store_dwordx4 v[78:79], v[72:75], off
	ds_read_b128 v[72:75], v128 offset:6912
	v_exp_f32_e32 v69, v69
	v_lshl_add_u64 v[76:77], v[76:77], 0, v[64:65]
	v_add_f32_e32 v69, 1.0, v69
	s_waitcnt lgkmcnt(0)
	global_store_dwordx4 v[76:77], v[72:75], off
	s_waitcnt lgkmcnt(0)
	s_nop 1
	v_rcp_f32_e32 v73, v69
	s_nop 0
	v_mul_f32_e32 v48, v48, v73
	v_mul_f32_e32 v32, v32, v48
	v_cvt_pk_bf16_f32 v32, v32, s0
	ds_write_b16 v96, v32
	v_mul_f32_e32 v32, 0xbfb8aa3b, v49
	v_exp_f32_e32 v32, v32
	s_nop 0
	v_add_f32_e32 v32, 1.0, v32
	v_rcp_f32_e32 v69, v32
	s_nop 0
	v_mul_f32_e32 v32, v49, v69
	v_mul_f32_e32 v32, v33, v32
	v_cvt_pk_bf16_f32 v32, v32, s0
	ds_write_b16 v96, v32 offset:144
	v_mul_f32_e32 v32, 0xbfb8aa3b, v50
	v_exp_f32_e32 v32, v32
	s_nop 0
	v_add_f32_e32 v32, 1.0, v32
	v_rcp_f32_e32 v48, v32
	s_nop 0
	v_mul_f32_e32 v32, v50, v48
	v_mul_f32_e32 v32, v34, v32
	v_cvt_pk_bf16_f32 v32, v32, s0
	ds_write_b16 v96, v32 offset:288
	v_mul_f32_e32 v32, 0xbfb8aa3b, v51
	v_exp_f32_e32 v32, v32
	s_nop 0
	v_add_f32_e32 v32, 1.0, v32
	v_rcp_f32_e32 v34, v32
	s_nop 0
	v_mul_f32_e32 v32, v51, v34
	v_mul_f32_e32 v32, v35, v32
	v_cvt_pk_bf16_f32 v32, v32, s0
	ds_write_b16 v96, v32 offset:432
	v_mul_f32_e32 v32, 0xbfb8aa3b, v52
	v_exp_f32_e32 v32, v32
	s_nop 0
	v_add_f32_e32 v32, 1.0, v32
	v_rcp_f32_e32 v34, v32
	s_nop 0
	v_mul_f32_e32 v32, v52, v34
	v_mul_f32_e32 v32, v36, v32
	v_cvt_pk_bf16_f32 v32, v32, s0
	ds_write_b16 v96, v32 offset:1152
	v_mul_f32_e32 v32, 0xbfb8aa3b, v53
	v_exp_f32_e32 v32, v32
	s_nop 0
	v_add_f32_e32 v32, 1.0, v32
	v_rcp_f32_e32 v34, v32
	s_nop 0
	v_mul_f32_e32 v32, v53, v34
	v_mul_f32_e32 v32, v37, v32
	v_cvt_pk_bf16_f32 v32, v32, s0
	ds_write_b16 v96, v32 offset:1296
	v_mul_f32_e32 v32, 0xbfb8aa3b, v54
	v_exp_f32_e32 v32, v32
	s_nop 0
	v_add_f32_e32 v32, 1.0, v32
	v_rcp_f32_e32 v34, v32
	s_nop 0
	v_mul_f32_e32 v32, v54, v34
	v_mul_f32_e32 v32, v38, v32
	v_cvt_pk_bf16_f32 v32, v32, s0
	ds_write_b16 v96, v32 offset:1440
	v_mul_f32_e32 v32, 0xbfb8aa3b, v55
	v_exp_f32_e32 v32, v32
	s_nop 0
	v_add_f32_e32 v32, 1.0, v32
	v_rcp_f32_e32 v34, v32
	s_nop 0
	v_mul_f32_e32 v32, v55, v34
	v_mul_f32_e32 v32, v39, v32
	v_cvt_pk_bf16_f32 v32, v32, s0
	ds_write_b16 v96, v32 offset:1584
	v_mul_f32_e32 v32, 0xbfb8aa3b, v56
	v_exp_f32_e32 v32, v32
	s_nop 0
	v_add_f32_e32 v32, 1.0, v32
	v_rcp_f32_e32 v34, v32
	s_nop 0
	v_mul_f32_e32 v32, v56, v34
	v_mul_f32_e32 v32, v40, v32
	v_cvt_pk_bf16_f32 v32, v32, s0
	ds_write_b16 v96, v32 offset:2304
	v_mul_f32_e32 v32, 0xbfb8aa3b, v57
	v_exp_f32_e32 v32, v32
	s_nop 0
	v_add_f32_e32 v32, 1.0, v32
	v_rcp_f32_e32 v34, v32
	s_nop 0
	v_mul_f32_e32 v32, v57, v34
	v_mul_f32_e32 v32, v41, v32
	v_cvt_pk_bf16_f32 v32, v32, s0
	ds_write_b16 v96, v32 offset:2448
	v_mul_f32_e32 v32, 0xbfb8aa3b, v58
	v_exp_f32_e32 v32, v32
	s_nop 0
	v_add_f32_e32 v32, 1.0, v32
	v_rcp_f32_e32 v34, v32
	s_nop 0
	v_mul_f32_e32 v32, v58, v34
	v_mul_f32_e32 v32, v42, v32
	v_cvt_pk_bf16_f32 v32, v32, s0
	ds_write_b16 v96, v32 offset:2592
	v_mul_f32_e32 v32, 0xbfb8aa3b, v59
	v_exp_f32_e32 v32, v32
	s_nop 0
	v_add_f32_e32 v32, 1.0, v32
	v_rcp_f32_e32 v34, v32
	s_nop 0
	v_mul_f32_e32 v32, v59, v34
	v_mul_f32_e32 v32, v43, v32
	v_cvt_pk_bf16_f32 v32, v32, s0
	ds_write_b16 v96, v32 offset:2736
	v_mul_f32_e32 v32, 0xbfb8aa3b, v60
	v_exp_f32_e32 v32, v32
	s_nop 0
	v_add_f32_e32 v32, 1.0, v32
	v_rcp_f32_e32 v34, v32
	s_nop 0
	v_mul_f32_e32 v32, v60, v34
	v_mul_f32_e32 v32, v44, v32
	v_cvt_pk_bf16_f32 v32, v32, s0
	ds_write_b16 v96, v32 offset:3456
	v_mul_f32_e32 v32, 0xbfb8aa3b, v61
	v_exp_f32_e32 v32, v32
	s_nop 0
	v_add_f32_e32 v32, 1.0, v32
	v_rcp_f32_e32 v34, v32
	s_nop 0
	v_mul_f32_e32 v32, v61, v34
	v_mul_f32_e32 v32, v45, v32
	v_cvt_pk_bf16_f32 v32, v32, s0
	ds_write_b16 v96, v32 offset:3600
	v_mul_f32_e32 v32, 0xbfb8aa3b, v62
	v_exp_f32_e32 v32, v32
	s_nop 0
	v_add_f32_e32 v32, 1.0, v32
	v_rcp_f32_e32 v34, v32
	s_nop 0
	v_mul_f32_e32 v32, v62, v34
	v_mul_f32_e32 v32, v46, v32
	v_cvt_pk_bf16_f32 v32, v32, s0
	ds_write_b16 v96, v32 offset:3744
	v_mul_f32_e32 v32, 0xbfb8aa3b, v63
	v_exp_f32_e32 v32, v32
	s_nop 0
	v_add_f32_e32 v32, 1.0, v32
	v_rcp_f32_e32 v34, v32
	s_nop 0
	v_mul_f32_e32 v32, v63, v34
	v_mul_f32_e32 v32, v47, v32
	v_cvt_pk_bf16_f32 v32, v32, s0
	ds_write_b16 v96, v32 offset:3888
	v_mul_f32_e32 v32, 0xbfb8aa3b, v16
	v_exp_f32_e32 v32, v32
	s_nop 0
	v_add_f32_e32 v32, 1.0, v32
	v_rcp_f32_e32 v34, v32
	s_nop 0
	v_mul_f32_e32 v16, v16, v34
	v_mul_f32_e32 v0, v0, v16
	v_cvt_pk_bf16_f32 v0, v0, s0
	ds_write_b16 v96, v0 offset:4608
	v_mul_f32_e32 v0, 0xbfb8aa3b, v17
	v_exp_f32_e32 v0, v0
	s_nop 0
	v_add_f32_e32 v0, 1.0, v0
	v_rcp_f32_e32 v32, v0
	s_nop 0
	v_mul_f32_e32 v0, v17, v32
	v_mul_f32_e32 v0, v1, v0
	v_cvt_pk_bf16_f32 v0, v0, s0
	ds_write_b16 v96, v0 offset:4752
	v_mul_f32_e32 v0, 0xbfb8aa3b, v18
	v_exp_f32_e32 v0, v0
	s_nop 0
	v_add_f32_e32 v0, 1.0, v0
	v_rcp_f32_e32 v16, v0
	s_nop 0
	v_mul_f32_e32 v0, v18, v16
	v_mul_f32_e32 v0, v2, v0
	v_cvt_pk_bf16_f32 v0, v0, s0
	ds_write_b16 v96, v0 offset:4896
	v_mul_f32_e32 v0, 0xbfb8aa3b, v19
	v_exp_f32_e32 v0, v0
	s_nop 0
	v_add_f32_e32 v0, 1.0, v0
	v_rcp_f32_e32 v2, v0
	s_nop 0
	v_mul_f32_e32 v0, v19, v2
	v_mul_f32_e32 v0, v3, v0
	v_cvt_pk_bf16_f32 v0, v0, s0
	ds_write_b16 v96, v0 offset:5040
	v_mul_f32_e32 v0, 0xbfb8aa3b, v20
	v_exp_f32_e32 v0, v0
	s_nop 0
	v_add_f32_e32 v0, 1.0, v0
	v_rcp_f32_e32 v2, v0
	s_nop 0
	v_mul_f32_e32 v0, v20, v2
	v_mul_f32_e32 v0, v4, v0
	v_cvt_pk_bf16_f32 v0, v0, s0
	ds_write_b16 v96, v0 offset:5760
	v_mul_f32_e32 v0, 0xbfb8aa3b, v21
	v_exp_f32_e32 v0, v0
	s_nop 0
	v_add_f32_e32 v0, 1.0, v0
	v_rcp_f32_e32 v2, v0
	s_nop 0
	v_mul_f32_e32 v0, v21, v2
	v_mul_f32_e32 v0, v5, v0
	v_cvt_pk_bf16_f32 v0, v0, s0
	ds_write_b16 v96, v0 offset:5904
	v_mul_f32_e32 v0, 0xbfb8aa3b, v22
	v_exp_f32_e32 v0, v0
	s_nop 0
	v_add_f32_e32 v0, 1.0, v0
	v_rcp_f32_e32 v2, v0
	s_nop 0
	v_mul_f32_e32 v0, v22, v2
	v_mul_f32_e32 v0, v6, v0
	v_cvt_pk_bf16_f32 v0, v0, s0
	ds_write_b16 v96, v0 offset:6048
	v_mul_f32_e32 v0, 0xbfb8aa3b, v23
	v_exp_f32_e32 v0, v0
	s_nop 0
	v_add_f32_e32 v0, 1.0, v0
	v_rcp_f32_e32 v2, v0
	s_nop 0
	v_mul_f32_e32 v0, v23, v2
	v_mul_f32_e32 v0, v7, v0
	v_cvt_pk_bf16_f32 v0, v0, s0
	ds_write_b16 v96, v0 offset:6192
	v_mul_f32_e32 v0, 0xbfb8aa3b, v24
	v_exp_f32_e32 v0, v0
	s_nop 0
	v_add_f32_e32 v0, 1.0, v0
	v_rcp_f32_e32 v2, v0
	s_nop 0
	v_mul_f32_e32 v0, v24, v2
	v_mul_f32_e32 v0, v8, v0
	v_cvt_pk_bf16_f32 v0, v0, s0
	ds_write_b16 v96, v0 offset:6912
	v_mul_f32_e32 v0, 0xbfb8aa3b, v25
	v_exp_f32_e32 v0, v0
	s_nop 0
	v_add_f32_e32 v0, 1.0, v0
	v_rcp_f32_e32 v2, v0
	s_nop 0
	v_mul_f32_e32 v0, v25, v2
	v_mul_f32_e32 v0, v9, v0
	v_cvt_pk_bf16_f32 v0, v0, s0
	ds_write_b16 v96, v0 offset:7056
	v_mul_f32_e32 v0, 0xbfb8aa3b, v26
	v_exp_f32_e32 v0, v0
	s_nop 0
	v_add_f32_e32 v0, 1.0, v0
	v_rcp_f32_e32 v2, v0
	s_nop 0
	v_mul_f32_e32 v0, v26, v2
	v_mul_f32_e32 v0, v10, v0
	v_cvt_pk_bf16_f32 v0, v0, s0
	ds_write_b16 v96, v0 offset:7200
	v_mul_f32_e32 v0, 0xbfb8aa3b, v27
	v_exp_f32_e32 v0, v0
	s_nop 0
	v_add_f32_e32 v0, 1.0, v0
	v_rcp_f32_e32 v2, v0
	s_nop 0
	v_mul_f32_e32 v0, v27, v2
	v_mul_f32_e32 v0, v11, v0
	v_cvt_pk_bf16_f32 v0, v0, s0
	ds_write_b16 v96, v0 offset:7344
	v_mul_f32_e32 v0, 0xbfb8aa3b, v28
	v_exp_f32_e32 v0, v0
	s_nop 0
	v_add_f32_e32 v0, 1.0, v0
	v_rcp_f32_e32 v2, v0
	s_nop 0
	v_mul_f32_e32 v0, v28, v2
	v_mul_f32_e32 v0, v12, v0
	v_cvt_pk_bf16_f32 v0, v0, s0
	ds_write_b16 v96, v0 offset:8064
	v_mul_f32_e32 v0, 0xbfb8aa3b, v29
	v_exp_f32_e32 v0, v0
	s_nop 0
	v_add_f32_e32 v0, 1.0, v0
	v_rcp_f32_e32 v2, v0
	s_nop 0
	v_mul_f32_e32 v0, v29, v2
	v_mul_f32_e32 v0, v13, v0
	v_cvt_pk_bf16_f32 v0, v0, s0
	ds_write_b16 v96, v0 offset:8208
	v_mul_f32_e32 v0, 0xbfb8aa3b, v30
	v_exp_f32_e32 v0, v0
	s_nop 0
	v_add_f32_e32 v0, 1.0, v0
	v_rcp_f32_e32 v2, v0
	s_nop 0
	v_mul_f32_e32 v0, v30, v2
	v_mul_f32_e32 v0, v14, v0
	v_cvt_pk_bf16_f32 v0, v0, s0
	ds_write_b16 v96, v0 offset:8352
	v_mul_f32_e32 v0, 0xbfb8aa3b, v31
	v_exp_f32_e32 v0, v0
	s_nop 0
	v_add_f32_e32 v0, 1.0, v0
	v_rcp_f32_e32 v2, v0
	s_nop 0
	v_mul_f32_e32 v0, v31, v2
	v_mul_f32_e32 v0, v15, v0
	v_cvt_pk_bf16_f32 v0, v0, s0
	ds_write_b16 v96, v0 offset:8496
	v_or_b32_e32 v4, 2, v68
	s_waitcnt lgkmcnt(0)
	v_ashrrev_i32_e32 v5, 31, v4
	ds_read_b128 v[0:3], v128
	v_mad_i64_i32 v[6:7], s[0:1], v71, s23, v[4:5]
	v_lshlrev_b64 v[6:7], 10, v[6:7]
	v_lshl_add_u64 v[6:7], s[66:67], 0, v[6:7]
	v_lshl_add_u64 v[6:7], v[6:7], 0, v[176:177]
	v_lshl_add_u64 v[8:9], v[6:7], 0, v[66:67]
	s_waitcnt lgkmcnt(0)
	global_store_dwordx4 v[8:9], v[0:3], off
	ds_read_b128 v[0:3], v128 offset:2304
	v_lshl_add_u64 v[6:7], v[6:7], 0, v[64:65]
	v_mad_i64_i32 v[4:5], s[0:1], v70, s23, v[4:5]
	v_lshlrev_b64 v[4:5], 10, v[4:5]
	s_waitcnt lgkmcnt(0)
	global_store_dwordx4 v[6:7], v[0:3], off
	ds_read_b128 v[0:3], v128 offset:4608
	v_lshl_add_u64 v[4:5], s[66:67], 0, v[4:5]
	v_lshl_add_u64 v[4:5], v[4:5], 0, v[176:177]
	v_lshl_add_u64 v[6:7], v[4:5], 0, v[66:67]
	v_lshl_add_u64 v[4:5], v[4:5], 0, v[64:65]
	s_waitcnt lgkmcnt(0)
	global_store_dwordx4 v[6:7], v[0:3], off
	ds_read_b128 v[0:3], v128 offset:6912
	v_readlane_b32 s0, v254, 11
	s_add_i32 s2, s2, s0
	s_cmp_lt_i32 s2, s3
	s_waitcnt lgkmcnt(0)
	global_store_dwordx4 v[4:5], v[0:3], off
	s_waitcnt lgkmcnt(0)
	s_barrier
	s_cbranch_scc1 .LBB0_1031

.Lg16_down_k:
	s_add_i32 s9, s8, 2
	s_min_u32 s10, s9, 86
	s_lshl_b32 s96, s10, 13
	v_lshl_add_u64 v[166:167], v[188:189], 0, s[96:97]
	global_load_dwordx4 v[160:163], v[166:167], off offset:-2048
	global_load_dwordx4 v[164:167], v[166:167], off offset:2048
	ds_read_b128 v[196:199], v246 offset:0
	ds_read_b128 v[200:203], v246 offset:1024
	ds_read_b128 v[204:207], v246 offset:2048
	ds_read_b128 v[242:245], v246 offset:3072
	s_lshl_b32 s96, s10, 11
	v_lshl_add_u64 v[248:249], v[184:185], 0, s[96:97]
	v_lshl_add_u64 v[250:251], v[186:187], 0, s[96:97]
	s_waitcnt vmcnt(8) lgkmcnt(3)
	v_mfma_f32_16x16x32_bf16 v[112:115], v[128:131], v[196:199], v[112:115]
	v_mfma_f32_16x16x32_bf16 v[120:123], v[132:135], v[196:199], v[120:123]
	v_mfma_f32_16x16x32_bf16 v[48:51], v[136:139], v[196:199], v[48:51]
	v_mfma_f32_16x16x32_bf16 v[56:59], v[140:143], v[196:199], v[56:59]
	ds_read_b128 v[196:199], v246 offset:4096
	s_waitcnt lgkmcnt(3)
	v_mfma_f32_16x16x32_bf16 v[116:119], v[128:131], v[200:203], v[116:119]
	v_mfma_f32_16x16x32_bf16 v[124:127], v[132:135], v[200:203], v[124:127]
	v_mfma_f32_16x16x32_bf16 v[52:55], v[136:139], v[200:203], v[52:55]
	v_mfma_f32_16x16x32_bf16 v[60:63], v[140:143], v[200:203], v[60:63]
	ds_read_b128 v[200:203], v246 offset:5120
	s_waitcnt lgkmcnt(3)
	v_mfma_f32_16x16x32_bf16 v[96:99], v[128:131], v[204:207], v[96:99]
	v_mfma_f32_16x16x32_bf16 v[104:107], v[132:135], v[204:207], v[104:107]
	v_mfma_f32_16x16x32_bf16 v[32:35], v[136:139], v[204:207], v[32:35]
	v_mfma_f32_16x16x32_bf16 v[40:43], v[140:143], v[204:207], v[40:43]
	ds_read_b128 v[204:207], v246 offset:6144
	s_waitcnt lgkmcnt(3)
	v_mfma_f32_16x16x32_bf16 v[100:103], v[128:131], v[242:245], v[100:103]
	v_mfma_f32_16x16x32_bf16 v[108:111], v[132:135], v[242:245], v[108:111]
	v_mfma_f32_16x16x32_bf16 v[36:39], v[136:139], v[242:245], v[36:39]
	v_mfma_f32_16x16x32_bf16 v[44:47], v[140:143], v[242:245], v[44:47]
	ds_read_b128 v[242:245], v246 offset:7168
	s_waitcnt vmcnt(6)
	ds_write_b128 v241, v[168:171] offset:8192
	ds_write_b128 v241, v[172:175] offset:12288
	s_waitcnt lgkmcnt(5)
	v_mfma_f32_16x16x32_bf16 v[80:83], v[128:131], v[196:199], v[80:83]
	v_mfma_f32_16x16x32_bf16 v[88:91], v[132:135], v[196:199], v[88:91]
	v_mfma_f32_16x16x32_bf16 v[16:19], v[136:139], v[196:199], v[16:19]
	v_mfma_f32_16x16x32_bf16 v[24:27], v[140:143], v[196:199], v[24:27]
	s_waitcnt lgkmcnt(4)
	v_mfma_f32_16x16x32_bf16 v[84:87], v[128:131], v[200:203], v[84:87]
	v_mfma_f32_16x16x32_bf16 v[92:95], v[132:135], v[200:203], v[92:95]
	v_mfma_f32_16x16x32_bf16 v[20:23], v[136:139], v[200:203], v[20:23]
	v_mfma_f32_16x16x32_bf16 v[28:31], v[140:143], v[200:203], v[28:31]
	s_waitcnt lgkmcnt(3)
	v_mfma_f32_16x16x32_bf16 v[64:67], v[128:131], v[204:207], v[64:67]
	v_mfma_f32_16x16x32_bf16 v[72:75], v[132:135], v[204:207], v[72:75]
	v_mfma_f32_16x16x32_bf16 v[0:3], v[136:139], v[204:207], v[0:3]
	v_mfma_f32_16x16x32_bf16 v[8:11], v[140:143], v[204:207], v[8:11]
	s_waitcnt lgkmcnt(2)
	v_mfma_f32_16x16x32_bf16 v[68:71], v[128:131], v[242:245], v[68:71]
	v_mfma_f32_16x16x32_bf16 v[76:79], v[132:135], v[242:245], v[76:79]
	v_mfma_f32_16x16x32_bf16 v[4:7], v[136:139], v[242:245], v[4:7]
	v_mfma_f32_16x16x32_bf16 v[12:15], v[140:143], v[242:245], v[12:15]
	global_load_dwordx4 v[128:131], v[248:249], off
	global_load_dwordx4 v[132:135], v[248:249], off offset:256
	global_load_dwordx4 v[136:139], v[250:251], off
	global_load_dwordx4 v[140:143], v[250:251], off offset:256
	s_waitcnt lgkmcnt(0)
	s_barrier
	s_add_i32 s9, s8, 3
	s_min_u32 s10, s9, 87
	s_lshl_b32 s96, s10, 13
	v_lshl_add_u64 v[174:175], v[188:189], 0, s[96:97]
	global_load_dwordx4 v[168:171], v[174:175], off offset:-2048
	global_load_dwordx4 v[172:175], v[174:175], off offset:2048
	ds_read_b128 v[196:199], v246 offset:8192
	ds_read_b128 v[200:203], v246 offset:9216
	ds_read_b128 v[204:207], v246 offset:10240
	ds_read_b128 v[242:245], v246 offset:11264
	s_lshl_b32 s96, s10, 11
	v_lshl_add_u64 v[248:249], v[184:185], 0, s[96:97]
	v_lshl_add_u64 v[250:251], v[186:187], 0, s[96:97]
	s_waitcnt vmcnt(8) lgkmcnt(3)
	v_mfma_f32_16x16x32_bf16 v[112:115], v[144:147], v[196:199], v[112:115]
	v_mfma_f32_16x16x32_bf16 v[120:123], v[148:151], v[196:199], v[120:123]
	v_mfma_f32_16x16x32_bf16 v[48:51], v[152:155], v[196:199], v[48:51]
	v_mfma_f32_16x16x32_bf16 v[56:59], v[156:159], v[196:199], v[56:59]
	ds_read_b128 v[196:199], v246 offset:12288
	s_waitcnt lgkmcnt(3)
	v_mfma_f32_16x16x32_bf16 v[116:119], v[144:147], v[200:203], v[116:119]
	v_mfma_f32_16x16x32_bf16 v[124:127], v[148:151], v[200:203], v[124:127]
	v_mfma_f32_16x16x32_bf16 v[52:55], v[152:155], v[200:203], v[52:55]
	v_mfma_f32_16x16x32_bf16 v[60:63], v[156:159], v[200:203], v[60:63]
	ds_read_b128 v[200:203], v246 offset:13312
	s_waitcnt lgkmcnt(3)
	v_mfma_f32_16x16x32_bf16 v[96:99], v[144:147], v[204:207], v[96:99]
	v_mfma_f32_16x16x32_bf16 v[104:107], v[148:151], v[204:207], v[104:107]
	v_mfma_f32_16x16x32_bf16 v[32:35], v[152:155], v[204:207], v[32:35]
	v_mfma_f32_16x16x32_bf16 v[40:43], v[156:159], v[204:207], v[40:43]
	ds_read_b128 v[204:207], v246 offset:14336
	s_waitcnt lgkmcnt(3)
	v_mfma_f32_16x16x32_bf16 v[100:103], v[144:147], v[242:245], v[100:103]
	v_mfma_f32_16x16x32_bf16 v[108:111], v[148:151], v[242:245], v[108:111]
	v_mfma_f32_16x16x32_bf16 v[36:39], v[152:155], v[242:245], v[36:39]
	v_mfma_f32_16x16x32_bf16 v[44:47], v[156:159], v[242:245], v[44:47]
	ds_read_b128 v[242:245], v246 offset:15360
	s_waitcnt vmcnt(6)
	ds_write_b128 v241, v[160:163] offset:0
	ds_write_b128 v241, v[164:167] offset:4096
	s_waitcnt lgkmcnt(5)
	v_mfma_f32_16x16x32_bf16 v[80:83], v[144:147], v[196:199], v[80:83]
	v_mfma_f32_16x16x32_bf16 v[88:91], v[148:151], v[196:199], v[88:91]
	v_mfma_f32_16x16x32_bf16 v[16:19], v[152:155], v[196:199], v[16:19]
	v_mfma_f32_16x16x32_bf16 v[24:27], v[156:159], v[196:199], v[24:27]
	s_waitcnt lgkmcnt(4)
	v_mfma_f32_16x16x32_bf16 v[84:87], v[144:147], v[200:203], v[84:87]
	v_mfma_f32_16x16x32_bf16 v[92:95], v[148:151], v[200:203], v[92:95]
	v_mfma_f32_16x16x32_bf16 v[20:23], v[152:155], v[200:203], v[20:23]
	v_mfma_f32_16x16x32_bf16 v[28:31], v[156:159], v[200:203], v[28:31]
	s_waitcnt lgkmcnt(3)
	v_mfma_f32_16x16x32_bf16 v[64:67], v[144:147], v[204:207], v[64:67]
	v_mfma_f32_16x16x32_bf16 v[72:75], v[148:151], v[204:207], v[72:75]
	v_mfma_f32_16x16x32_bf16 v[0:3], v[152:155], v[204:207], v[0:3]
	v_mfma_f32_16x16x32_bf16 v[8:11], v[156:159], v[204:207], v[8:11]
	s_waitcnt lgkmcnt(2)
	v_mfma_f32_16x16x32_bf16 v[68:71], v[144:147], v[242:245], v[68:71]
	v_mfma_f32_16x16x32_bf16 v[76:79], v[148:151], v[242:245], v[76:79]
	v_mfma_f32_16x16x32_bf16 v[4:7], v[152:155], v[242:245], v[4:7]
	v_mfma_f32_16x16x32_bf16 v[12:15], v[156:159], v[242:245], v[12:15]
	global_load_dwordx4 v[144:147], v[248:249], off
	global_load_dwordx4 v[148:151], v[248:249], off offset:256
	global_load_dwordx4 v[152:155], v[250:251], off
	global_load_dwordx4 v[156:159], v[250:251], off offset:256
	s_add_i32 s8, s8, 2
	s_cmp_lt_u32 s8, 86
	s_waitcnt lgkmcnt(0)
	s_barrier
	s_cbranch_scc1 .Lg16_down_k
	ds_read_b128 v[196:199], v246 offset:0
	ds_read_b128 v[200:203], v246 offset:1024
	ds_read_b128 v[204:207], v246 offset:2048
	ds_read_b128 v[242:245], v246 offset:3072
	s_waitcnt vmcnt(6) lgkmcnt(3)
	v_mfma_f32_16x16x32_bf16 v[112:115], v[128:131], v[196:199], v[112:115]
	v_mfma_f32_16x16x32_bf16 v[120:123], v[132:135], v[196:199], v[120:123]
	v_mfma_f32_16x16x32_bf16 v[48:51], v[136:139], v[196:199], v[48:51]
	v_mfma_f32_16x16x32_bf16 v[56:59], v[140:143], v[196:199], v[56:59]
	ds_read_b128 v[196:199], v246 offset:4096
	s_waitcnt lgkmcnt(3)
	v_mfma_f32_16x16x32_bf16 v[116:119], v[128:131], v[200:203], v[116:119]
	v_mfma_f32_16x16x32_bf16 v[124:127], v[132:135], v[200:203], v[124:127]
	v_mfma_f32_16x16x32_bf16 v[52:55], v[136:139], v[200:203], v[52:55]
	v_mfma_f32_16x16x32_bf16 v[60:63], v[140:143], v[200:203], v[60:63]
	ds_read_b128 v[200:203], v246 offset:5120
	s_waitcnt lgkmcnt(3)
	v_mfma_f32_16x16x32_bf16 v[96:99], v[128:131], v[204:207], v[96:99]
	v_mfma_f32_16x16x32_bf16 v[104:107], v[132:135], v[204:207], v[104:107]
	v_mfma_f32_16x16x32_bf16 v[32:35], v[136:139], v[204:207], v[32:35]
	v_mfma_f32_16x16x32_bf16 v[40:43], v[140:143], v[204:207], v[40:43]
	ds_read_b128 v[204:207], v246 offset:6144
	s_waitcnt lgkmcnt(3)
	v_mfma_f32_16x16x32_bf16 v[100:103], v[128:131], v[242:245], v[100:103]
	v_mfma_f32_16x16x32_bf16 v[108:111], v[132:135], v[242:245], v[108:111]
	v_mfma_f32_16x16x32_bf16 v[36:39], v[136:139], v[242:245], v[36:39]
	v_mfma_f32_16x16x32_bf16 v[44:47], v[140:143], v[242:245], v[44:47]
	ds_read_b128 v[242:245], v246 offset:7168
	s_waitcnt vmcnt(4)
	ds_write_b128 v241, v[168:171] offset:8192
	ds_write_b128 v241, v[172:175] offset:12288
	s_waitcnt lgkmcnt(5)
	v_mfma_f32_16x16x32_bf16 v[80:83], v[128:131], v[196:199], v[80:83]
	v_mfma_f32_16x16x32_bf16 v[88:91], v[132:135], v[196:199], v[88:91]
	v_mfma_f32_16x16x32_bf16 v[16:19], v[136:139], v[196:199], v[16:19]
	v_mfma_f32_16x16x32_bf16 v[24:27], v[140:143], v[196:199], v[24:27]
	s_waitcnt lgkmcnt(4)
	v_mfma_f32_16x16x32_bf16 v[84:87], v[128:131], v[200:203], v[84:87]
	v_mfma_f32_16x16x32_bf16 v[92:95], v[132:135], v[200:203], v[92:95]
	v_mfma_f32_16x16x32_bf16 v[20:23], v[136:139], v[200:203], v[20:23]
	v_mfma_f32_16x16x32_bf16 v[28:31], v[140:143], v[200:203], v[28:31]
	s_waitcnt lgkmcnt(3)
	v_mfma_f32_16x16x32_bf16 v[64:67], v[128:131], v[204:207], v[64:67]
	v_mfma_f32_16x16x32_bf16 v[72:75], v[132:135], v[204:207], v[72:75]
	v_mfma_f32_16x16x32_bf16 v[0:3], v[136:139], v[204:207], v[0:3]
	v_mfma_f32_16x16x32_bf16 v[8:11], v[140:143], v[204:207], v[8:11]
	s_waitcnt lgkmcnt(2)
	v_mfma_f32_16x16x32_bf16 v[68:71], v[128:131], v[242:245], v[68:71]
	v_mfma_f32_16x16x32_bf16 v[76:79], v[132:135], v[242:245], v[76:79]
	v_mfma_f32_16x16x32_bf16 v[4:7], v[136:139], v[242:245], v[4:7]
	v_mfma_f32_16x16x32_bf16 v[12:15], v[140:143], v[242:245], v[12:15]
	s_waitcnt lgkmcnt(0)
	s_barrier
	ds_read_b128 v[196:199], v246 offset:8192
	ds_read_b128 v[200:203], v246 offset:9216
	ds_read_b128 v[204:207], v246 offset:10240
	ds_read_b128 v[242:245], v246 offset:11264
	s_waitcnt vmcnt(0) lgkmcnt(3)
	v_mfma_f32_16x16x32_bf16 v[112:115], v[144:147], v[196:199], v[112:115]
	v_mfma_f32_16x16x32_bf16 v[120:123], v[148:151], v[196:199], v[120:123]
	v_mfma_f32_16x16x32_bf16 v[48:51], v[152:155], v[196:199], v[48:51]
	v_mfma_f32_16x16x32_bf16 v[56:59], v[156:159], v[196:199], v[56:59]
	ds_read_b128 v[196:199], v246 offset:12288
	s_waitcnt lgkmcnt(3)
	v_mfma_f32_16x16x32_bf16 v[116:119], v[144:147], v[200:203], v[116:119]
	v_mfma_f32_16x16x32_bf16 v[124:127], v[148:151], v[200:203], v[124:127]
	v_mfma_f32_16x16x32_bf16 v[52:55], v[152:155], v[200:203], v[52:55]
	v_mfma_f32_16x16x32_bf16 v[60:63], v[156:159], v[200:203], v[60:63]
	ds_read_b128 v[200:203], v246 offset:13312
	s_waitcnt lgkmcnt(3)
	v_mfma_f32_16x16x32_bf16 v[96:99], v[144:147], v[204:207], v[96:99]
	v_mfma_f32_16x16x32_bf16 v[104:107], v[148:151], v[204:207], v[104:107]
	v_mfma_f32_16x16x32_bf16 v[32:35], v[152:155], v[204:207], v[32:35]
	v_mfma_f32_16x16x32_bf16 v[40:43], v[156:159], v[204:207], v[40:43]
	ds_read_b128 v[204:207], v246 offset:14336
	s_waitcnt lgkmcnt(3)
	v_mfma_f32_16x16x32_bf16 v[100:103], v[144:147], v[242:245], v[100:103]
	v_mfma_f32_16x16x32_bf16 v[108:111], v[148:151], v[242:245], v[108:111]
	v_mfma_f32_16x16x32_bf16 v[36:39], v[152:155], v[242:245], v[36:39]
	v_mfma_f32_16x16x32_bf16 v[44:47], v[156:159], v[242:245], v[44:47]
	ds_read_b128 v[242:245], v246 offset:15360
	s_waitcnt lgkmcnt(3)
	v_mfma_f32_16x16x32_bf16 v[80:83], v[144:147], v[196:199], v[80:83]
	v_mfma_f32_16x16x32_bf16 v[88:91], v[148:151], v[196:199], v[88:91]
	v_mfma_f32_16x16x32_bf16 v[16:19], v[152:155], v[196:199], v[16:19]
	v_mfma_f32_16x16x32_bf16 v[24:27], v[156:159], v[196:199], v[24:27]
	s_waitcnt lgkmcnt(2)
	v_mfma_f32_16x16x32_bf16 v[84:87], v[144:147], v[200:203], v[84:87]
	v_mfma_f32_16x16x32_bf16 v[92:95], v[148:151], v[200:203], v[92:95]
	v_mfma_f32_16x16x32_bf16 v[20:23], v[152:155], v[200:203], v[20:23]
	v_mfma_f32_16x16x32_bf16 v[28:31], v[156:159], v[200:203], v[28:31]
	s_waitcnt lgkmcnt(1)
	v_mfma_f32_16x16x32_bf16 v[64:67], v[144:147], v[204:207], v[64:67]
	v_mfma_f32_16x16x32_bf16 v[72:75], v[148:151], v[204:207], v[72:75]
	v_mfma_f32_16x16x32_bf16 v[0:3], v[152:155], v[204:207], v[0:3]
	v_mfma_f32_16x16x32_bf16 v[8:11], v[156:159], v[204:207], v[8:11]
	s_waitcnt lgkmcnt(0)
	v_mfma_f32_16x16x32_bf16 v[68:71], v[144:147], v[242:245], v[68:71]
	v_mfma_f32_16x16x32_bf16 v[76:79], v[148:151], v[242:245], v[76:79]
	v_mfma_f32_16x16x32_bf16 v[4:7], v[152:155], v[242:245], v[4:7]
	v_mfma_f32_16x16x32_bf16 v[12:15], v[156:159], v[242:245], v[12:15]
	s_waitcnt lgkmcnt(0)
	s_barrier
	s_nop 7
	v_permlane16_swap_b32_e32 v112, v116
	v_permlane16_swap_b32_e32 v113, v117
	v_permlane16_swap_b32_e32 v114, v118
	v_permlane16_swap_b32_e32 v115, v119
	v_permlane16_swap_b32_e32 v120, v124
	v_permlane16_swap_b32_e32 v121, v125
	v_permlane16_swap_b32_e32 v122, v126
	v_permlane16_swap_b32_e32 v123, v127
	v_permlane16_swap_b32_e32 v96, v100
	v_permlane16_swap_b32_e32 v97, v101
	v_permlane16_swap_b32_e32 v98, v102
	v_permlane16_swap_b32_e32 v99, v103
	v_permlane16_swap_b32_e32 v104, v108
	v_permlane16_swap_b32_e32 v105, v109
	v_permlane16_swap_b32_e32 v106, v110
	v_permlane16_swap_b32_e32 v107, v111
	v_permlane16_swap_b32_e32 v80, v84
	v_permlane16_swap_b32_e32 v81, v85
	v_permlane16_swap_b32_e32 v82, v86
	v_permlane16_swap_b32_e32 v83, v87
	v_permlane16_swap_b32_e32 v88, v92
	v_permlane16_swap_b32_e32 v89, v93
	v_permlane16_swap_b32_e32 v90, v94
	v_permlane16_swap_b32_e32 v91, v95
	v_permlane16_swap_b32_e32 v64, v68
	v_permlane16_swap_b32_e32 v65, v69
	v_permlane16_swap_b32_e32 v66, v70
	v_permlane16_swap_b32_e32 v67, v71
	v_permlane16_swap_b32_e32 v72, v76
	v_permlane16_swap_b32_e32 v73, v77
	v_permlane16_swap_b32_e32 v74, v78
	v_permlane16_swap_b32_e32 v75, v79
	v_permlane16_swap_b32_e32 v48, v52
	v_permlane16_swap_b32_e32 v49, v53
	v_permlane16_swap_b32_e32 v50, v54
	v_permlane16_swap_b32_e32 v51, v55
	v_permlane16_swap_b32_e32 v56, v60
	v_permlane16_swap_b32_e32 v57, v61
	v_permlane16_swap_b32_e32 v58, v62
	v_permlane16_swap_b32_e32 v59, v63
	v_permlane16_swap_b32_e32 v32, v36
	v_permlane16_swap_b32_e32 v33, v37
	v_permlane16_swap_b32_e32 v34, v38
	v_permlane16_swap_b32_e32 v35, v39
	v_permlane16_swap_b32_e32 v40, v44
	v_permlane16_swap_b32_e32 v41, v45
	v_permlane16_swap_b32_e32 v42, v46
	v_permlane16_swap_b32_e32 v43, v47
	v_permlane16_swap_b32_e32 v16, v20
	v_permlane16_swap_b32_e32 v17, v21
	v_permlane16_swap_b32_e32 v18, v22
	v_permlane16_swap_b32_e32 v19, v23
	v_permlane16_swap_b32_e32 v24, v28
	v_permlane16_swap_b32_e32 v25, v29
	v_permlane16_swap_b32_e32 v26, v30
	v_permlane16_swap_b32_e32 v27, v31
	v_permlane16_swap_b32_e32 v0, v4
	v_permlane16_swap_b32_e32 v1, v5
	v_permlane16_swap_b32_e32 v2, v6
	v_permlane16_swap_b32_e32 v3, v7
	v_permlane16_swap_b32_e32 v8, v12
	v_permlane16_swap_b32_e32 v9, v13
	v_permlane16_swap_b32_e32 v10, v14
	v_permlane16_swap_b32_e32 v11, v15
	v_permlane32_swap_b32_e32 v112, v116
	v_permlane32_swap_b32_e32 v113, v117
	v_permlane32_swap_b32_e32 v114, v118
	v_permlane32_swap_b32_e32 v115, v119
	v_permlane32_swap_b32_e32 v120, v124
	v_permlane32_swap_b32_e32 v121, v125
	v_permlane32_swap_b32_e32 v122, v126
	v_permlane32_swap_b32_e32 v123, v127
	v_permlane32_swap_b32_e32 v96, v100
	v_permlane32_swap_b32_e32 v97, v101
	v_permlane32_swap_b32_e32 v98, v102
	v_permlane32_swap_b32_e32 v99, v103
	v_permlane32_swap_b32_e32 v104, v108
	v_permlane32_swap_b32_e32 v105, v109
	v_permlane32_swap_b32_e32 v106, v110
	v_permlane32_swap_b32_e32 v107, v111
	v_permlane32_swap_b32_e32 v80, v84
	v_permlane32_swap_b32_e32 v81, v85
	v_permlane32_swap_b32_e32 v82, v86
	v_permlane32_swap_b32_e32 v83, v87
	v_permlane32_swap_b32_e32 v88, v92
	v_permlane32_swap_b32_e32 v89, v93
	v_permlane32_swap_b32_e32 v90, v94
	v_permlane32_swap_b32_e32 v91, v95
	v_permlane32_swap_b32_e32 v64, v68
	v_permlane32_swap_b32_e32 v65, v69
	v_permlane32_swap_b32_e32 v66, v70
	v_permlane32_swap_b32_e32 v67, v71
	v_permlane32_swap_b32_e32 v72, v76
	v_permlane32_swap_b32_e32 v73, v77
	v_permlane32_swap_b32_e32 v74, v78
	v_permlane32_swap_b32_e32 v75, v79
	v_permlane32_swap_b32_e32 v48, v52
	v_permlane32_swap_b32_e32 v49, v53
	v_permlane32_swap_b32_e32 v50, v54
	v_permlane32_swap_b32_e32 v51, v55
	v_permlane32_swap_b32_e32 v56, v60
	v_permlane32_swap_b32_e32 v57, v61
	v_permlane32_swap_b32_e32 v58, v62
	v_permlane32_swap_b32_e32 v59, v63
	v_permlane32_swap_b32_e32 v32, v36
	v_permlane32_swap_b32_e32 v33, v37
	v_permlane32_swap_b32_e32 v34, v38
	v_permlane32_swap_b32_e32 v35, v39
	v_permlane32_swap_b32_e32 v40, v44
	v_permlane32_swap_b32_e32 v41, v45
	v_permlane32_swap_b32_e32 v42, v46
	v_permlane32_swap_b32_e32 v43, v47
	v_permlane32_swap_b32_e32 v16, v20
	v_permlane32_swap_b32_e32 v17, v21
	v_permlane32_swap_b32_e32 v18, v22
	v_permlane32_swap_b32_e32 v19, v23
	v_permlane32_swap_b32_e32 v24, v28
	v_permlane32_swap_b32_e32 v25, v29
	v_permlane32_swap_b32_e32 v26, v30
	v_permlane32_swap_b32_e32 v27, v31
	v_permlane32_swap_b32_e32 v0, v4
	v_permlane32_swap_b32_e32 v1, v5
	v_permlane32_swap_b32_e32 v2, v6
	v_permlane32_swap_b32_e32 v3, v7
	v_permlane32_swap_b32_e32 v8, v12
	v_permlane32_swap_b32_e32 v9, v13
	v_permlane32_swap_b32_e32 v10, v14
	v_permlane32_swap_b32_e32 v11, v15
	s_waitcnt vmcnt(0)
	s_movk_i32 s8, 0x2400
	s_waitcnt vmcnt(0)
	v_and_b32_e32 v132, 0xffffffc0, v181
	v_mul_lo_u32 v129, v237, s8
	v_lshlrev_b32_e32 v130, 2, v238
	v_lshl_add_u32 v156, s7, 8, v132
	v_mul_u32_u24_e32 v132, 0x110, v183
	v_or_b32_e32 v131, v129, v130
	v_lshlrev_b32_e32 v132, 2, v132
	v_add_u32_e32 v131, v131, v132
	v_add3_u32 v132, v129, v132, v130
	v_readlane_b32 s8, v253, 36
	v_lshlrev_b32_e32 v128, 2, v181
	v_add_u32_e32 v133, 0x800, v131
	v_add_u32_e32 v134, 0x800, v132
	v_lshrrev_b32_e32 v155, 4, v239
	v_readlane_b32 s12, v253, 40
	v_readlane_b32 s13, v253, 41
	v_readlane_b32 s14, v253, 42
	v_readlane_b32 s15, v253, 43
	v_readlane_b32 s16, v253, 44
	v_readlane_b32 s17, v253, 45
	v_readlane_b32 s18, v253, 46
	v_readlane_b32 s19, v253, 47
	v_and_b32_e32 v128, 60, v128
	ds_write2_b32 v131, v112, v113 offset1:68
	ds_write2_b32 v132, v96, v97 offset0:32 offset1:100
	ds_write2_b32 v131, v114, v115 offset0:136 offset1:204
	ds_write2_b32 v132, v98, v99 offset0:168 offset1:236
	ds_write2_b32 v133, v116, v117 offset0:32 offset1:100
	ds_write2_b32 v134, v100, v101 offset0:64 offset1:132
	ds_write2_b32 v133, v118, v119 offset0:168 offset1:236
	v_or_b32_e32 v100, v156, v155
	v_readlane_b32 s20, v253, 48
	v_readlane_b32 s21, v253, 49
	v_readlane_b32 s22, v253, 50
	v_readlane_b32 s23, v253, 51
	s_mov_b64 s[12:13], s[16:17]
	v_lshl_or_b32 v144, v128, 2, v129
	v_lshl_or_b32 v128, s6, 7, v128
	s_movk_i32 s6, 0x110
	v_cmp_gt_i32_e32 vcc, s39, v100
	v_add_u32_e32 v96, 0xffff8000, v100
	v_ashrrev_i32_e32 v97, 31, v100
	s_mov_b64 s[14:15], s[18:19]
	v_mad_u32_u24 v130, v155, s6, v144
	v_cndmask_b32_e32 v97, 0, v97, vcc
	v_cndmask_b32_e32 v96, v96, v100, vcc
	v_mov_b32_e32 v144, s63
	v_mov_b32_e32 v145, s15
	v_mov_b32_e32 v146, s62
	v_mov_b32_e32 v147, s14
	v_min_i32_e32 v100, 0x8000, v100
	v_add_u32_e32 v135, 0xa00, v132
	v_add_u32_e32 v136, 0x1000, v131
	v_add_u32_e32 v137, 0x1000, v132
	v_add_u32_e32 v138, 0x1200, v131
	v_add_u32_e32 v139, 0x1200, v132
	v_add_u32_e32 v140, 0x1800, v131
	v_add_u32_e32 v141, 0x1800, v132
	v_add_u32_e32 v142, 0x1a00, v131
	v_add_u32_e32 v143, 0x1c00, v132
	v_ashrrev_i32_e32 v129, 31, v128
	v_cndmask_b32_e32 v99, v144, v145, vcc
	v_cndmask_b32_e32 v98, v146, v147, vcc
	v_lshlrev_b64 v[96:97], 12, v[96:97]
	v_ashrrev_i32_e32 v100, 12, v100
	ds_write2_b32 v135, v102, v103 offset0:72 offset1:140
	ds_write2_b32 v136, v120, v121 offset0:64 offset1:132
	ds_write2_b32 v137, v104, v105 offset0:96 offset1:164
	ds_write2_b32 v138, v122, v123 offset0:72 offset1:140
	ds_write2_b32 v139, v106, v107 offset0:104 offset1:172
	ds_write2_b32 v140, v124, v125 offset0:96 offset1:164
	ds_write2_b32 v141, v108, v109 offset0:128 offset1:196
	ds_write2_b32 v142, v126, v127 offset0:104 offset1:172
	ds_write2_b32 v143, v110, v111 offset0:8 offset1:76
	v_lshl_add_u64 v[98:99], v[98:99], 0, v[96:97]
	v_lshlrev_b64 v[96:97], 2, v[128:129]
	v_mul_hi_i32_i24_e32 v101, 0x6000, v100
	v_mul_i32_i24_e32 v100, 0x6000, v100
	s_waitcnt lgkmcnt(0)
	v_lshl_add_u64 v[98:99], v[98:99], 0, v[96:97]
	v_lshl_add_u64 v[100:101], s[0:1], 0, v[100:101]
	v_lshl_add_u64 v[100:101], v[100:101], 0, v[96:97]
	ds_read_b128 v[102:105], v130
	global_load_dwordx4 v[106:109], v[98:99], off
	global_load_dwordx4 v[110:113], v[100:101], off
	v_or_b32_e32 v148, 4, v155
	v_or_b32_e32 v149, 8, v155
	v_or_b32_e32 v150, 12, v155
	v_or_b32_e32 v151, 16, v155
	v_or_b32_e32 v152, 20, v155
	v_or_b32_e32 v153, 24, v155
	v_or_b32_e32 v154, 28, v155
	v_or_b32_e32 v157, v156, v154
	v_readlane_b32 s6, v254, 11
	s_add_i32 s2, s2, s6
	s_cmp_lt_i32 s2, s26
	v_readlane_b32 s9, v253, 37
	v_readlane_b32 s10, v253, 38
	v_readlane_b32 s11, v253, 39
	s_mov_b64 s[16:17], s[20:21]
	s_mov_b64 s[18:19], s[22:23]
	s_waitcnt vmcnt(0) lgkmcnt(0)
	v_pk_fma_f32 v[102:103], v[102:103], v[110:111], v[106:107]
	v_pk_fma_f32 v[104:105], v[104:105], v[112:113], v[108:109]
	v_or_b32_e32 v106, v156, v148
	global_store_dwordx4 v[98:99], v[102:105], off
	v_cmp_gt_i32_e32 vcc, s39, v106
	s_nop 0
	v_ashrrev_i32_e32 v102, 31, v106
	v_add_u32_e32 v104, 0xffff8000, v106
	v_cndmask_b32_e32 v103, 0, v102, vcc
	v_cndmask_b32_e32 v102, v104, v106, vcc
	v_cndmask_b32_e32 v105, v144, v145, vcc
	v_cndmask_b32_e32 v104, v146, v147, vcc
	v_lshlrev_b64 v[102:103], 12, v[102:103]
	v_lshl_add_u64 v[102:103], v[104:105], 0, v[102:103]
	v_min_i32_e32 v104, 0x8000, v106
	v_ashrrev_i32_e32 v104, 12, v104
	v_mul_hi_i32_i24_e32 v105, 0x6000, v104
	v_mul_i32_i24_e32 v104, 0x6000, v104
	v_lshl_add_u64 v[102:103], v[102:103], 0, v[96:97]
	v_lshl_add_u64 v[104:105], s[0:1], 0, v[104:105]
	v_lshl_add_u64 v[104:105], v[104:105], 0, v[96:97]
	ds_read_b128 v[106:109], v130 offset:1088
	global_load_dwordx4 v[110:113], v[102:103], off
	global_load_dwordx4 v[114:117], v[104:105], off
	s_waitcnt vmcnt(0) lgkmcnt(0)
	v_pk_fma_f32 v[106:107], v[106:107], v[114:115], v[110:111]
	v_pk_fma_f32 v[108:109], v[108:109], v[116:117], v[112:113]
	v_or_b32_e32 v110, v156, v149
	global_store_dwordx4 v[102:103], v[106:109], off
	v_cmp_gt_i32_e32 vcc, s39, v110
	s_nop 0
	v_ashrrev_i32_e32 v106, 31, v110
	v_add_u32_e32 v108, 0xffff8000, v110
	v_cndmask_b32_e32 v107, 0, v106, vcc
	v_cndmask_b32_e32 v106, v108, v110, vcc
	v_cndmask_b32_e32 v109, v144, v145, vcc
	v_cndmask_b32_e32 v108, v146, v147, vcc
	v_lshlrev_b64 v[106:107], 12, v[106:107]
	v_lshl_add_u64 v[106:107], v[108:109], 0, v[106:107]
	v_min_i32_e32 v108, 0x8000, v110
	v_ashrrev_i32_e32 v108, 12, v108
	v_mul_hi_i32_i24_e32 v109, 0x6000, v108
	v_mul_i32_i24_e32 v108, 0x6000, v108
	v_lshl_add_u64 v[106:107], v[106:107], 0, v[96:97]
	v_lshl_add_u64 v[108:109], s[0:1], 0, v[108:109]
	v_lshl_add_u64 v[108:109], v[108:109], 0, v[96:97]
	ds_read_b128 v[110:113], v130 offset:2176
	global_load_dwordx4 v[114:117], v[106:107], off
	global_load_dwordx4 v[118:121], v[108:109], off
	s_waitcnt vmcnt(0) lgkmcnt(0)
	v_pk_fma_f32 v[110:111], v[110:111], v[118:119], v[114:115]
	v_pk_fma_f32 v[112:113], v[112:113], v[120:121], v[116:117]
	v_or_b32_e32 v114, v156, v150
	global_store_dwordx4 v[106:107], v[110:113], off
	v_cmp_gt_i32_e32 vcc, s39, v114
	s_nop 0
	v_ashrrev_i32_e32 v110, 31, v114
	v_add_u32_e32 v112, 0xffff8000, v114
	v_cndmask_b32_e32 v111, 0, v110, vcc
	v_cndmask_b32_e32 v110, v112, v114, vcc
	v_cndmask_b32_e32 v113, v144, v145, vcc
	v_cndmask_b32_e32 v112, v146, v147, vcc
	v_lshlrev_b64 v[110:111], 12, v[110:111]
	v_lshl_add_u64 v[110:111], v[112:113], 0, v[110:111]
	v_min_i32_e32 v112, 0x8000, v114
	v_ashrrev_i32_e32 v112, 12, v112
	v_mul_hi_i32_i24_e32 v113, 0x6000, v112
	v_mul_i32_i24_e32 v112, 0x6000, v112
	v_lshl_add_u64 v[110:111], v[110:111], 0, v[96:97]
	v_lshl_add_u64 v[112:113], s[0:1], 0, v[112:113]
	v_lshl_add_u64 v[112:113], v[112:113], 0, v[96:97]
	ds_read_b128 v[114:117], v130 offset:3264
	global_load_dwordx4 v[118:121], v[110:111], off
	global_load_dwordx4 v[122:125], v[112:113], off
	s_waitcnt vmcnt(0) lgkmcnt(0)
	v_pk_fma_f32 v[114:115], v[114:115], v[122:123], v[118:119]
	v_pk_fma_f32 v[116:117], v[116:117], v[124:125], v[120:121]
	v_or_b32_e32 v118, v156, v151
	global_store_dwordx4 v[110:111], v[114:117], off
	v_cmp_gt_i32_e32 vcc, s39, v118
	s_nop 0
	v_ashrrev_i32_e32 v114, 31, v118
	v_add_u32_e32 v116, 0xffff8000, v118
	v_cndmask_b32_e32 v115, 0, v114, vcc
	v_cndmask_b32_e32 v114, v116, v118, vcc
	v_cndmask_b32_e32 v117, v144, v145, vcc
	v_cndmask_b32_e32 v116, v146, v147, vcc
	v_lshlrev_b64 v[114:115], 12, v[114:115]
	v_lshl_add_u64 v[114:115], v[116:117], 0, v[114:115]
	v_min_i32_e32 v116, 0x8000, v118
	v_ashrrev_i32_e32 v116, 12, v116
	v_mul_hi_i32_i24_e32 v117, 0x6000, v116
	v_mul_i32_i24_e32 v116, 0x6000, v116
	v_lshl_add_u64 v[114:115], v[114:115], 0, v[96:97]
	v_lshl_add_u64 v[116:117], s[0:1], 0, v[116:117]
	v_lshl_add_u64 v[116:117], v[116:117], 0, v[96:97]
	ds_read_b128 v[118:121], v130 offset:4352
	global_load_dwordx4 v[122:125], v[114:115], off
	global_load_dwordx4 v[126:129], v[116:117], off
	s_waitcnt vmcnt(0) lgkmcnt(0)
	v_pk_fma_f32 v[118:119], v[118:119], v[126:127], v[122:123]
	v_pk_fma_f32 v[120:121], v[120:121], v[128:129], v[124:125]
	v_or_b32_e32 v122, v156, v152
	global_store_dwordx4 v[114:115], v[118:121], off
	v_cmp_gt_i32_e32 vcc, s39, v122
	s_nop 0
	v_ashrrev_i32_e32 v118, 31, v122
	v_add_u32_e32 v120, 0xffff8000, v122
	v_cndmask_b32_e32 v119, 0, v118, vcc
	v_cndmask_b32_e32 v118, v120, v122, vcc
	v_cndmask_b32_e32 v121, v144, v145, vcc
	v_cndmask_b32_e32 v120, v146, v147, vcc
	v_lshlrev_b64 v[118:119], 12, v[118:119]
	v_lshl_add_u64 v[118:119], v[120:121], 0, v[118:119]
	v_min_i32_e32 v120, 0x8000, v122
	v_ashrrev_i32_e32 v120, 12, v120
	v_mul_hi_i32_i24_e32 v121, 0x6000, v120
	v_mul_i32_i24_e32 v120, 0x6000, v120
	v_lshl_add_u64 v[118:119], v[118:119], 0, v[96:97]
	v_lshl_add_u64 v[120:121], s[0:1], 0, v[120:121]
	v_lshl_add_u64 v[120:121], v[120:121], 0, v[96:97]
	ds_read_b128 v[122:125], v130 offset:5440
	global_load_dwordx4 v[126:129], v[118:119], off
	global_load_dwordx4 v[158:161], v[120:121], off
	s_waitcnt vmcnt(0) lgkmcnt(0)
	v_pk_fma_f32 v[122:123], v[122:123], v[158:159], v[126:127]
	v_pk_fma_f32 v[124:125], v[124:125], v[160:161], v[128:129]
	v_or_b32_e32 v126, v156, v153
	global_store_dwordx4 v[118:119], v[122:125], off
	v_cmp_gt_i32_e32 vcc, s39, v126
	s_nop 0
	v_ashrrev_i32_e32 v122, 31, v126
	v_add_u32_e32 v124, 0xffff8000, v126
	v_cndmask_b32_e32 v123, 0, v122, vcc
	v_cndmask_b32_e32 v122, v124, v126, vcc
	v_cndmask_b32_e32 v125, v144, v145, vcc
	v_cndmask_b32_e32 v124, v146, v147, vcc
	v_lshlrev_b64 v[122:123], 12, v[122:123]
	v_lshl_add_u64 v[122:123], v[124:125], 0, v[122:123]
	v_min_i32_e32 v124, 0x8000, v126
	v_ashrrev_i32_e32 v124, 12, v124
	v_mul_hi_i32_i24_e32 v125, 0x6000, v124
	v_mul_i32_i24_e32 v124, 0x6000, v124
	v_lshl_add_u64 v[122:123], v[122:123], 0, v[96:97]
	v_lshl_add_u64 v[124:125], s[0:1], 0, v[124:125]
	v_lshl_add_u64 v[124:125], v[124:125], 0, v[96:97]
	ds_read_b128 v[126:129], v130 offset:6528
	global_load_dwordx4 v[158:161], v[122:123], off
	global_load_dwordx4 v[162:165], v[124:125], off
	v_cmp_gt_i32_e32 vcc, s39, v157
	s_waitcnt vmcnt(0) lgkmcnt(0)
	v_pk_fma_f32 v[126:127], v[126:127], v[162:163], v[158:159]
	v_pk_fma_f32 v[128:129], v[128:129], v[164:165], v[160:161]
	global_store_dwordx4 v[122:123], v[126:129], off
	ds_read_b128 v[158:161], v130 offset:7616
	s_nop 0
	v_ashrrev_i32_e32 v126, 31, v157
	v_add_u32_e32 v128, 0xffff8000, v157
	v_cndmask_b32_e32 v127, 0, v126, vcc
	v_cndmask_b32_e32 v126, v128, v157, vcc
	v_cndmask_b32_e32 v129, v144, v145, vcc
	v_cndmask_b32_e32 v128, v146, v147, vcc
	v_lshlrev_b64 v[126:127], 12, v[126:127]
	v_lshl_add_u64 v[126:127], v[128:129], 0, v[126:127]
	v_min_i32_e32 v128, 0x8000, v157
	v_ashrrev_i32_e32 v128, 12, v128
	v_mul_hi_i32_i24_e32 v129, 0x6000, v128
	v_mul_i32_i24_e32 v128, 0x6000, v128
	v_lshl_add_u64 v[126:127], v[126:127], 0, v[96:97]
	v_lshl_add_u64 v[128:129], s[0:1], 0, v[128:129]
	v_lshl_add_u64 v[128:129], v[128:129], 0, v[96:97]
	global_load_dwordx4 v[162:165], v[126:127], off
	global_load_dwordx4 v[166:169], v[128:129], off
	s_waitcnt vmcnt(0) lgkmcnt(0)
	v_pk_fma_f32 v[158:159], v[158:159], v[166:167], v[162:163]
	v_pk_fma_f32 v[160:161], v[160:161], v[168:169], v[164:165]
	global_store_dwordx4 v[126:127], v[158:161], off
	s_waitcnt lgkmcnt(0)
	ds_write2_b32 v131, v80, v81 offset1:68
	ds_write2_b32 v132, v64, v65 offset0:32 offset1:100
	ds_write2_b32 v131, v82, v83 offset0:136 offset1:204
	ds_write2_b32 v132, v66, v67 offset0:168 offset1:236
	ds_write2_b32 v133, v84, v85 offset0:32 offset1:100
	ds_write2_b32 v134, v68, v69 offset0:64 offset1:132
	ds_write2_b32 v133, v86, v87 offset0:168 offset1:236
	ds_write2_b32 v135, v70, v71 offset0:72 offset1:140
	ds_write2_b32 v136, v88, v89 offset0:64 offset1:132
	ds_write2_b32 v137, v72, v73 offset0:96 offset1:164
	ds_write2_b32 v138, v90, v91 offset0:72 offset1:140
	ds_write2_b32 v139, v74, v75 offset0:104 offset1:172
	ds_write2_b32 v140, v92, v93 offset0:96 offset1:164
	ds_write2_b32 v141, v76, v77 offset0:128 offset1:196
	ds_write2_b32 v142, v94, v95 offset0:104 offset1:172
	ds_write2_b32 v143, v78, v79 offset0:8 offset1:76
	s_waitcnt lgkmcnt(0)
	ds_read_b128 v[64:67], v130
	global_load_dwordx4 v[68:71], v[98:99], off offset:256
	global_load_dwordx4 v[72:75], v[100:101], off offset:256
	s_waitcnt vmcnt(0) lgkmcnt(0)
	v_pk_fma_f32 v[64:65], v[64:65], v[72:73], v[68:69]
	v_pk_fma_f32 v[66:67], v[66:67], v[74:75], v[70:71]
	global_store_dwordx4 v[98:99], v[64:67], off offset:256
	ds_read_b128 v[64:67], v130 offset:1088
	global_load_dwordx4 v[68:71], v[102:103], off offset:256
	global_load_dwordx4 v[72:75], v[104:105], off offset:256
	s_waitcnt vmcnt(0) lgkmcnt(0)
	v_pk_fma_f32 v[64:65], v[64:65], v[72:73], v[68:69]
	v_pk_fma_f32 v[66:67], v[66:67], v[74:75], v[70:71]
	global_store_dwordx4 v[102:103], v[64:67], off offset:256
	ds_read_b128 v[64:67], v130 offset:2176
	global_load_dwordx4 v[68:71], v[106:107], off offset:256
	global_load_dwordx4 v[72:75], v[108:109], off offset:256
	s_waitcnt vmcnt(0) lgkmcnt(0)
	v_pk_fma_f32 v[64:65], v[64:65], v[72:73], v[68:69]
	v_pk_fma_f32 v[66:67], v[66:67], v[74:75], v[70:71]
	global_store_dwordx4 v[106:107], v[64:67], off offset:256
	ds_read_b128 v[64:67], v130 offset:3264
	global_load_dwordx4 v[68:71], v[110:111], off offset:256
	global_load_dwordx4 v[72:75], v[112:113], off offset:256
	s_waitcnt vmcnt(0) lgkmcnt(0)
	v_pk_fma_f32 v[64:65], v[64:65], v[72:73], v[68:69]
	v_pk_fma_f32 v[66:67], v[66:67], v[74:75], v[70:71]
	global_store_dwordx4 v[110:111], v[64:67], off offset:256
	ds_read_b128 v[64:67], v130 offset:4352
	global_load_dwordx4 v[68:71], v[114:115], off offset:256
	global_load_dwordx4 v[72:75], v[116:117], off offset:256
	s_waitcnt vmcnt(0) lgkmcnt(0)
	v_pk_fma_f32 v[64:65], v[64:65], v[72:73], v[68:69]
	v_pk_fma_f32 v[66:67], v[66:67], v[74:75], v[70:71]
	global_store_dwordx4 v[114:115], v[64:67], off offset:256
	ds_read_b128 v[64:67], v130 offset:5440
	global_load_dwordx4 v[68:71], v[118:119], off offset:256
	global_load_dwordx4 v[72:75], v[120:121], off offset:256
	s_waitcnt vmcnt(0) lgkmcnt(0)
	v_pk_fma_f32 v[64:65], v[64:65], v[72:73], v[68:69]
	v_pk_fma_f32 v[66:67], v[66:67], v[74:75], v[70:71]
	global_store_dwordx4 v[118:119], v[64:67], off offset:256
	ds_read_b128 v[64:67], v130 offset:6528
	global_load_dwordx4 v[68:71], v[122:123], off offset:256
	global_load_dwordx4 v[72:75], v[124:125], off offset:256
	s_waitcnt vmcnt(0) lgkmcnt(0)
	v_pk_fma_f32 v[64:65], v[64:65], v[72:73], v[68:69]
	v_pk_fma_f32 v[66:67], v[66:67], v[74:75], v[70:71]
	global_store_dwordx4 v[122:123], v[64:67], off offset:256
	ds_read_b128 v[64:67], v130 offset:7616
	global_load_dwordx4 v[68:71], v[126:127], off offset:256
	global_load_dwordx4 v[72:75], v[128:129], off offset:256
	s_waitcnt vmcnt(0) lgkmcnt(0)
	v_pk_fma_f32 v[64:65], v[64:65], v[72:73], v[68:69]
	v_pk_fma_f32 v[66:67], v[66:67], v[74:75], v[70:71]
	global_store_dwordx4 v[126:127], v[64:67], off offset:256
	s_waitcnt lgkmcnt(0)
	ds_write2_b32 v131, v48, v49 offset1:68
	ds_write2_b32 v132, v32, v33 offset0:32 offset1:100
	ds_write2_b32 v131, v50, v51 offset0:136 offset1:204
	ds_write2_b32 v132, v34, v35 offset0:168 offset1:236
	ds_write2_b32 v133, v52, v53 offset0:32 offset1:100
	ds_write2_b32 v134, v36, v37 offset0:64 offset1:132
	ds_write2_b32 v133, v54, v55 offset0:168 offset1:236
	ds_write2_b32 v135, v38, v39 offset0:72 offset1:140
	ds_write2_b32 v136, v56, v57 offset0:64 offset1:132
	ds_write2_b32 v137, v40, v41 offset0:96 offset1:164
	ds_write2_b32 v138, v58, v59 offset0:72 offset1:140
	ds_write2_b32 v139, v42, v43 offset0:104 offset1:172
	ds_write2_b32 v140, v60, v61 offset0:96 offset1:164
	ds_write2_b32 v141, v44, v45 offset0:128 offset1:196
	ds_write2_b32 v142, v62, v63 offset0:104 offset1:172
	ds_write2_b32 v143, v46, v47 offset0:8 offset1:76
	v_or_b32_e32 v64, 32, v156
	v_or_b32_e32 v36, v64, v155
	v_cmp_gt_i32_e32 vcc, s39, v36
	v_ashrrev_i32_e32 v32, 31, v36
	v_add_u32_e32 v34, 0xffff8000, v36
	v_cndmask_b32_e32 v33, 0, v32, vcc
	v_cndmask_b32_e32 v32, v34, v36, vcc
	v_cndmask_b32_e32 v35, v144, v145, vcc
	v_cndmask_b32_e32 v34, v146, v147, vcc
	v_lshlrev_b64 v[32:33], 12, v[32:33]
	v_lshl_add_u64 v[32:33], v[34:35], 0, v[32:33]
	v_min_i32_e32 v34, 0x8000, v36
	v_ashrrev_i32_e32 v34, 12, v34
	v_mul_hi_i32_i24_e32 v35, 0x6000, v34
	v_mul_i32_i24_e32 v34, 0x6000, v34
	s_waitcnt lgkmcnt(0)
	v_lshl_add_u64 v[32:33], v[32:33], 0, v[96:97]
	v_lshl_add_u64 v[34:35], s[0:1], 0, v[34:35]
	v_lshl_add_u64 v[34:35], v[34:35], 0, v[96:97]
	ds_read_b128 v[36:39], v130
	global_load_dwordx4 v[40:43], v[32:33], off
	global_load_dwordx4 v[44:47], v[34:35], off
	s_waitcnt vmcnt(0) lgkmcnt(0)
	v_pk_fma_f32 v[36:37], v[36:37], v[44:45], v[40:41]
	v_pk_fma_f32 v[38:39], v[38:39], v[46:47], v[42:43]
	v_or_b32_e32 v40, v64, v148
	global_store_dwordx4 v[32:33], v[36:39], off
	v_cmp_gt_i32_e32 vcc, s39, v40
	s_nop 0
	v_ashrrev_i32_e32 v36, 31, v40
	v_add_u32_e32 v38, 0xffff8000, v40
	v_cndmask_b32_e32 v37, 0, v36, vcc
	v_cndmask_b32_e32 v36, v38, v40, vcc
	v_cndmask_b32_e32 v39, v144, v145, vcc
	v_cndmask_b32_e32 v38, v146, v147, vcc
	v_lshlrev_b64 v[36:37], 12, v[36:37]
	v_lshl_add_u64 v[36:37], v[38:39], 0, v[36:37]
	v_min_i32_e32 v38, 0x8000, v40
	v_ashrrev_i32_e32 v38, 12, v38
	v_mul_hi_i32_i24_e32 v39, 0x6000, v38
	v_mul_i32_i24_e32 v38, 0x6000, v38
	v_lshl_add_u64 v[36:37], v[36:37], 0, v[96:97]
	v_lshl_add_u64 v[38:39], s[0:1], 0, v[38:39]
	v_lshl_add_u64 v[38:39], v[38:39], 0, v[96:97]
	ds_read_b128 v[40:43], v130 offset:1088
	global_load_dwordx4 v[44:47], v[36:37], off
	global_load_dwordx4 v[48:51], v[38:39], off
	s_waitcnt vmcnt(0) lgkmcnt(0)
	v_pk_fma_f32 v[40:41], v[40:41], v[48:49], v[44:45]
	v_pk_fma_f32 v[42:43], v[42:43], v[50:51], v[46:47]
	v_or_b32_e32 v44, v64, v149
	global_store_dwordx4 v[36:37], v[40:43], off
	v_cmp_gt_i32_e32 vcc, s39, v44
	s_nop 0
	v_ashrrev_i32_e32 v40, 31, v44
	v_add_u32_e32 v42, 0xffff8000, v44
	v_cndmask_b32_e32 v41, 0, v40, vcc
	v_cndmask_b32_e32 v40, v42, v44, vcc
	v_cndmask_b32_e32 v43, v144, v145, vcc
	v_cndmask_b32_e32 v42, v146, v147, vcc
	v_lshlrev_b64 v[40:41], 12, v[40:41]
	v_lshl_add_u64 v[40:41], v[42:43], 0, v[40:41]
	v_min_i32_e32 v42, 0x8000, v44
	v_ashrrev_i32_e32 v42, 12, v42
	v_mul_hi_i32_i24_e32 v43, 0x6000, v42
	v_mul_i32_i24_e32 v42, 0x6000, v42
	v_lshl_add_u64 v[40:41], v[40:41], 0, v[96:97]
	v_lshl_add_u64 v[42:43], s[0:1], 0, v[42:43]
	v_lshl_add_u64 v[42:43], v[42:43], 0, v[96:97]
	ds_read_b128 v[44:47], v130 offset:2176
	global_load_dwordx4 v[48:51], v[40:41], off
	global_load_dwordx4 v[52:55], v[42:43], off
	s_waitcnt vmcnt(0) lgkmcnt(0)
	v_pk_fma_f32 v[44:45], v[44:45], v[52:53], v[48:49]
	v_pk_fma_f32 v[46:47], v[46:47], v[54:55], v[50:51]
	v_or_b32_e32 v48, v64, v150
	global_store_dwordx4 v[40:41], v[44:47], off
	v_cmp_gt_i32_e32 vcc, s39, v48
	s_nop 0
	v_ashrrev_i32_e32 v44, 31, v48
	v_add_u32_e32 v46, 0xffff8000, v48
	v_cndmask_b32_e32 v45, 0, v44, vcc
	v_cndmask_b32_e32 v44, v46, v48, vcc
	v_cndmask_b32_e32 v47, v144, v145, vcc
	v_cndmask_b32_e32 v46, v146, v147, vcc
	v_lshlrev_b64 v[44:45], 12, v[44:45]
	v_lshl_add_u64 v[44:45], v[46:47], 0, v[44:45]
	v_min_i32_e32 v46, 0x8000, v48
	v_ashrrev_i32_e32 v46, 12, v46
	v_mul_hi_i32_i24_e32 v47, 0x6000, v46
	v_mul_i32_i24_e32 v46, 0x6000, v46
	v_lshl_add_u64 v[44:45], v[44:45], 0, v[96:97]
	v_lshl_add_u64 v[46:47], s[0:1], 0, v[46:47]
	v_lshl_add_u64 v[46:47], v[46:47], 0, v[96:97]
	ds_read_b128 v[48:51], v130 offset:3264
	global_load_dwordx4 v[52:55], v[44:45], off
	global_load_dwordx4 v[56:59], v[46:47], off
	s_waitcnt vmcnt(0) lgkmcnt(0)
	v_pk_fma_f32 v[48:49], v[48:49], v[56:57], v[52:53]
	v_pk_fma_f32 v[50:51], v[50:51], v[58:59], v[54:55]
	v_or_b32_e32 v52, v64, v151
	global_store_dwordx4 v[44:45], v[48:51], off
	v_cmp_gt_i32_e32 vcc, s39, v52
	s_nop 0
	v_ashrrev_i32_e32 v48, 31, v52
	v_add_u32_e32 v50, 0xffff8000, v52
	v_cndmask_b32_e32 v49, 0, v48, vcc
	v_cndmask_b32_e32 v48, v50, v52, vcc
	v_cndmask_b32_e32 v51, v144, v145, vcc
	v_cndmask_b32_e32 v50, v146, v147, vcc
	v_lshlrev_b64 v[48:49], 12, v[48:49]
	v_lshl_add_u64 v[48:49], v[50:51], 0, v[48:49]
	v_min_i32_e32 v50, 0x8000, v52
	v_ashrrev_i32_e32 v50, 12, v50
	v_mul_hi_i32_i24_e32 v51, 0x6000, v50
	v_mul_i32_i24_e32 v50, 0x6000, v50
	v_lshl_add_u64 v[48:49], v[48:49], 0, v[96:97]
	v_lshl_add_u64 v[50:51], s[0:1], 0, v[50:51]
	v_lshl_add_u64 v[50:51], v[50:51], 0, v[96:97]
	ds_read_b128 v[52:55], v130 offset:4352
	global_load_dwordx4 v[56:59], v[48:49], off
	global_load_dwordx4 v[60:63], v[50:51], off
	s_waitcnt vmcnt(0) lgkmcnt(0)
	v_pk_fma_f32 v[52:53], v[52:53], v[60:61], v[56:57]
	v_pk_fma_f32 v[54:55], v[54:55], v[62:63], v[58:59]
	v_or_b32_e32 v56, v64, v152
	global_store_dwordx4 v[48:49], v[52:55], off
	v_cmp_gt_i32_e32 vcc, s39, v56
	s_nop 0
	v_ashrrev_i32_e32 v52, 31, v56
	v_add_u32_e32 v54, 0xffff8000, v56
	v_cndmask_b32_e32 v53, 0, v52, vcc
	v_cndmask_b32_e32 v52, v54, v56, vcc
	v_cndmask_b32_e32 v55, v144, v145, vcc
	v_cndmask_b32_e32 v54, v146, v147, vcc
	v_lshlrev_b64 v[52:53], 12, v[52:53]
	v_lshl_add_u64 v[52:53], v[54:55], 0, v[52:53]
	v_min_i32_e32 v54, 0x8000, v56
	v_ashrrev_i32_e32 v54, 12, v54
	v_mul_hi_i32_i24_e32 v55, 0x6000, v54
	v_mul_i32_i24_e32 v54, 0x6000, v54
	v_lshl_add_u64 v[52:53], v[52:53], 0, v[96:97]
	v_lshl_add_u64 v[54:55], s[0:1], 0, v[54:55]
	v_lshl_add_u64 v[54:55], v[54:55], 0, v[96:97]
	ds_read_b128 v[56:59], v130 offset:5440
	global_load_dwordx4 v[60:63], v[52:53], off
	global_load_dwordx4 v[66:69], v[54:55], off
	s_waitcnt vmcnt(0) lgkmcnt(0)
	v_pk_fma_f32 v[56:57], v[56:57], v[66:67], v[60:61]
	v_pk_fma_f32 v[58:59], v[58:59], v[68:69], v[62:63]
	v_or_b32_e32 v60, v64, v153
	global_store_dwordx4 v[52:53], v[56:59], off
	v_cmp_gt_i32_e32 vcc, s39, v60
	v_or_b32_e32 v64, v64, v154
	v_ashrrev_i32_e32 v56, 31, v60
	v_add_u32_e32 v58, 0xffff8000, v60
	v_cndmask_b32_e32 v57, 0, v56, vcc
	v_cndmask_b32_e32 v56, v58, v60, vcc
	v_cndmask_b32_e32 v59, v144, v145, vcc
	v_cndmask_b32_e32 v58, v146, v147, vcc
	v_lshlrev_b64 v[56:57], 12, v[56:57]
	v_lshl_add_u64 v[56:57], v[58:59], 0, v[56:57]
	v_min_i32_e32 v58, 0x8000, v60
	v_ashrrev_i32_e32 v58, 12, v58
	v_mul_hi_i32_i24_e32 v59, 0x6000, v58
	v_mul_i32_i24_e32 v58, 0x6000, v58
	v_lshl_add_u64 v[56:57], v[56:57], 0, v[96:97]
	v_lshl_add_u64 v[58:59], s[0:1], 0, v[58:59]
	v_lshl_add_u64 v[58:59], v[58:59], 0, v[96:97]
	ds_read_b128 v[60:63], v130 offset:6528
	global_load_dwordx4 v[66:69], v[56:57], off
	global_load_dwordx4 v[70:73], v[58:59], off
	v_cmp_gt_i32_e32 vcc, s39, v64
	s_waitcnt vmcnt(0) lgkmcnt(0)
	v_pk_fma_f32 v[60:61], v[60:61], v[70:71], v[66:67]
	v_pk_fma_f32 v[62:63], v[62:63], v[72:73], v[68:69]
	global_store_dwordx4 v[56:57], v[60:63], off
	s_nop 1
	v_ashrrev_i32_e32 v60, 31, v64
	v_add_u32_e32 v62, 0xffff8000, v64
	v_cndmask_b32_e32 v61, 0, v60, vcc
	v_cndmask_b32_e32 v60, v62, v64, vcc
	v_cndmask_b32_e32 v63, v144, v145, vcc
	v_cndmask_b32_e32 v62, v146, v147, vcc
	v_lshlrev_b64 v[60:61], 12, v[60:61]
	v_lshl_add_u64 v[60:61], v[62:63], 0, v[60:61]
	v_min_i32_e32 v62, 0x8000, v64
	v_ashrrev_i32_e32 v62, 12, v62
	v_mul_hi_i32_i24_e32 v63, 0x6000, v62
	v_mul_i32_i24_e32 v62, 0x6000, v62
	v_lshl_add_u64 v[60:61], v[60:61], 0, v[96:97]
	v_lshl_add_u64 v[62:63], s[0:1], 0, v[62:63]
	v_lshl_add_u64 v[62:63], v[62:63], 0, v[96:97]
	ds_read_b128 v[64:67], v130 offset:7616
	global_load_dwordx4 v[68:71], v[60:61], off
	global_load_dwordx4 v[72:75], v[62:63], off
	s_waitcnt vmcnt(0) lgkmcnt(0)
	v_pk_fma_f32 v[64:65], v[64:65], v[72:73], v[68:69]
	v_pk_fma_f32 v[66:67], v[66:67], v[74:75], v[70:71]
	global_store_dwordx4 v[60:61], v[64:67], off
	s_waitcnt lgkmcnt(0)
	ds_write2_b32 v131, v16, v17 offset1:68
	ds_write2_b32 v132, v0, v1 offset0:32 offset1:100
	ds_write2_b32 v131, v18, v19 offset0:136 offset1:204
	ds_write2_b32 v132, v2, v3 offset0:168 offset1:236
	ds_write2_b32 v133, v20, v21 offset0:32 offset1:100
	ds_write2_b32 v134, v4, v5 offset0:64 offset1:132
	ds_write2_b32 v133, v22, v23 offset0:168 offset1:236
	ds_write2_b32 v135, v6, v7 offset0:72 offset1:140
	ds_write2_b32 v136, v24, v25 offset0:64 offset1:132
	ds_write2_b32 v137, v8, v9 offset0:96 offset1:164
	ds_write2_b32 v138, v26, v27 offset0:72 offset1:140
	ds_write2_b32 v139, v10, v11 offset0:104 offset1:172
	ds_write2_b32 v140, v28, v29 offset0:96 offset1:164
	ds_write2_b32 v141, v12, v13 offset0:128 offset1:196
	ds_write2_b32 v142, v30, v31 offset0:104 offset1:172
	ds_write2_b32 v143, v14, v15 offset0:8 offset1:76
	s_waitcnt lgkmcnt(0)
	ds_read_b128 v[0:3], v130
	global_load_dwordx4 v[4:7], v[32:33], off offset:256
	global_load_dwordx4 v[8:11], v[34:35], off offset:256
	s_waitcnt vmcnt(0) lgkmcnt(0)
	v_pk_fma_f32 v[0:1], v[0:1], v[8:9], v[4:5]
	v_pk_fma_f32 v[2:3], v[2:3], v[10:11], v[6:7]
	global_store_dwordx4 v[32:33], v[0:3], off offset:256
	ds_read_b128 v[0:3], v130 offset:1088
	global_load_dwordx4 v[4:7], v[36:37], off offset:256
	global_load_dwordx4 v[8:11], v[38:39], off offset:256
	s_waitcnt vmcnt(0) lgkmcnt(0)
	v_pk_fma_f32 v[0:1], v[0:1], v[8:9], v[4:5]
	v_pk_fma_f32 v[2:3], v[2:3], v[10:11], v[6:7]
	global_store_dwordx4 v[36:37], v[0:3], off offset:256
	ds_read_b128 v[0:3], v130 offset:2176
	global_load_dwordx4 v[4:7], v[40:41], off offset:256
	global_load_dwordx4 v[8:11], v[42:43], off offset:256
	s_waitcnt vmcnt(0) lgkmcnt(0)
	v_pk_fma_f32 v[0:1], v[0:1], v[8:9], v[4:5]
	v_pk_fma_f32 v[2:3], v[2:3], v[10:11], v[6:7]
	global_store_dwordx4 v[40:41], v[0:3], off offset:256
	ds_read_b128 v[0:3], v130 offset:3264
	global_load_dwordx4 v[4:7], v[44:45], off offset:256
	global_load_dwordx4 v[8:11], v[46:47], off offset:256
	s_waitcnt vmcnt(0) lgkmcnt(0)
	v_pk_fma_f32 v[0:1], v[0:1], v[8:9], v[4:5]
	v_pk_fma_f32 v[2:3], v[2:3], v[10:11], v[6:7]
	global_store_dwordx4 v[44:45], v[0:3], off offset:256
	ds_read_b128 v[0:3], v130 offset:4352
	global_load_dwordx4 v[4:7], v[48:49], off offset:256
	global_load_dwordx4 v[8:11], v[50:51], off offset:256
	s_waitcnt vmcnt(0) lgkmcnt(0)
	v_pk_fma_f32 v[0:1], v[0:1], v[8:9], v[4:5]
	v_pk_fma_f32 v[2:3], v[2:3], v[10:11], v[6:7]
	global_store_dwordx4 v[48:49], v[0:3], off offset:256
	ds_read_b128 v[0:3], v130 offset:5440
	global_load_dwordx4 v[4:7], v[52:53], off offset:256
	global_load_dwordx4 v[8:11], v[54:55], off offset:256
	s_waitcnt vmcnt(0) lgkmcnt(0)
	v_pk_fma_f32 v[0:1], v[0:1], v[8:9], v[4:5]
	v_pk_fma_f32 v[2:3], v[2:3], v[10:11], v[6:7]
	global_store_dwordx4 v[52:53], v[0:3], off offset:256
	ds_read_b128 v[0:3], v130 offset:6528
	global_load_dwordx4 v[4:7], v[56:57], off offset:256
	global_load_dwordx4 v[8:11], v[58:59], off offset:256
	s_waitcnt vmcnt(0) lgkmcnt(0)
	v_pk_fma_f32 v[0:1], v[0:1], v[8:9], v[4:5]
	v_pk_fma_f32 v[2:3], v[2:3], v[10:11], v[6:7]
	global_store_dwordx4 v[56:57], v[0:3], off offset:256
	ds_read_b128 v[0:3], v130 offset:7616
	global_load_dwordx4 v[4:7], v[60:61], off offset:256
	global_load_dwordx4 v[8:11], v[62:63], off offset:256
	s_waitcnt vmcnt(0) lgkmcnt(0)
	v_pk_fma_f32 v[0:1], v[0:1], v[8:9], v[4:5]
	v_pk_fma_f32 v[2:3], v[2:3], v[10:11], v[6:7]
	global_store_dwordx4 v[60:61], v[0:3], off offset:256
	s_waitcnt lgkmcnt(0)
	s_barrier
	s_cbranch_scc1 .LBB0_1086
